# GEMM main loops: the scalar tail after each MFMA block (s_setprio 0, pointer/counter updates) moved behind the following barrier so the partner group's MFMAs start sooner
# speedup vs baseline: 1.0019x; 1.0019x over previous
; #define PG8_STAGE(bufoff, gbase, voff) do { _Pragma("unroll") for (int _i = 0; _i < 2; ++_i) \
;         __builtin_amdgcn_global_load_lds((const unsigned*)((const char*)(gbase) + (voff)[_i]), (LAS unsigned*)(lds + (bufoff) + ldsw + _i * 8192), 16, 0, 0); } while (0)
; #define PG8_LDA(dst, b, h) do { _Pragma("unroll") for (int m = 0; m < 4; ++m) _Pragma("unroll") for (int k = 0; k < 2; ++k) dst[m][k] = *(const LAS bf16x8*)(lds + PG8_SA(b, h) + aoff + m * 2048 + k * 1024); } while (0)
; #define PG8_LDB(dst, b, h) do { _Pragma("unroll") for (int n = 0; n < 2; ++n) _Pragma("unroll") for (int k = 0; k < 2; ++k) dst[n][k] = *(const LAS bf16x8*)(lds + PG8_SB(b, h) + boff + n * 2048 + k * 1024); } while (0)
; #define PG8_MMA(ai, bj, At, Bt) do { __builtin_amdgcn_s_setprio(1); _Pragma("unroll") for (int m = 0; m < 4; ++m) _Pragma("unroll") for (int n = 0; n < 2; ++n) _Pragma("unroll") for (int k = 0; k < 2; ++k) \
;         acc[ai][bj][m][n] = __builtin_amdgcn_mfma_f32_16x16x32_bf16(Bt[n][k], At[m][k], acc[ai][bj][m][n], 0, 0, 0); __builtin_amdgcn_s_setprio(0); } while (0)
; #define PG8_WAIT_V(n) asm volatile("s_waitcnt vmcnt(" #n ")" ::: "memory")
; #define PG8_WAIT_L(n) asm volatile("s_waitcnt lgkmcnt(" #n ")" ::: "memory")
; #define PG8_BAR __builtin_amdgcn_s_barrier()
; #define PG8_SCHED __builtin_amdgcn_sched_barrier(0)
; template <class Epi>
; __device__ __forceinline__ void gemm_phase(LAS unsigned char* lds, const Gemm g, const Epi& E) {
;     ...
;             PG8_LDB(B0, 0, 0); PG8_SCHED; PG8_LDA(At, 0, 0); PG8_STAGE(PG8_SA(1, 1), a1 + hstep, voffA);
;             PG8_WAIT_L(8); PG8_BAR; PG8_WAIT_L(0); PG8_MMA(0, 0, At, B0); PG8_BAR; PG8_SCHED;
;             PG8_LDB(B1, 0, 1); PG8_STAGE(PG8_SB(0, 0), b2, voffB);
;             PG8_BAR; PG8_WAIT_L(0); PG8_MMA(0, 1, At, B1); PG8_BAR;
;             PG8_LDA(At, 0, 1); PG8_STAGE(PG8_SA(0, 0), a2, voffA);
;             PG8_BAR; PG8_WAIT_L(0); PG8_MMA(1, 0, At, B0); PG8_BAR; PG8_SCHED;
;             PG8_STAGE(PG8_SB(0, 1), b2 + hstep, voffB);
;             PG8_WAIT_V(6); PG8_BAR; PG8_MMA(1, 1, At, B1); PG8_BAR;
.LBB0_30:
	s_add_u32 s28, s26, 0xfff80080
	s_addc_u32 s29, s27, -1
	s_add_i32 s34, 0, 0x10000
	v_add_u32_e32 v143, s34, v141
	ds_read_b128 v[144:147], v143
	ds_read_b128 v[148:151], v143 offset:1024
	ds_read_b128 v[152:155], v143 offset:2048
	ds_read_b128 v[156:159], v143 offset:3072
	s_cmp_eq_u32 s89, 28
	s_cselect_b32 s37, s45, s29
	s_cselect_b32 s36, s78, s28
	s_cselect_b32 s29, s43, s83
	s_cselect_b32 s28, s79, s82
	s_add_i32 m0, s39, 0xc000
	ds_read_b128 v[160:163], v142
	ds_read_b128 v[164:167], v142 offset:1024
	ds_read_b128 v[168:171], v142 offset:2048
	ds_read_b128 v[172:175], v142 offset:3072
	ds_read_b128 v[176:179], v142 offset:4096
	ds_read_b128 v[180:183], v142 offset:5120
	ds_read_b128 v[184:187], v142 offset:6144
	ds_read_b128 v[188:191], v142 offset:7168
	global_load_lds_dwordx4 v136, s[26:27]
	s_add_i32 m0, s39, 0xe000
	s_nop 0
	global_load_lds_dwordx4 v138, s[26:27]
	s_waitcnt lgkmcnt(8)
	s_setprio 1
	s_barrier
	s_waitcnt lgkmcnt(0)
	v_mfma_f32_16x16x32_bf16 v[124:127], v[144:147], v[160:163], v[124:127]
	v_mfma_f32_16x16x32_bf16 v[116:119], v[152:155], v[160:163], v[116:119]
	v_mfma_f32_16x16x32_bf16 v[108:111], v[144:147], v[168:171], v[108:111]
	v_mfma_f32_16x16x32_bf16 v[100:103], v[152:155], v[168:171], v[100:103]
	v_mfma_f32_16x16x32_bf16 v[92:95], v[144:147], v[176:179], v[92:95]
	v_mfma_f32_16x16x32_bf16 v[84:87], v[152:155], v[176:179], v[84:87]
	v_mfma_f32_16x16x32_bf16 v[76:79], v[144:147], v[184:187], v[76:79]
	v_mfma_f32_16x16x32_bf16 v[68:71], v[152:155], v[184:187], v[68:71]
	v_mfma_f32_16x16x32_bf16 v[124:127], v[148:151], v[164:167], v[124:127]
	v_mfma_f32_16x16x32_bf16 v[116:119], v[156:159], v[164:167], v[116:119]
	v_mfma_f32_16x16x32_bf16 v[108:111], v[148:151], v[172:175], v[108:111]
	v_mfma_f32_16x16x32_bf16 v[100:103], v[156:159], v[172:175], v[100:103]
	v_mfma_f32_16x16x32_bf16 v[92:95], v[148:151], v[180:183], v[92:95]
	v_mfma_f32_16x16x32_bf16 v[84:87], v[156:159], v[180:183], v[84:87]
	v_mfma_f32_16x16x32_bf16 v[76:79], v[148:151], v[188:191], v[76:79]
	v_mfma_f32_16x16x32_bf16 v[68:71], v[156:159], v[188:191], v[68:71]
	s_barrier
	s_setprio 0
	s_add_i32 s46, 0, 0x14000
	s_add_i32 s34, s34, s31
	v_add_u32_e32 v143, s46, v141
	s_mov_b32 m0, s34
	ds_read_b128 v[192:195], v143
	ds_read_b128 v[196:199], v143 offset:1024
	ds_read_b128 v[200:203], v143 offset:2048
	ds_read_b128 v[204:207], v143 offset:3072
	global_load_lds_dwordx4 v132, s[28:29]
	s_add_i32 m0, s34, 0x2000
	s_nop 0
	global_load_lds_dwordx4 v128, s[28:29]
	s_setprio 1
	s_barrier
	s_waitcnt lgkmcnt(0)
	v_mfma_f32_16x16x32_bf16 v[120:123], v[192:195], v[160:163], v[120:123]
	v_mfma_f32_16x16x32_bf16 v[112:115], v[200:203], v[160:163], v[112:115]
	v_mfma_f32_16x16x32_bf16 v[104:107], v[192:195], v[168:171], v[104:107]
	v_mfma_f32_16x16x32_bf16 v[96:99], v[200:203], v[168:171], v[96:99]
	v_mfma_f32_16x16x32_bf16 v[88:91], v[192:195], v[176:179], v[88:91]
	v_mfma_f32_16x16x32_bf16 v[80:83], v[200:203], v[176:179], v[80:83]
	v_mfma_f32_16x16x32_bf16 v[72:75], v[192:195], v[184:187], v[72:75]
	v_mfma_f32_16x16x32_bf16 v[64:67], v[200:203], v[184:187], v[64:67]
	v_mfma_f32_16x16x32_bf16 v[120:123], v[196:199], v[164:167], v[120:123]
	v_mfma_f32_16x16x32_bf16 v[112:115], v[204:207], v[164:167], v[112:115]
	v_mfma_f32_16x16x32_bf16 v[104:107], v[196:199], v[172:175], v[104:107]
	v_mfma_f32_16x16x32_bf16 v[96:99], v[204:207], v[172:175], v[96:99]
	v_mfma_f32_16x16x32_bf16 v[88:91], v[196:199], v[180:183], v[88:91]
	v_mfma_f32_16x16x32_bf16 v[80:83], v[204:207], v[180:183], v[80:83]
	v_mfma_f32_16x16x32_bf16 v[72:75], v[196:199], v[188:191], v[72:75]
	v_mfma_f32_16x16x32_bf16 v[64:67], v[204:207], v[188:191], v[64:67]
	s_barrier
	s_setprio 0
	s_mov_b32 m0, s39
	ds_read_b128 v[160:163], v142 offset:16384
	ds_read_b128 v[164:167], v142 offset:17408
	ds_read_b128 v[168:171], v142 offset:18432
	ds_read_b128 v[172:175], v142 offset:19456
	ds_read_b128 v[176:179], v142 offset:20480
	ds_read_b128 v[180:183], v142 offset:21504
	ds_read_b128 v[184:187], v142 offset:22528
	ds_read_b128 v[188:191], v142 offset:23552
	global_load_lds_dwordx4 v134, s[36:37]
	s_mov_b32 m0, s68
	s_nop 0
	global_load_lds_dwordx4 v130, s[36:37]
	s_setprio 1
	s_barrier
	s_waitcnt lgkmcnt(0)
	v_mfma_f32_16x16x32_bf16 v[60:63], v[144:147], v[160:163], v[60:63]
	v_mfma_f32_16x16x32_bf16 v[52:55], v[152:155], v[160:163], v[52:55]
	v_mfma_f32_16x16x32_bf16 v[44:47], v[144:147], v[168:171], v[44:47]
	v_mfma_f32_16x16x32_bf16 v[36:39], v[152:155], v[168:171], v[36:39]
	v_mfma_f32_16x16x32_bf16 v[28:31], v[144:147], v[176:179], v[28:31]
	v_mfma_f32_16x16x32_bf16 v[20:23], v[152:155], v[176:179], v[20:23]
	v_mfma_f32_16x16x32_bf16 v[12:15], v[144:147], v[184:187], v[12:15]
	v_mfma_f32_16x16x32_bf16 v[4:7], v[152:155], v[184:187], v[4:7]
	v_mfma_f32_16x16x32_bf16 v[60:63], v[148:151], v[164:167], v[60:63]
	v_mfma_f32_16x16x32_bf16 v[52:55], v[156:159], v[164:167], v[52:55]
	v_mfma_f32_16x16x32_bf16 v[44:47], v[148:151], v[172:175], v[44:47]
	v_mfma_f32_16x16x32_bf16 v[36:39], v[156:159], v[172:175], v[36:39]
	v_mfma_f32_16x16x32_bf16 v[28:31], v[148:151], v[180:183], v[28:31]
	v_mfma_f32_16x16x32_bf16 v[20:23], v[156:159], v[180:183], v[20:23]
	v_mfma_f32_16x16x32_bf16 v[12:15], v[148:151], v[188:191], v[12:15]
	v_mfma_f32_16x16x32_bf16 v[4:7], v[156:159], v[188:191], v[4:7]
	s_barrier
	s_setprio 0
	s_add_u32 s34, s28, 0x80000
	s_addc_u32 s35, s29, 0
	s_add_i32 s46, s46, s31
	s_mov_b32 m0, s46
	s_nop 0
	global_load_lds_dwordx4 v132, s[34:35]
	s_add_i32 m0, s46, 0x2000
	s_nop 0
	global_load_lds_dwordx4 v128, s[34:35]
	s_waitcnt vmcnt(6)
	s_setprio 1
	s_barrier
; #define PG8_STAGE(bufoff, gbase, voff) do { _Pragma("unroll") for (int _i = 0; _i < 2; ++_i) \
;         __builtin_amdgcn_global_load_lds((const unsigned*)((const char*)(gbase) + (voff)[_i]), (LAS unsigned*)(lds + (bufoff) + ldsw + _i * 8192), 16, 0, 0); } while (0)
; #define PG8_LDA(dst, b, h) do { _Pragma("unroll") for (int m = 0; m < 4; ++m) _Pragma("unroll") for (int k = 0; k < 2; ++k) dst[m][k] = *(const LAS bf16x8*)(lds + PG8_SA(b, h) + aoff + m * 2048 + k * 1024); } while (0)
; #define PG8_LDB(dst, b, h) do { _Pragma("unroll") for (int n = 0; n < 2; ++n) _Pragma("unroll") for (int k = 0; k < 2; ++k) dst[n][k] = *(const LAS bf16x8*)(lds + PG8_SB(b, h) + boff + n * 2048 + k * 1024); } while (0)
; #define PG8_MMA(ai, bj, At, Bt) do { __builtin_amdgcn_s_setprio(1); _Pragma("unroll") for (int m = 0; m < 4; ++m) _Pragma("unroll") for (int n = 0; n < 2; ++n) _Pragma("unroll") for (int k = 0; k < 2; ++k) \
;         acc[ai][bj][m][n] = __builtin_amdgcn_mfma_f32_16x16x32_bf16(Bt[n][k], At[m][k], acc[ai][bj][m][n], 0, 0, 0); __builtin_amdgcn_s_setprio(0); } while (0)
; #define PG8_WAIT_V(n) asm volatile("s_waitcnt vmcnt(" #n ")" ::: "memory")
; #define PG8_WAIT_L(n) asm volatile("s_waitcnt lgkmcnt(" #n ")" ::: "memory")
; #define PG8_BAR __builtin_amdgcn_s_barrier()
; #define PG8_SCHED __builtin_amdgcn_sched_barrier(0)
; template <class Epi>
; __device__ __forceinline__ void gemm_phase(LAS unsigned char* lds, const Gemm g, const Epi& E) {
;     ...
;             PG8_WAIT_V(6); PG8_BAR; PG8_MMA(1, 1, At, B1); PG8_BAR;
;             PG8_LDB(B0, 1, 0); PG8_SCHED; PG8_LDA(At, 1, 0); PG8_STAGE(PG8_SA(0, 1), a2 + hstep, voffA);
;             PG8_WAIT_L(8); PG8_BAR; PG8_WAIT_L(0); PG8_MMA(0, 0, At, B0); PG8_BAR; PG8_SCHED;
;             PG8_LDB(B1, 1, 1); PG8_STAGE(PG8_SB(1, 0), b3, voffB);
;             PG8_BAR; PG8_WAIT_L(0); PG8_MMA(0, 1, At, B1); PG8_BAR;
;             PG8_LDA(At, 1, 1); PG8_STAGE(PG8_SA(1, 0), a3, voffA);
;             PG8_BAR; PG8_WAIT_L(0); PG8_MMA(1, 0, At, B0); PG8_BAR; PG8_SCHED;
;             PG8_STAGE(PG8_SB(1, 1), b3 + hstep, voffB);
	v_mfma_f32_16x16x32_bf16 v[56:59], v[192:195], v[160:163], v[56:59]
	v_mfma_f32_16x16x32_bf16 v[48:51], v[200:203], v[160:163], v[48:51]
	v_mfma_f32_16x16x32_bf16 v[40:43], v[192:195], v[168:171], v[40:43]
	v_mfma_f32_16x16x32_bf16 v[32:35], v[200:203], v[168:171], v[32:35]
	v_mfma_f32_16x16x32_bf16 v[24:27], v[192:195], v[176:179], v[24:27]
	v_mfma_f32_16x16x32_bf16 v[16:19], v[200:203], v[176:179], v[16:19]
	v_mfma_f32_16x16x32_bf16 v[8:11], v[192:195], v[184:187], v[8:11]
	v_mfma_f32_16x16x32_bf16 v[0:3], v[200:203], v[184:187], v[0:3]
	v_mfma_f32_16x16x32_bf16 v[56:59], v[196:199], v[164:167], v[56:59]
	v_mfma_f32_16x16x32_bf16 v[48:51], v[204:207], v[164:167], v[48:51]
	v_mfma_f32_16x16x32_bf16 v[40:43], v[196:199], v[172:175], v[40:43]
	v_mfma_f32_16x16x32_bf16 v[32:35], v[204:207], v[172:175], v[32:35]
	v_mfma_f32_16x16x32_bf16 v[24:27], v[196:199], v[180:183], v[24:27]
	v_mfma_f32_16x16x32_bf16 v[16:19], v[204:207], v[180:183], v[16:19]
	v_mfma_f32_16x16x32_bf16 v[8:11], v[196:199], v[188:191], v[8:11]
	v_mfma_f32_16x16x32_bf16 v[0:3], v[204:207], v[188:191], v[0:3]
	s_barrier
	s_setprio 0
	s_add_i32 s46, 0, 0x18000
	v_add_u32_e32 v143, s46, v141
	ds_read_b128 v[144:147], v143
	ds_read_b128 v[148:151], v143 offset:1024
	ds_read_b128 v[152:155], v143 offset:2048
	ds_read_b128 v[156:159], v143 offset:3072
	s_add_u32 s34, s36, 0x80000
	s_addc_u32 s35, s37, 0
	s_mov_b32 m0, s69
	ds_read_b128 v[160:163], v142 offset:32768
	ds_read_b128 v[164:167], v142 offset:33792
	ds_read_b128 v[168:171], v142 offset:34816
	ds_read_b128 v[172:175], v142 offset:35840
	ds_read_b128 v[176:179], v142 offset:36864
	ds_read_b128 v[180:183], v142 offset:37888
	ds_read_b128 v[184:187], v142 offset:38912
	ds_read_b128 v[188:191], v142 offset:39936
	global_load_lds_dwordx4 v134, s[34:35]
	s_mov_b32 m0, s70
	s_nop 0
	global_load_lds_dwordx4 v130, s[34:35]
	s_waitcnt lgkmcnt(8)
	s_setprio 1
	s_barrier
	s_waitcnt lgkmcnt(0)
	v_mfma_f32_16x16x32_bf16 v[124:127], v[144:147], v[160:163], v[124:127]
	v_mfma_f32_16x16x32_bf16 v[116:119], v[152:155], v[160:163], v[116:119]
	v_mfma_f32_16x16x32_bf16 v[108:111], v[144:147], v[168:171], v[108:111]
	v_mfma_f32_16x16x32_bf16 v[100:103], v[152:155], v[168:171], v[100:103]
	v_mfma_f32_16x16x32_bf16 v[92:95], v[144:147], v[176:179], v[92:95]
	v_mfma_f32_16x16x32_bf16 v[84:87], v[152:155], v[176:179], v[84:87]
	v_mfma_f32_16x16x32_bf16 v[76:79], v[144:147], v[184:187], v[76:79]
	v_mfma_f32_16x16x32_bf16 v[68:71], v[152:155], v[184:187], v[68:71]
	v_mfma_f32_16x16x32_bf16 v[124:127], v[148:151], v[164:167], v[124:127]
	v_mfma_f32_16x16x32_bf16 v[116:119], v[156:159], v[164:167], v[116:119]
	v_mfma_f32_16x16x32_bf16 v[108:111], v[148:151], v[172:175], v[108:111]
	v_mfma_f32_16x16x32_bf16 v[100:103], v[156:159], v[172:175], v[100:103]
	v_mfma_f32_16x16x32_bf16 v[92:95], v[148:151], v[180:183], v[92:95]
	v_mfma_f32_16x16x32_bf16 v[84:87], v[156:159], v[180:183], v[84:87]
	v_mfma_f32_16x16x32_bf16 v[76:79], v[148:151], v[188:191], v[76:79]
	v_mfma_f32_16x16x32_bf16 v[68:71], v[156:159], v[188:191], v[68:71]
	s_barrier
	s_setprio 0
	s_add_i32 s34, 0, 0x1c000
	s_add_i32 s35, s46, s31
	v_add_u32_e32 v143, s34, v141
	s_mov_b32 m0, s35
	ds_read_b128 v[192:195], v143
	ds_read_b128 v[196:199], v143 offset:1024
	ds_read_b128 v[200:203], v143 offset:2048
	ds_read_b128 v[204:207], v143 offset:3072
	s_add_u32 s98, s28, 0x80
	s_addc_u32 s99, s29, 0
	global_load_lds_dwordx4 v132, s[98:99]
	s_add_i32 m0, s35, 0x2000
	s_add_u32 s100, s28, 0x80
	s_addc_u32 s101, s29, 0
	global_load_lds_dwordx4 v128, s[100:101]
	s_setprio 1
	s_barrier
	s_waitcnt lgkmcnt(0)
	v_mfma_f32_16x16x32_bf16 v[120:123], v[192:195], v[160:163], v[120:123]
	v_mfma_f32_16x16x32_bf16 v[112:115], v[200:203], v[160:163], v[112:115]
	v_mfma_f32_16x16x32_bf16 v[104:107], v[192:195], v[168:171], v[104:107]
	v_mfma_f32_16x16x32_bf16 v[96:99], v[200:203], v[168:171], v[96:99]
	v_mfma_f32_16x16x32_bf16 v[88:91], v[192:195], v[176:179], v[88:91]
	v_mfma_f32_16x16x32_bf16 v[80:83], v[200:203], v[176:179], v[80:83]
	v_mfma_f32_16x16x32_bf16 v[72:75], v[192:195], v[184:187], v[72:75]
	v_mfma_f32_16x16x32_bf16 v[64:67], v[200:203], v[184:187], v[64:67]
	v_mfma_f32_16x16x32_bf16 v[120:123], v[196:199], v[164:167], v[120:123]
	v_mfma_f32_16x16x32_bf16 v[112:115], v[204:207], v[164:167], v[112:115]
	v_mfma_f32_16x16x32_bf16 v[104:107], v[196:199], v[172:175], v[104:107]
	v_mfma_f32_16x16x32_bf16 v[96:99], v[204:207], v[172:175], v[96:99]
	v_mfma_f32_16x16x32_bf16 v[88:91], v[196:199], v[180:183], v[88:91]
	v_mfma_f32_16x16x32_bf16 v[80:83], v[204:207], v[180:183], v[80:83]
	v_mfma_f32_16x16x32_bf16 v[72:75], v[196:199], v[188:191], v[72:75]
	v_mfma_f32_16x16x32_bf16 v[64:67], v[204:207], v[188:191], v[64:67]
	s_barrier
	s_setprio 0
	s_mov_b32 m0, s2
	ds_read_b128 v[160:163], v142 offset:49152
	ds_read_b128 v[164:167], v142 offset:50176
	ds_read_b128 v[168:171], v142 offset:51200
	ds_read_b128 v[172:175], v142 offset:52224
	ds_read_b128 v[176:179], v142 offset:53248
	ds_read_b128 v[180:183], v142 offset:54272
	ds_read_b128 v[184:187], v142 offset:55296
	ds_read_b128 v[188:191], v142 offset:56320
	s_add_u32 s98, s36, 0x80
	s_addc_u32 s99, s37, 0
	global_load_lds_dwordx4 v134, s[98:99]
	s_mov_b32 m0, s71
	s_add_u32 s100, s36, 0x80
	s_addc_u32 s101, s37, 0
	global_load_lds_dwordx4 v130, s[100:101]
	s_setprio 1
	s_barrier
; __device__ __forceinline__ u32x4 pack8u(f32x4 a, f32x4 b) { u32x4 w = {cvt_pk_bf16(a[0], a[1]), cvt_pk_bf16(a[2], a[3]), cvt_pk_bf16(b[0], b[1]), cvt_pk_bf16(b[2], b[3])}; return w; }
; __device__ __forceinline__ float siluf_(float x) { return x * __builtin_amdgcn_rcpf(1.0f + __expf(-x)); }
; #define PG8_STAGE(bufoff, gbase, voff) do { _Pragma("unroll") for (int _i = 0; _i < 2; ++_i) \
;         __builtin_amdgcn_global_load_lds((const unsigned*)((const char*)(gbase) + (voff)[_i]), (LAS unsigned*)(lds + (bufoff) + ldsw + _i * 8192), 16, 0, 0); } while (0)
; #define PG8_LDA(dst, b, h) do { _Pragma("unroll") for (int m = 0; m < 4; ++m) _Pragma("unroll") for (int k = 0; k < 2; ++k) dst[m][k] = *(const LAS bf16x8*)(lds + PG8_SA(b, h) + aoff + m * 2048 + k * 1024); } while (0)
; #define PG8_WAIT_V(n) asm volatile("s_waitcnt vmcnt(" #n ")" ::: "memory")
; #define PG8_WAIT_L(n) asm volatile("s_waitcnt lgkmcnt(" #n ")" ::: "memory")
; template <class Epi>
; __device__ __forceinline__ void gemm_phase(LAS unsigned char* lds, const Gemm g, const Epi& E) {
;     ...
;             PG8_WAIT_V(6); PG8_BAR; PG8_MMA(1, 1, At, B1); PG8_BAR;
;             PG8_LDB(B0, 1, 0); PG8_SCHED; PG8_LDA(At, 1, 0); PG8_STAGE(PG8_SA(0, 1), a2 + hstep, voffA);
;             PG8_WAIT_L(8); PG8_BAR; PG8_WAIT_L(0); PG8_MMA(0, 0, At, B0); PG8_BAR; PG8_SCHED;
;             PG8_LDB(B1, 1, 1); PG8_STAGE(PG8_SB(1, 0), b3, voffB);
;             PG8_BAR; PG8_WAIT_L(0); PG8_MMA(0, 1, At, B1); PG8_BAR;
;             PG8_LDA(At, 1, 1); PG8_STAGE(PG8_SA(1, 0), a3, voffA);
;             PG8_BAR; PG8_WAIT_L(0); PG8_MMA(1, 0, At, B0); PG8_BAR; PG8_SCHED;
;             PG8_STAGE(PG8_SB(1, 1), b3 + hstep, voffB);
;             PG8_WAIT_V(6); PG8_BAR; PG8_MMA(1, 1, At, B1); PG8_BAR;
;     __device__ __forceinline__ void operator()(const AccT& acc, const Unit& u, int wr, int wc, int fr, int fq) const {
; #pragma unroll
;         for (int ai = 0; ai < 2; ++ai)
; #pragma unroll
;             for (int m = 0; m < 4; ++m) {
;                 const int row = u.pm * 256 + ai * 128 + wr * 64 + m * 16 + fr;
;                 f32x4 o0, o1;
; #pragma unroll
;                 for (int j = 0; j < 4; ++j) { o0[j] = siluf_(acc[ai][0][m][0][j]) * acc[ai][1][m][0][j]; o1[j] = siluf_(acc[ai][0][m][1][j]) * acc[ai][1][m][1][j]; }
;                 *(u32x4*)(ACT + (size_t)row * DFF + u.pn * 128 + wc * 32 + fq * 8) = pack8u(o0, o1);
	s_waitcnt lgkmcnt(0)
	v_mfma_f32_16x16x32_bf16 v[60:63], v[144:147], v[160:163], v[60:63]
	v_mfma_f32_16x16x32_bf16 v[52:55], v[152:155], v[160:163], v[52:55]
	v_mfma_f32_16x16x32_bf16 v[44:47], v[144:147], v[168:171], v[44:47]
	v_mfma_f32_16x16x32_bf16 v[36:39], v[152:155], v[168:171], v[36:39]
	v_mfma_f32_16x16x32_bf16 v[28:31], v[144:147], v[176:179], v[28:31]
	v_mfma_f32_16x16x32_bf16 v[20:23], v[152:155], v[176:179], v[20:23]
	v_mfma_f32_16x16x32_bf16 v[12:15], v[144:147], v[184:187], v[12:15]
	v_mfma_f32_16x16x32_bf16 v[4:7], v[152:155], v[184:187], v[4:7]
	v_mfma_f32_16x16x32_bf16 v[60:63], v[148:151], v[164:167], v[60:63]
	v_mfma_f32_16x16x32_bf16 v[52:55], v[156:159], v[164:167], v[52:55]
	v_mfma_f32_16x16x32_bf16 v[44:47], v[148:151], v[172:175], v[44:47]
	v_mfma_f32_16x16x32_bf16 v[36:39], v[156:159], v[172:175], v[36:39]
	v_mfma_f32_16x16x32_bf16 v[28:31], v[148:151], v[180:183], v[28:31]
	v_mfma_f32_16x16x32_bf16 v[20:23], v[156:159], v[180:183], v[20:23]
	v_mfma_f32_16x16x32_bf16 v[12:15], v[148:151], v[188:191], v[12:15]
	v_mfma_f32_16x16x32_bf16 v[4:7], v[156:159], v[188:191], v[4:7]
	s_barrier
	s_setprio 0
	s_add_u32 s28, s28, 0x80080
	s_addc_u32 s29, s29, 0
	s_add_i32 s34, s34, s31
	s_mov_b32 m0, s34
	s_nop 0
	global_load_lds_dwordx4 v132, s[28:29]
	s_add_i32 m0, s34, 0x2000
	s_nop 0
	global_load_lds_dwordx4 v128, s[28:29]
	s_waitcnt vmcnt(6)
	s_setprio 1
	s_barrier
	v_mfma_f32_16x16x32_bf16 v[56:59], v[192:195], v[160:163], v[56:59]
	v_mfma_f32_16x16x32_bf16 v[48:51], v[200:203], v[160:163], v[48:51]
	v_mfma_f32_16x16x32_bf16 v[40:43], v[192:195], v[168:171], v[40:43]
	v_mfma_f32_16x16x32_bf16 v[32:35], v[200:203], v[168:171], v[32:35]
	v_mfma_f32_16x16x32_bf16 v[24:27], v[192:195], v[176:179], v[24:27]
	v_mfma_f32_16x16x32_bf16 v[16:19], v[200:203], v[176:179], v[16:19]
	v_mfma_f32_16x16x32_bf16 v[8:11], v[192:195], v[184:187], v[8:11]
	v_mfma_f32_16x16x32_bf16 v[0:3], v[200:203], v[184:187], v[0:3]
	v_mfma_f32_16x16x32_bf16 v[56:59], v[196:199], v[164:167], v[56:59]
	v_mfma_f32_16x16x32_bf16 v[48:51], v[204:207], v[164:167], v[48:51]
	v_mfma_f32_16x16x32_bf16 v[40:43], v[196:199], v[172:175], v[40:43]
	v_mfma_f32_16x16x32_bf16 v[32:35], v[204:207], v[172:175], v[32:35]
	v_mfma_f32_16x16x32_bf16 v[24:27], v[196:199], v[180:183], v[24:27]
	v_mfma_f32_16x16x32_bf16 v[16:19], v[204:207], v[180:183], v[16:19]
	v_mfma_f32_16x16x32_bf16 v[8:11], v[196:199], v[188:191], v[8:11]
	v_mfma_f32_16x16x32_bf16 v[0:3], v[204:207], v[188:191], v[0:3]
	s_barrier
	s_setprio 0
	s_add_i32 s89, s89, 2
	s_add_u32 s26, s26, 0x100
	s_addc_u32 s27, s27, 0
	s_add_u32 s82, s82, 0x100
	s_addc_u32 s83, s83, 0
	s_cmp_gt_u32 s89, 29
	s_cbranch_scc0 .LBB0_30
	v_mul_f32_e32 v145, 0xbfb8aa3b, v116
	v_exp_f32_e32 v145, v145
	v_mul_f32_e32 v144, 0xbfb8aa3b, v124
	v_exp_f32_e32 v144, v144
	v_readlane_b32 s28, v252, 37
	v_add_f32_e32 v145, 1.0, v145
	v_rcp_f32_e32 v146, v145
	v_mul_f32_e32 v145, 0xbfb8aa3b, v125
	v_exp_f32_e32 v145, v145
	v_add_f32_e32 v144, 1.0, v144
	v_rcp_f32_e32 v144, v144
	s_lshl_b32 s26, s76, 7
	v_add_f32_e32 v145, 1.0, v145
	v_rcp_f32_e32 v145, v145
	v_readlane_b32 s29, v252, 38
	v_lshl_add_u32 v143, s88, 8, v140
	s_ashr_i32 s27, s26, 31
	v_pk_mul_f32 v[124:125], v[124:125], v[144:145]
	s_movk_i32 s34, 0x2c00
	v_pk_mul_f32 v[120:121], v[124:125], v[120:121]
	v_mul_f32_e32 v124, 0xbfb8aa3b, v117
	v_exp_f32_e32 v124, v124
	s_lshl_b64 s[88:89], s[26:27], 1
	s_and_b64 vcc, exec, s[40:41]
	s_mov_b32 s76, s42
	v_add_f32_e32 v124, 1.0, v124
	v_rcp_f32_e32 v147, v124
	s_nop 0
	v_pk_mul_f32 v[116:117], v[116:117], v[146:147]
	s_nop 0
	v_pk_mul_f32 v[112:113], v[116:117], v[112:113]
	v_mul_f32_e32 v117, 0xbfb8aa3b, v118
	v_exp_f32_e32 v117, v117
	v_mul_f32_e32 v116, 0xbfb8aa3b, v126
	v_exp_f32_e32 v116, v116
	v_add_f32_e32 v117, 1.0, v117
	v_rcp_f32_e32 v124, v117
	v_mul_f32_e32 v117, 0xbfb8aa3b, v127
	v_exp_f32_e32 v117, v117
	v_add_f32_e32 v116, 1.0, v116
	v_rcp_f32_e32 v116, v116
	v_add_f32_e32 v117, 1.0, v117
	v_rcp_f32_e32 v117, v117
	s_nop 0
	v_pk_mul_f32 v[116:117], v[126:127], v[116:117]
	s_nop 0
	v_pk_mul_f32 v[116:117], v[116:117], v[122:123]
	v_mul_f32_e32 v122, 0xbfb8aa3b, v119
	v_exp_f32_e32 v122, v122
	s_nop 0
	v_add_f32_e32 v122, 1.0, v122
	v_rcp_f32_e32 v125, v122
	s_nop 0
	v_pk_mul_f32 v[118:119], v[118:119], v[124:125]
	s_nop 0
	v_pk_mul_f32 v[118:119], v[118:119], v[114:115]
	v_cvt_pk_bf16_f32 v115, v116, v117
	v_cvt_pk_bf16_f32 v116, v112, v113
	v_mov_b64_e32 v[112:113], s[28:29]
	v_cvt_pk_bf16_f32 v117, v118, v119
	v_mad_i64_i32 v[118:119], s[28:29], v143, s34, v[112:113]
	v_lshl_add_u64 v[118:119], v[118:119], 0, s[88:89]
	s_mov_b64 s[28:29], s[90:91]
	v_lshl_add_u64 v[118:119], v[118:119], 0, s[28:29]
	v_cvt_pk_bf16_f32 v114, v120, v121
	v_lshl_add_u64 v[118:119], v[118:119], 0, v[208:209]
	global_store_dwordx4 v[118:119], v[114:117], off
	s_nop 1
	v_mul_f32_e32 v115, 0xbfb8aa3b, v100
	v_exp_f32_e32 v115, v115
	v_mul_f32_e32 v114, 0xbfb8aa3b, v108
	v_exp_f32_e32 v114, v114
	v_add_f32_e32 v115, 1.0, v115
	v_rcp_f32_e32 v116, v115
	v_mul_f32_e32 v115, 0xbfb8aa3b, v109
	v_exp_f32_e32 v115, v115
	v_add_f32_e32 v114, 1.0, v114
	v_rcp_f32_e32 v114, v114
	v_add_f32_e32 v115, 1.0, v115
	v_rcp_f32_e32 v115, v115
	s_nop 0
	v_pk_mul_f32 v[108:109], v[108:109], v[114:115]
	s_nop 0
	v_pk_mul_f32 v[104:105], v[108:109], v[104:105]
	v_mul_f32_e32 v108, 0xbfb8aa3b, v101
	v_exp_f32_e32 v108, v108
	s_nop 0
	v_add_f32_e32 v108, 1.0, v108
	v_rcp_f32_e32 v117, v108
	s_nop 0
	v_pk_mul_f32 v[100:101], v[100:101], v[116:117]
	s_nop 0
	v_pk_mul_f32 v[100:101], v[100:101], v[96:97]
	v_mul_f32_e32 v97, 0xbfb8aa3b, v102
	v_exp_f32_e32 v97, v97
; __device__ __forceinline__ u32x4 pack8u(f32x4 a, f32x4 b) { u32x4 w = {cvt_pk_bf16(a[0], a[1]), cvt_pk_bf16(a[2], a[3]), cvt_pk_bf16(b[0], b[1]), cvt_pk_bf16(b[2], b[3])}; return w; }
; __device__ __forceinline__ float siluf_(float x) { return x * __builtin_amdgcn_rcpf(1.0f + __expf(-x)); }
;     __device__ __forceinline__ void operator()(const AccT& acc, const Unit& u, int wr, int wc, int fr, int fq) const {
; #pragma unroll
;         for (int ai = 0; ai < 2; ++ai)
; #pragma unroll
;             for (int m = 0; m < 4; ++m) {
;                 const int row = u.pm * 256 + ai * 128 + wr * 64 + m * 16 + fr;
;                 f32x4 o0, o1;
; #pragma unroll
;                 for (int j = 0; j < 4; ++j) { o0[j] = siluf_(acc[ai][0][m][0][j]) * acc[ai][1][m][0][j]; o1[j] = siluf_(acc[ai][0][m][1][j]) * acc[ai][1][m][1][j]; }
;                 *(u32x4*)(ACT + (size_t)row * DFF + u.pn * 128 + wc * 32 + fq * 8) = pack8u(o0, o1);
	v_mul_f32_e32 v96, 0xbfb8aa3b, v110
	v_exp_f32_e32 v96, v96
	v_add_f32_e32 v97, 1.0, v97
	v_rcp_f32_e32 v108, v97
	v_mul_f32_e32 v97, 0xbfb8aa3b, v111
	v_exp_f32_e32 v97, v97
	v_add_f32_e32 v96, 1.0, v96
	v_rcp_f32_e32 v96, v96
	v_add_f32_e32 v97, 1.0, v97
	v_rcp_f32_e32 v97, v97
	s_nop 0
	v_pk_mul_f32 v[96:97], v[110:111], v[96:97]
	s_nop 0
	v_pk_mul_f32 v[106:107], v[96:97], v[106:107]
	v_mul_f32_e32 v96, 0xbfb8aa3b, v103
	v_exp_f32_e32 v96, v96
	s_nop 0
	v_add_f32_e32 v96, 1.0, v96
	v_rcp_f32_e32 v109, v96
	s_nop 0
	v_pk_mul_f32 v[96:97], v[102:103], v[108:109]
	v_or_b32_e32 v108, 16, v143
	v_pk_mul_f32 v[102:103], v[96:97], v[98:99]
	v_cvt_pk_bf16_f32 v98, v100, v101
	v_mad_i64_i32 v[100:101], s[26:27], v108, s34, v[112:113]
	v_lshl_add_u64 v[100:101], v[100:101], 0, s[88:89]
	v_lshl_add_u64 v[100:101], v[100:101], 0, s[28:29]
	v_cvt_pk_bf16_f32 v96, v104, v105
	v_cvt_pk_bf16_f32 v97, v106, v107
	v_cvt_pk_bf16_f32 v99, v102, v103
	v_lshl_add_u64 v[100:101], v[100:101], 0, v[208:209]
	global_store_dwordx4 v[100:101], v[96:99], off
	s_nop 1
	v_mul_f32_e32 v97, 0xbfb8aa3b, v84
	v_exp_f32_e32 v97, v97
	v_mul_f32_e32 v96, 0xbfb8aa3b, v92
	v_exp_f32_e32 v96, v96
	v_add_f32_e32 v97, 1.0, v97
	v_rcp_f32_e32 v98, v97
	v_mul_f32_e32 v97, 0xbfb8aa3b, v93
	v_exp_f32_e32 v97, v97
	v_add_f32_e32 v96, 1.0, v96
	v_rcp_f32_e32 v96, v96
	v_add_f32_e32 v97, 1.0, v97
	v_rcp_f32_e32 v97, v97
	s_nop 0
	v_pk_mul_f32 v[92:93], v[92:93], v[96:97]
	s_nop 0
	v_pk_mul_f32 v[88:89], v[92:93], v[88:89]
	v_mul_f32_e32 v92, 0xbfb8aa3b, v85
	v_exp_f32_e32 v92, v92
	s_nop 0
	v_add_f32_e32 v92, 1.0, v92
	v_rcp_f32_e32 v99, v92
	s_nop 0
	v_pk_mul_f32 v[84:85], v[84:85], v[98:99]
	s_nop 0
	v_pk_mul_f32 v[84:85], v[84:85], v[80:81]
	v_mul_f32_e32 v81, 0xbfb8aa3b, v86
	v_exp_f32_e32 v81, v81
	v_mul_f32_e32 v80, 0xbfb8aa3b, v94
	v_exp_f32_e32 v80, v80
	v_add_f32_e32 v81, 1.0, v81
	v_rcp_f32_e32 v92, v81
	v_mul_f32_e32 v81, 0xbfb8aa3b, v95
	v_exp_f32_e32 v81, v81
	v_add_f32_e32 v80, 1.0, v80
	v_rcp_f32_e32 v80, v80
	v_add_f32_e32 v81, 1.0, v81
	v_rcp_f32_e32 v81, v81
	s_nop 0
	v_pk_mul_f32 v[80:81], v[94:95], v[80:81]
	s_nop 0
	v_pk_mul_f32 v[90:91], v[80:81], v[90:91]
	v_mul_f32_e32 v80, 0xbfb8aa3b, v87
	v_exp_f32_e32 v80, v80
	s_nop 0
	v_add_f32_e32 v80, 1.0, v80
	v_rcp_f32_e32 v93, v80
	s_nop 0
	v_pk_mul_f32 v[80:81], v[86:87], v[92:93]
	v_or_b32_e32 v92, 32, v143
	v_pk_mul_f32 v[86:87], v[80:81], v[82:83]
	v_cvt_pk_bf16_f32 v82, v84, v85
	v_mad_i64_i32 v[84:85], s[26:27], v92, s34, v[112:113]
	v_lshl_add_u64 v[84:85], v[84:85], 0, s[88:89]
	v_lshl_add_u64 v[84:85], v[84:85], 0, s[28:29]
	v_cvt_pk_bf16_f32 v80, v88, v89
	v_cvt_pk_bf16_f32 v81, v90, v91
	v_cvt_pk_bf16_f32 v83, v86, v87
	v_lshl_add_u64 v[84:85], v[84:85], 0, v[208:209]
	global_store_dwordx4 v[84:85], v[80:83], off
	s_nop 1
	v_mul_f32_e32 v81, 0xbfb8aa3b, v68
	v_exp_f32_e32 v81, v81
	v_mul_f32_e32 v80, 0xbfb8aa3b, v76
	v_exp_f32_e32 v80, v80
	v_add_f32_e32 v81, 1.0, v81
	v_rcp_f32_e32 v82, v81
	v_mul_f32_e32 v81, 0xbfb8aa3b, v77
	v_exp_f32_e32 v81, v81
	v_add_f32_e32 v80, 1.0, v80
	v_rcp_f32_e32 v80, v80
	v_add_f32_e32 v81, 1.0, v81
	v_rcp_f32_e32 v81, v81
	s_nop 0
	v_pk_mul_f32 v[76:77], v[76:77], v[80:81]
	s_nop 0
	v_pk_mul_f32 v[72:73], v[76:77], v[72:73]
	v_mul_f32_e32 v76, 0xbfb8aa3b, v69
	v_exp_f32_e32 v76, v76
	s_nop 0
	v_add_f32_e32 v76, 1.0, v76
	v_rcp_f32_e32 v83, v76
	s_nop 0
	v_pk_mul_f32 v[68:69], v[68:69], v[82:83]
	s_nop 0
	v_pk_mul_f32 v[68:69], v[68:69], v[64:65]
	v_mul_f32_e32 v65, 0xbfb8aa3b, v70
	v_exp_f32_e32 v65, v65
	v_mul_f32_e32 v64, 0xbfb8aa3b, v78
	v_exp_f32_e32 v64, v64
	v_add_f32_e32 v65, 1.0, v65
	v_rcp_f32_e32 v76, v65
	v_mul_f32_e32 v65, 0xbfb8aa3b, v79
	v_exp_f32_e32 v65, v65
	v_add_f32_e32 v64, 1.0, v64
	v_rcp_f32_e32 v64, v64
	v_add_f32_e32 v65, 1.0, v65
	v_rcp_f32_e32 v65, v65
	s_nop 0
	v_pk_mul_f32 v[64:65], v[78:79], v[64:65]
	s_nop 0
	v_pk_mul_f32 v[74:75], v[64:65], v[74:75]
	v_mul_f32_e32 v64, 0xbfb8aa3b, v71
	v_exp_f32_e32 v64, v64
	s_nop 0
	v_add_f32_e32 v64, 1.0, v64
	v_rcp_f32_e32 v77, v64
	s_nop 0
	v_pk_mul_f32 v[64:65], v[70:71], v[76:77]
	v_or_b32_e32 v76, 48, v143
	v_pk_mul_f32 v[70:71], v[64:65], v[66:67]
	v_cvt_pk_bf16_f32 v66, v68, v69
	v_mad_i64_i32 v[68:69], s[26:27], v76, s34, v[112:113]
	v_lshl_add_u64 v[68:69], v[68:69], 0, s[88:89]
	v_lshl_add_u64 v[68:69], v[68:69], 0, s[28:29]
	v_cvt_pk_bf16_f32 v64, v72, v73
	v_cvt_pk_bf16_f32 v65, v74, v75
	v_cvt_pk_bf16_f32 v67, v70, v71
	v_lshl_add_u64 v[68:69], v[68:69], 0, v[208:209]
	global_store_dwordx4 v[68:69], v[64:67], off
	v_add_u32_e32 v68, 0x80, v143
	s_nop 0
	v_mul_f32_e32 v65, 0xbfb8aa3b, v52
	v_exp_f32_e32 v65, v65
	v_mul_f32_e32 v64, 0xbfb8aa3b, v60
	v_exp_f32_e32 v64, v64
	v_add_f32_e32 v65, 1.0, v65
	v_rcp_f32_e32 v66, v65
	v_mul_f32_e32 v65, 0xbfb8aa3b, v61
	v_exp_f32_e32 v65, v65
	v_add_f32_e32 v64, 1.0, v64
	v_rcp_f32_e32 v64, v64
	v_add_f32_e32 v65, 1.0, v65
	v_rcp_f32_e32 v65, v65
	s_nop 0
	v_pk_mul_f32 v[60:61], v[60:61], v[64:65]
	s_nop 0
	v_pk_mul_f32 v[56:57], v[60:61], v[56:57]
	v_mul_f32_e32 v60, 0xbfb8aa3b, v53
	v_exp_f32_e32 v60, v60
	s_nop 0
	v_add_f32_e32 v60, 1.0, v60
	v_rcp_f32_e32 v67, v60
	s_nop 0
	v_pk_mul_f32 v[52:53], v[52:53], v[66:67]
	s_nop 0
	v_pk_mul_f32 v[52:53], v[52:53], v[48:49]
	v_mul_f32_e32 v49, 0xbfb8aa3b, v54
	v_exp_f32_e32 v49, v49
	v_mul_f32_e32 v48, 0xbfb8aa3b, v62
	v_exp_f32_e32 v48, v48
	v_add_f32_e32 v49, 1.0, v49
	v_rcp_f32_e32 v60, v49
	v_mul_f32_e32 v49, 0xbfb8aa3b, v63
	v_exp_f32_e32 v49, v49
	v_add_f32_e32 v48, 1.0, v48
	v_rcp_f32_e32 v48, v48
	v_add_f32_e32 v49, 1.0, v49
	v_rcp_f32_e32 v49, v49
	s_nop 0
	v_pk_mul_f32 v[48:49], v[62:63], v[48:49]
; __device__ __forceinline__ u32x4 pack8u(f32x4 a, f32x4 b) { u32x4 w = {cvt_pk_bf16(a[0], a[1]), cvt_pk_bf16(a[2], a[3]), cvt_pk_bf16(b[0], b[1]), cvt_pk_bf16(b[2], b[3])}; return w; }
; __device__ __forceinline__ float siluf_(float x) { return x * __builtin_amdgcn_rcpf(1.0f + __expf(-x)); }
; #define PG8_WAIT_V(n) asm volatile("s_waitcnt vmcnt(" #n ")" ::: "memory")
; #define PG8_BAR __builtin_amdgcn_s_barrier()
; template <class Epi>
; __device__ __forceinline__ void gemm_phase(LAS unsigned char* lds, const Gemm g, const Epi& E) {
;     ...
;         if (!has_next) break;
; #pragma unroll
;         for (int a = 0; a < 2; ++a)
; #pragma unroll
;             for (int b = 0; b < 2; ++b)
; #pragma unroll
;                 for (int m = 0; m < 4; ++m)
; #pragma unroll
;                     for (int n = 0; n < 2; ++n) acc[a][b][m][n] = (f32x4){0.f, 0.f, 0.f, 0.f};
;         cur = nxt; cA = nA; cB = nB; ++ui;
;     }
;     PG8_WAIT_V(0);
;     if (wr == 0) PG8_BAR;
;     PG8_BAR;
;     __device__ __forceinline__ void operator()(const AccT& acc, const Unit& u, int wr, int wc, int fr, int fq) const {
; #pragma unroll
;         for (int ai = 0; ai < 2; ++ai)
; #pragma unroll
;             for (int m = 0; m < 4; ++m) {
;                 const int row = u.pm * 256 + ai * 128 + wr * 64 + m * 16 + fr;
;                 f32x4 o0, o1;
; #pragma unroll
;                 for (int j = 0; j < 4; ++j) { o0[j] = siluf_(acc[ai][0][m][0][j]) * acc[ai][1][m][0][j]; o1[j] = siluf_(acc[ai][0][m][1][j]) * acc[ai][1][m][1][j]; }
;                 *(u32x4*)(ACT + (size_t)row * DFF + u.pn * 128 + wc * 32 + fq * 8) = pack8u(o0, o1);
	s_nop 0
	v_pk_mul_f32 v[58:59], v[48:49], v[58:59]
	v_mul_f32_e32 v48, 0xbfb8aa3b, v55
	v_exp_f32_e32 v48, v48
	s_nop 0
	v_add_f32_e32 v48, 1.0, v48
	v_rcp_f32_e32 v61, v48
	s_nop 0
	v_pk_mul_f32 v[48:49], v[54:55], v[60:61]
	s_nop 0
	v_pk_mul_f32 v[54:55], v[48:49], v[50:51]
	v_cvt_pk_bf16_f32 v50, v52, v53
	v_mad_i64_i32 v[52:53], s[26:27], v68, s34, v[112:113]
	v_lshl_add_u64 v[52:53], v[52:53], 0, s[88:89]
	v_lshl_add_u64 v[52:53], v[52:53], 0, s[28:29]
	v_cvt_pk_bf16_f32 v48, v56, v57
	v_cvt_pk_bf16_f32 v49, v58, v59
	v_cvt_pk_bf16_f32 v51, v54, v55
	v_lshl_add_u64 v[52:53], v[52:53], 0, v[208:209]
	global_store_dwordx4 v[52:53], v[48:51], off
	s_nop 1
	v_mul_f32_e32 v49, 0xbfb8aa3b, v36
	v_exp_f32_e32 v49, v49
	v_mul_f32_e32 v48, 0xbfb8aa3b, v44
	v_exp_f32_e32 v48, v48
	v_add_f32_e32 v49, 1.0, v49
	v_rcp_f32_e32 v50, v49
	v_mul_f32_e32 v49, 0xbfb8aa3b, v45
	v_exp_f32_e32 v49, v49
	v_add_f32_e32 v48, 1.0, v48
	v_rcp_f32_e32 v48, v48
	v_add_f32_e32 v49, 1.0, v49
	v_rcp_f32_e32 v49, v49
	s_nop 0
	v_pk_mul_f32 v[44:45], v[44:45], v[48:49]
	s_nop 0
	v_pk_mul_f32 v[40:41], v[44:45], v[40:41]
	v_mul_f32_e32 v44, 0xbfb8aa3b, v37
	v_exp_f32_e32 v44, v44
	s_nop 0
	v_add_f32_e32 v44, 1.0, v44
	v_rcp_f32_e32 v51, v44
	s_nop 0
	v_pk_mul_f32 v[36:37], v[36:37], v[50:51]
	s_nop 0
	v_pk_mul_f32 v[36:37], v[36:37], v[32:33]
	v_mul_f32_e32 v33, 0xbfb8aa3b, v38
	v_exp_f32_e32 v33, v33
	v_mul_f32_e32 v32, 0xbfb8aa3b, v46
	v_exp_f32_e32 v32, v32
	v_add_f32_e32 v33, 1.0, v33
	v_rcp_f32_e32 v44, v33
	v_mul_f32_e32 v33, 0xbfb8aa3b, v47
	v_exp_f32_e32 v33, v33
	v_add_f32_e32 v32, 1.0, v32
	v_rcp_f32_e32 v32, v32
	v_add_f32_e32 v33, 1.0, v33
	v_rcp_f32_e32 v33, v33
	s_nop 0
	v_pk_mul_f32 v[32:33], v[46:47], v[32:33]
	s_nop 0
	v_pk_mul_f32 v[42:43], v[32:33], v[42:43]
	v_mul_f32_e32 v32, 0xbfb8aa3b, v39
	v_exp_f32_e32 v32, v32
	s_nop 0
	v_add_f32_e32 v32, 1.0, v32
	v_rcp_f32_e32 v45, v32
	s_nop 0
	v_pk_mul_f32 v[32:33], v[38:39], v[44:45]
	v_add_u32_e32 v44, 0x90, v143
	v_pk_mul_f32 v[38:39], v[32:33], v[34:35]
	v_cvt_pk_bf16_f32 v34, v36, v37
	v_mad_i64_i32 v[36:37], s[26:27], v44, s34, v[112:113]
	v_lshl_add_u64 v[36:37], v[36:37], 0, s[88:89]
	v_lshl_add_u64 v[36:37], v[36:37], 0, s[28:29]
	v_cvt_pk_bf16_f32 v32, v40, v41
	v_cvt_pk_bf16_f32 v33, v42, v43
	v_cvt_pk_bf16_f32 v35, v38, v39
	v_lshl_add_u64 v[36:37], v[36:37], 0, v[208:209]
	global_store_dwordx4 v[36:37], v[32:35], off
	s_nop 1
	v_mul_f32_e32 v33, 0xbfb8aa3b, v20
	v_exp_f32_e32 v33, v33
	v_mul_f32_e32 v32, 0xbfb8aa3b, v28
	v_exp_f32_e32 v32, v32
	v_add_f32_e32 v33, 1.0, v33
	v_rcp_f32_e32 v34, v33
	v_mul_f32_e32 v33, 0xbfb8aa3b, v29
	v_exp_f32_e32 v33, v33
	v_add_f32_e32 v32, 1.0, v32
	v_rcp_f32_e32 v32, v32
	v_add_f32_e32 v33, 1.0, v33
	v_rcp_f32_e32 v33, v33
	s_nop 0
	v_pk_mul_f32 v[28:29], v[28:29], v[32:33]
	s_nop 0
	v_pk_mul_f32 v[24:25], v[28:29], v[24:25]
	v_mul_f32_e32 v28, 0xbfb8aa3b, v21
	v_exp_f32_e32 v28, v28
	s_nop 0
	v_add_f32_e32 v28, 1.0, v28
	v_rcp_f32_e32 v35, v28
	s_nop 0
	v_pk_mul_f32 v[20:21], v[20:21], v[34:35]
	s_nop 0
	v_pk_mul_f32 v[20:21], v[20:21], v[16:17]
	v_mul_f32_e32 v17, 0xbfb8aa3b, v22
	v_exp_f32_e32 v17, v17
	v_mul_f32_e32 v16, 0xbfb8aa3b, v30
	v_exp_f32_e32 v16, v16
	v_add_f32_e32 v17, 1.0, v17
	v_rcp_f32_e32 v28, v17
	v_mul_f32_e32 v17, 0xbfb8aa3b, v31
	v_exp_f32_e32 v17, v17
	v_add_f32_e32 v16, 1.0, v16
	v_rcp_f32_e32 v16, v16
	v_add_f32_e32 v17, 1.0, v17
	v_rcp_f32_e32 v17, v17
	s_nop 0
	v_pk_mul_f32 v[16:17], v[30:31], v[16:17]
	s_nop 0
	v_pk_mul_f32 v[26:27], v[16:17], v[26:27]
	v_mul_f32_e32 v16, 0xbfb8aa3b, v23
	v_exp_f32_e32 v16, v16
	s_nop 0
	v_add_f32_e32 v16, 1.0, v16
	v_rcp_f32_e32 v29, v16
	s_nop 0
	v_pk_mul_f32 v[16:17], v[22:23], v[28:29]
	v_add_u32_e32 v28, 0xa0, v143
	v_pk_mul_f32 v[22:23], v[16:17], v[18:19]
	v_cvt_pk_bf16_f32 v18, v20, v21
	v_mad_i64_i32 v[20:21], s[26:27], v28, s34, v[112:113]
	v_lshl_add_u64 v[20:21], v[20:21], 0, s[88:89]
	v_lshl_add_u64 v[20:21], v[20:21], 0, s[28:29]
	v_cvt_pk_bf16_f32 v16, v24, v25
	v_cvt_pk_bf16_f32 v17, v26, v27
	v_cvt_pk_bf16_f32 v19, v22, v23
	v_lshl_add_u64 v[20:21], v[20:21], 0, v[208:209]
	global_store_dwordx4 v[20:21], v[16:19], off
	s_nop 1
	v_mul_f32_e32 v17, 0xbfb8aa3b, v4
	v_exp_f32_e32 v17, v17
	v_mul_f32_e32 v16, 0xbfb8aa3b, v12
	v_exp_f32_e32 v16, v16
	v_add_f32_e32 v17, 1.0, v17
	v_rcp_f32_e32 v18, v17
	v_mul_f32_e32 v17, 0xbfb8aa3b, v13
	v_exp_f32_e32 v17, v17
	v_add_f32_e32 v16, 1.0, v16
	v_rcp_f32_e32 v16, v16
	v_add_f32_e32 v17, 1.0, v17
	v_rcp_f32_e32 v17, v17
	s_nop 0
	v_pk_mul_f32 v[12:13], v[12:13], v[16:17]
	s_nop 0
	v_pk_mul_f32 v[8:9], v[12:13], v[8:9]
	v_mul_f32_e32 v12, 0xbfb8aa3b, v5
	v_exp_f32_e32 v12, v12
	s_nop 0
	v_add_f32_e32 v12, 1.0, v12
	v_rcp_f32_e32 v19, v12
	s_nop 0
	v_pk_mul_f32 v[4:5], v[4:5], v[18:19]
	s_nop 0
	v_pk_mul_f32 v[4:5], v[4:5], v[0:1]
	v_mul_f32_e32 v1, 0xbfb8aa3b, v6
	v_exp_f32_e32 v1, v1
	v_mul_f32_e32 v0, 0xbfb8aa3b, v14
	v_exp_f32_e32 v0, v0
	v_add_f32_e32 v1, 1.0, v1
	v_rcp_f32_e32 v12, v1
	v_mul_f32_e32 v1, 0xbfb8aa3b, v15
	v_exp_f32_e32 v1, v1
	v_add_f32_e32 v0, 1.0, v0
	v_rcp_f32_e32 v0, v0
	v_add_f32_e32 v1, 1.0, v1
	v_rcp_f32_e32 v1, v1
	s_nop 0
	v_pk_mul_f32 v[0:1], v[14:15], v[0:1]
	s_nop 0
	v_pk_mul_f32 v[10:11], v[0:1], v[10:11]
	v_mul_f32_e32 v0, 0xbfb8aa3b, v7
	v_exp_f32_e32 v0, v0
	s_nop 0
	v_add_f32_e32 v0, 1.0, v0
	v_rcp_f32_e32 v13, v0
	s_nop 0
	v_pk_mul_f32 v[0:1], v[6:7], v[12:13]
	v_add_u32_e32 v12, 0xb0, v143
	v_pk_mul_f32 v[6:7], v[0:1], v[2:3]
	v_cvt_pk_bf16_f32 v2, v4, v5
	v_mad_i64_i32 v[4:5], s[26:27], v12, s34, v[112:113]
	v_lshl_add_u64 v[4:5], v[4:5], 0, s[88:89]
	v_lshl_add_u64 v[4:5], v[4:5], 0, s[28:29]
	v_cvt_pk_bf16_f32 v0, v8, v9
	v_cvt_pk_bf16_f32 v1, v10, v11
	v_cvt_pk_bf16_f32 v3, v6, v7
	v_lshl_add_u64 v[4:5], v[4:5], 0, v[208:209]
	s_mov_b32 s88, s44
	s_mov_b64 s[28:29], s[64:65]
	s_mov_b64 s[26:27], s[48:49]
	global_store_dwordx4 v[4:5], v[0:3], off
	s_cbranch_vccz .LBB0_27
	s_waitcnt vmcnt(0)
	s_cmpk_gt_u32 s30, 0xff
	s_mov_b32 s89, 0xc000
	s_mov_b64 s[34:35], 0
	s_cbranch_scc1 .LBB0_34
	s_barrier

; #define PG8_STAGE(bufoff, gbase, voff) do { _Pragma("unroll") for (int _i = 0; _i < 2; ++_i) \
;         __builtin_amdgcn_global_load_lds((const unsigned*)((const char*)(gbase) + (voff)[_i]), (LAS unsigned*)(lds + (bufoff) + ldsw + _i * 8192), 16, 0, 0); } while (0)
; #define PG8_LDA(dst, b, h) do { _Pragma("unroll") for (int m = 0; m < 4; ++m) _Pragma("unroll") for (int k = 0; k < 2; ++k) dst[m][k] = *(const LAS bf16x8*)(lds + PG8_SA(b, h) + aoff + m * 2048 + k * 1024); } while (0)
; #define PG8_LDB(dst, b, h) do { _Pragma("unroll") for (int n = 0; n < 2; ++n) _Pragma("unroll") for (int k = 0; k < 2; ++k) dst[n][k] = *(const LAS bf16x8*)(lds + PG8_SB(b, h) + boff + n * 2048 + k * 1024); } while (0)
; #define PG8_MMA(ai, bj, At, Bt) do { __builtin_amdgcn_s_setprio(1); _Pragma("unroll") for (int m = 0; m < 4; ++m) _Pragma("unroll") for (int n = 0; n < 2; ++n) _Pragma("unroll") for (int k = 0; k < 2; ++k) \
;         acc[ai][bj][m][n] = __builtin_amdgcn_mfma_f32_16x16x32_bf16(Bt[n][k], At[m][k], acc[ai][bj][m][n], 0, 0, 0); __builtin_amdgcn_s_setprio(0); } while (0)
; #define PG8_WAIT_V(n) asm volatile("s_waitcnt vmcnt(" #n ")" ::: "memory")
; #define PG8_WAIT_L(n) asm volatile("s_waitcnt lgkmcnt(" #n ")" ::: "memory")
; #define PG8_BAR __builtin_amdgcn_s_barrier()
; template <class Epi>
; __device__ __forceinline__ void gemm_phase(LAS unsigned char* lds, const Gemm g, const Epi& E) {
;     ...
;         for (int t = 0; t < nt; t += 2) {
;             const bool last = (t == nt - 2);
;             const char* a1 = cA + (size_t)(t + 1) * kstep;
;             const char* a2 = last ? nA : cA + (size_t)(t + 2) * kstep; const char* b2 = last ? nB : cB + (size_t)(t + 2) * kstep;
;             const char* a3 = a2 + kstep; const char* b3 = b2 + kstep;
;             PG8_LDB(B0, 0, 0); PG8_SCHED; PG8_LDA(At, 0, 0); PG8_STAGE(PG8_SA(1, 1), a1 + hstep, voffA);
;             PG8_WAIT_L(8); PG8_BAR; PG8_WAIT_L(0); PG8_MMA(0, 0, At, B0); PG8_BAR; PG8_SCHED;
;             PG8_LDB(B1, 0, 1); PG8_STAGE(PG8_SB(0, 0), b2, voffB);
;             PG8_BAR; PG8_WAIT_L(0); PG8_MMA(0, 1, At, B1); PG8_BAR;
;             PG8_LDA(At, 0, 1); PG8_STAGE(PG8_SA(0, 0), a2, voffA);
;             PG8_BAR; PG8_WAIT_L(0); PG8_MMA(1, 0, At, B0); PG8_BAR; PG8_SCHED;
;             PG8_STAGE(PG8_SB(0, 1), b2 + hstep, voffB);
;             PG8_WAIT_V(6); PG8_BAR; PG8_MMA(1, 1, At, B1); PG8_BAR;
.LBB0_120:
	s_add_u32 s28, s26, 0xfff80080
	s_addc_u32 s29, s27, -1
	s_add_i32 s34, 0, 0x10000
	v_add_u32_e32 v92, s34, v174
	ds_read_b128 v[72:75], v92
	ds_read_b128 v[76:79], v92 offset:1024
	ds_read_b128 v[84:87], v92 offset:2048
	ds_read_b128 v[92:95], v92 offset:3072
	s_cmp_eq_u32 vcc_lo, 28
	s_cselect_b32 s37, s38, s29
	s_cselect_b32 s36, s39, s28
	s_cselect_b32 s29, s43, s97
	s_cselect_b32 s28, s49, s65
	s_add_i32 m0, s68, 0xc000
	ds_read_b128 v[144:147], v175
	ds_read_b128 v[148:151], v175 offset:1024
	ds_read_b128 v[164:167], v175 offset:2048
	ds_read_b128 v[168:171], v175 offset:3072
	ds_read_b128 v[178:181], v175 offset:4096
	ds_read_b128 v[182:185], v175 offset:5120
	ds_read_b128 v[186:189], v175 offset:6144
	ds_read_b128 v[190:193], v175 offset:7168
	global_load_lds_dwordx4 v160, s[26:27]
	s_add_i32 m0, s68, 0xe000
	s_nop 0
	global_load_lds_dwordx4 v162, s[26:27]
	s_waitcnt lgkmcnt(8)
	s_setprio 1
	s_barrier
	s_waitcnt lgkmcnt(0)
	v_mfma_f32_16x16x32_bf16 v[140:143], v[72:75], v[144:147], v[140:143]
	v_mfma_f32_16x16x32_bf16 v[136:139], v[84:87], v[144:147], v[136:139]
	v_mfma_f32_16x16x32_bf16 v[124:127], v[72:75], v[164:167], v[124:127]
	v_mfma_f32_16x16x32_bf16 v[120:123], v[84:87], v[164:167], v[120:123]
	v_mfma_f32_16x16x32_bf16 v[108:111], v[72:75], v[178:181], v[108:111]
	v_mfma_f32_16x16x32_bf16 v[104:107], v[84:87], v[178:181], v[104:107]
	v_mfma_f32_16x16x32_bf16 v[88:91], v[72:75], v[186:189], v[88:91]
	v_mfma_f32_16x16x32_bf16 v[80:83], v[84:87], v[186:189], v[80:83]
	v_mfma_f32_16x16x32_bf16 v[140:143], v[76:79], v[148:151], v[140:143]
	v_mfma_f32_16x16x32_bf16 v[136:139], v[92:95], v[148:151], v[136:139]
	v_mfma_f32_16x16x32_bf16 v[124:127], v[76:79], v[168:171], v[124:127]
	v_mfma_f32_16x16x32_bf16 v[120:123], v[92:95], v[168:171], v[120:123]
	v_mfma_f32_16x16x32_bf16 v[108:111], v[76:79], v[182:185], v[108:111]
	v_mfma_f32_16x16x32_bf16 v[104:107], v[92:95], v[182:185], v[104:107]
	v_mfma_f32_16x16x32_bf16 v[88:91], v[76:79], v[190:193], v[88:91]
	v_mfma_f32_16x16x32_bf16 v[80:83], v[92:95], v[190:193], v[80:83]
	s_barrier
	s_setprio 0
	s_add_i32 s46, 0, 0x14000
	v_add_u32_e32 v172, s46, v174
	s_add_i32 s34, s34, s31
	ds_read_b128 v[194:197], v172
	ds_read_b128 v[198:201], v172 offset:1024
	ds_read_b128 v[202:205], v172 offset:2048
	ds_read_b128 v[228:231], v172 offset:3072
	s_mov_b32 m0, s34
	s_nop 0
	global_load_lds_dwordx4 v208, s[28:29]
	s_add_i32 m0, s34, 0x2000
	s_nop 0
	global_load_lds_dwordx4 v156, s[28:29]
	s_setprio 1
	s_barrier
	s_waitcnt lgkmcnt(0)
	v_mfma_f32_16x16x32_bf16 v[132:135], v[194:197], v[144:147], v[132:135]
	v_mfma_f32_16x16x32_bf16 v[128:131], v[202:205], v[144:147], v[128:131]
	v_mfma_f32_16x16x32_bf16 v[116:119], v[194:197], v[164:167], v[116:119]
	v_mfma_f32_16x16x32_bf16 v[112:115], v[202:205], v[164:167], v[112:115]
	v_mfma_f32_16x16x32_bf16 v[100:103], v[194:197], v[178:181], v[100:103]
	v_mfma_f32_16x16x32_bf16 v[96:99], v[202:205], v[178:181], v[96:99]
	v_mfma_f32_16x16x32_bf16 v[68:71], v[194:197], v[186:189], v[68:71]
	v_mfma_f32_16x16x32_bf16 v[64:67], v[202:205], v[186:189], v[64:67]
	v_mfma_f32_16x16x32_bf16 v[132:135], v[198:201], v[148:151], v[132:135]
	v_mfma_f32_16x16x32_bf16 v[128:131], v[228:231], v[148:151], v[128:131]
	v_mfma_f32_16x16x32_bf16 v[116:119], v[198:201], v[168:171], v[116:119]
	v_mfma_f32_16x16x32_bf16 v[112:115], v[228:231], v[168:171], v[112:115]
	v_mfma_f32_16x16x32_bf16 v[100:103], v[198:201], v[182:185], v[100:103]
	v_mfma_f32_16x16x32_bf16 v[96:99], v[228:231], v[182:185], v[96:99]
	v_mfma_f32_16x16x32_bf16 v[68:71], v[198:201], v[190:193], v[68:71]
	v_mfma_f32_16x16x32_bf16 v[64:67], v[228:231], v[190:193], v[64:67]
	s_barrier
	s_setprio 0
	s_mov_b32 m0, s68
	ds_read_b128 v[144:147], v175 offset:16384
	ds_read_b128 v[148:151], v175 offset:17408
	ds_read_b128 v[164:167], v175 offset:18432
	ds_read_b128 v[168:171], v175 offset:19456
	ds_read_b128 v[178:181], v175 offset:20480
	ds_read_b128 v[182:185], v175 offset:21504
	ds_read_b128 v[186:189], v175 offset:22528
	ds_read_b128 v[190:193], v175 offset:23552
	global_load_lds_dwordx4 v152, s[36:37]
	s_mov_b32 m0, s69
	s_nop 0
	global_load_lds_dwordx4 v154, s[36:37]
	s_setprio 1
	s_barrier
	s_waitcnt lgkmcnt(0)
	v_mfma_f32_16x16x32_bf16 v[60:63], v[72:75], v[144:147], v[60:63]
	v_mfma_f32_16x16x32_bf16 v[56:59], v[84:87], v[144:147], v[56:59]
	v_mfma_f32_16x16x32_bf16 v[44:47], v[72:75], v[164:167], v[44:47]
	v_mfma_f32_16x16x32_bf16 v[40:43], v[84:87], v[164:167], v[40:43]
	v_mfma_f32_16x16x32_bf16 v[28:31], v[72:75], v[178:181], v[28:31]
	v_mfma_f32_16x16x32_bf16 v[24:27], v[84:87], v[178:181], v[24:27]
	v_mfma_f32_16x16x32_bf16 v[12:15], v[72:75], v[186:189], v[12:15]
	v_mfma_f32_16x16x32_bf16 v[8:11], v[84:87], v[186:189], v[8:11]
	v_mfma_f32_16x16x32_bf16 v[60:63], v[76:79], v[148:151], v[60:63]
	v_mfma_f32_16x16x32_bf16 v[56:59], v[92:95], v[148:151], v[56:59]
	v_mfma_f32_16x16x32_bf16 v[44:47], v[76:79], v[168:171], v[44:47]
	v_mfma_f32_16x16x32_bf16 v[40:43], v[92:95], v[168:171], v[40:43]
	v_mfma_f32_16x16x32_bf16 v[28:31], v[76:79], v[182:185], v[28:31]
	v_mfma_f32_16x16x32_bf16 v[24:27], v[92:95], v[182:185], v[24:27]
	v_mfma_f32_16x16x32_bf16 v[12:15], v[76:79], v[190:193], v[12:15]
	v_mfma_f32_16x16x32_bf16 v[8:11], v[92:95], v[190:193], v[8:11]
	s_barrier
	s_setprio 0
	s_add_u32 s34, s28, 0x80000
	s_addc_u32 s35, s29, 0
	s_add_i32 s46, s46, s31
	s_mov_b32 m0, s46
	s_nop 0
	global_load_lds_dwordx4 v208, s[34:35]
	s_add_i32 m0, s46, 0x2000
	s_nop 0
	global_load_lds_dwordx4 v156, s[34:35]
	s_waitcnt vmcnt(6)
	s_setprio 1
	s_barrier
; #define PG8_STAGE(bufoff, gbase, voff) do { _Pragma("unroll") for (int _i = 0; _i < 2; ++_i) \
;         __builtin_amdgcn_global_load_lds((const unsigned*)((const char*)(gbase) + (voff)[_i]), (LAS unsigned*)(lds + (bufoff) + ldsw + _i * 8192), 16, 0, 0); } while (0)
; #define PG8_LDA(dst, b, h) do { _Pragma("unroll") for (int m = 0; m < 4; ++m) _Pragma("unroll") for (int k = 0; k < 2; ++k) dst[m][k] = *(const LAS bf16x8*)(lds + PG8_SA(b, h) + aoff + m * 2048 + k * 1024); } while (0)
; #define PG8_LDB(dst, b, h) do { _Pragma("unroll") for (int n = 0; n < 2; ++n) _Pragma("unroll") for (int k = 0; k < 2; ++k) dst[n][k] = *(const LAS bf16x8*)(lds + PG8_SB(b, h) + boff + n * 2048 + k * 1024); } while (0)
; #define PG8_MMA(ai, bj, At, Bt) do { __builtin_amdgcn_s_setprio(1); _Pragma("unroll") for (int m = 0; m < 4; ++m) _Pragma("unroll") for (int n = 0; n < 2; ++n) _Pragma("unroll") for (int k = 0; k < 2; ++k) \
;         acc[ai][bj][m][n] = __builtin_amdgcn_mfma_f32_16x16x32_bf16(Bt[n][k], At[m][k], acc[ai][bj][m][n], 0, 0, 0); __builtin_amdgcn_s_setprio(0); } while (0)
; #define PG8_WAIT_V(n) asm volatile("s_waitcnt vmcnt(" #n ")" ::: "memory")
; #define PG8_WAIT_L(n) asm volatile("s_waitcnt lgkmcnt(" #n ")" ::: "memory")
; #define PG8_BAR __builtin_amdgcn_s_barrier()
; #define PG8_SCHED __builtin_amdgcn_sched_barrier(0)
; template <class Epi>
; __device__ __forceinline__ void gemm_phase(LAS unsigned char* lds, const Gemm g, const Epi& E) {
;     ...
;             PG8_WAIT_V(6); PG8_BAR; PG8_MMA(1, 1, At, B1); PG8_BAR;
;             PG8_LDB(B0, 1, 0); PG8_SCHED; PG8_LDA(At, 1, 0); PG8_STAGE(PG8_SA(0, 1), a2 + hstep, voffA);
;             PG8_WAIT_L(8); PG8_BAR; PG8_WAIT_L(0); PG8_MMA(0, 0, At, B0); PG8_BAR; PG8_SCHED;
;             PG8_LDB(B1, 1, 1); PG8_STAGE(PG8_SB(1, 0), b3, voffB);
;             PG8_BAR; PG8_WAIT_L(0); PG8_MMA(0, 1, At, B1); PG8_BAR;
;             PG8_LDA(At, 1, 1); PG8_STAGE(PG8_SA(1, 0), a3, voffA);
;             PG8_BAR; PG8_WAIT_L(0); PG8_MMA(1, 0, At, B0); PG8_BAR; PG8_SCHED;
;             PG8_STAGE(PG8_SB(1, 1), b3 + hstep, voffB);
	v_mfma_f32_16x16x32_bf16 v[52:55], v[194:197], v[144:147], v[52:55]
	v_mfma_f32_16x16x32_bf16 v[48:51], v[202:205], v[144:147], v[48:51]
	v_mfma_f32_16x16x32_bf16 v[36:39], v[194:197], v[164:167], v[36:39]
	v_mfma_f32_16x16x32_bf16 v[32:35], v[202:205], v[164:167], v[32:35]
	v_mfma_f32_16x16x32_bf16 v[20:23], v[194:197], v[178:181], v[20:23]
	v_mfma_f32_16x16x32_bf16 v[16:19], v[202:205], v[178:181], v[16:19]
	v_mfma_f32_16x16x32_bf16 v[4:7], v[194:197], v[186:189], v[4:7]
	v_mfma_f32_16x16x32_bf16 v[0:3], v[202:205], v[186:189], v[0:3]
	v_mfma_f32_16x16x32_bf16 v[52:55], v[198:201], v[148:151], v[52:55]
	v_mfma_f32_16x16x32_bf16 v[48:51], v[228:231], v[148:151], v[48:51]
	v_mfma_f32_16x16x32_bf16 v[36:39], v[198:201], v[168:171], v[36:39]
	v_mfma_f32_16x16x32_bf16 v[32:35], v[228:231], v[168:171], v[32:35]
	v_mfma_f32_16x16x32_bf16 v[20:23], v[198:201], v[182:185], v[20:23]
	v_mfma_f32_16x16x32_bf16 v[16:19], v[228:231], v[182:185], v[16:19]
	v_mfma_f32_16x16x32_bf16 v[4:7], v[198:201], v[190:193], v[4:7]
	v_mfma_f32_16x16x32_bf16 v[0:3], v[228:231], v[190:193], v[0:3]
	s_barrier
	s_setprio 0
	s_add_i32 s46, 0, 0x18000
	v_add_u32_e32 v92, s46, v174
	ds_read_b128 v[72:75], v92
	ds_read_b128 v[76:79], v92 offset:1024
	ds_read_b128 v[84:87], v92 offset:2048
	ds_read_b128 v[92:95], v92 offset:3072
	s_add_u32 s34, s36, 0x80000
	s_addc_u32 s35, s37, 0
	s_mov_b32 m0, s70
	ds_read_b128 v[144:147], v175 offset:32768
	ds_read_b128 v[148:151], v175 offset:33792
	ds_read_b128 v[164:167], v175 offset:34816
	ds_read_b128 v[168:171], v175 offset:35840
	ds_read_b128 v[178:181], v175 offset:36864
	ds_read_b128 v[182:185], v175 offset:37888
	ds_read_b128 v[186:189], v175 offset:38912
	ds_read_b128 v[190:193], v175 offset:39936
	global_load_lds_dwordx4 v152, s[34:35]
	s_mov_b32 m0, s71
	s_nop 0
	global_load_lds_dwordx4 v154, s[34:35]
	s_waitcnt lgkmcnt(8)
	s_setprio 1
	s_barrier
	s_waitcnt lgkmcnt(0)
	v_mfma_f32_16x16x32_bf16 v[140:143], v[72:75], v[144:147], v[140:143]
	v_mfma_f32_16x16x32_bf16 v[136:139], v[84:87], v[144:147], v[136:139]
	v_mfma_f32_16x16x32_bf16 v[124:127], v[72:75], v[164:167], v[124:127]
	v_mfma_f32_16x16x32_bf16 v[120:123], v[84:87], v[164:167], v[120:123]
	v_mfma_f32_16x16x32_bf16 v[108:111], v[72:75], v[178:181], v[108:111]
	v_mfma_f32_16x16x32_bf16 v[104:107], v[84:87], v[178:181], v[104:107]
	v_mfma_f32_16x16x32_bf16 v[88:91], v[72:75], v[186:189], v[88:91]
	v_mfma_f32_16x16x32_bf16 v[80:83], v[84:87], v[186:189], v[80:83]
	v_mfma_f32_16x16x32_bf16 v[140:143], v[76:79], v[148:151], v[140:143]
	v_mfma_f32_16x16x32_bf16 v[136:139], v[92:95], v[148:151], v[136:139]
	v_mfma_f32_16x16x32_bf16 v[124:127], v[76:79], v[168:171], v[124:127]
	v_mfma_f32_16x16x32_bf16 v[120:123], v[92:95], v[168:171], v[120:123]
	v_mfma_f32_16x16x32_bf16 v[108:111], v[76:79], v[182:185], v[108:111]
	v_mfma_f32_16x16x32_bf16 v[104:107], v[92:95], v[182:185], v[104:107]
	v_mfma_f32_16x16x32_bf16 v[88:91], v[76:79], v[190:193], v[88:91]
	v_mfma_f32_16x16x32_bf16 v[80:83], v[92:95], v[190:193], v[80:83]
	s_barrier
	s_setprio 0
	s_add_i32 s34, 0, 0x1c000
	s_add_i32 s35, s46, s31
	v_add_u32_e32 v177, s34, v174
	s_mov_b32 m0, s35
	ds_read_b128 v[194:197], v177
	ds_read_b128 v[198:201], v177 offset:1024
	ds_read_b128 v[202:205], v177 offset:2048
	ds_read_b128 v[228:231], v177 offset:3072
	s_add_u32 s98, s28, 0x80
	s_addc_u32 s99, s29, 0
	global_load_lds_dwordx4 v208, s[98:99]
	s_add_i32 m0, s35, 0x2000
	s_add_u32 s100, s28, 0x80
	s_addc_u32 s101, s29, 0
	global_load_lds_dwordx4 v156, s[100:101]
	s_setprio 1
	s_barrier
	s_waitcnt lgkmcnt(0)
	v_mfma_f32_16x16x32_bf16 v[132:135], v[194:197], v[144:147], v[132:135]
	v_mfma_f32_16x16x32_bf16 v[128:131], v[202:205], v[144:147], v[128:131]
	v_mfma_f32_16x16x32_bf16 v[116:119], v[194:197], v[164:167], v[116:119]
	v_mfma_f32_16x16x32_bf16 v[112:115], v[202:205], v[164:167], v[112:115]
	v_mfma_f32_16x16x32_bf16 v[100:103], v[194:197], v[178:181], v[100:103]
	v_mfma_f32_16x16x32_bf16 v[96:99], v[202:205], v[178:181], v[96:99]
	v_mfma_f32_16x16x32_bf16 v[68:71], v[194:197], v[186:189], v[68:71]
	v_mfma_f32_16x16x32_bf16 v[64:67], v[202:205], v[186:189], v[64:67]
	v_mfma_f32_16x16x32_bf16 v[132:135], v[198:201], v[148:151], v[132:135]
	v_mfma_f32_16x16x32_bf16 v[128:131], v[228:231], v[148:151], v[128:131]
	v_mfma_f32_16x16x32_bf16 v[116:119], v[198:201], v[168:171], v[116:119]
	v_mfma_f32_16x16x32_bf16 v[112:115], v[228:231], v[168:171], v[112:115]
	v_mfma_f32_16x16x32_bf16 v[100:103], v[198:201], v[182:185], v[100:103]
	v_mfma_f32_16x16x32_bf16 v[96:99], v[228:231], v[182:185], v[96:99]
	v_mfma_f32_16x16x32_bf16 v[68:71], v[198:201], v[190:193], v[68:71]
	v_mfma_f32_16x16x32_bf16 v[64:67], v[228:231], v[190:193], v[64:67]
	s_barrier
	s_setprio 0
	s_mov_b32 m0, s78
	ds_read_b128 v[144:147], v175 offset:49152
	ds_read_b128 v[148:151], v175 offset:50176
	ds_read_b128 v[164:167], v175 offset:51200
	ds_read_b128 v[168:171], v175 offset:52224
	ds_read_b128 v[178:181], v175 offset:53248
	ds_read_b128 v[182:185], v175 offset:54272
	ds_read_b128 v[186:189], v175 offset:55296
	ds_read_b128 v[190:193], v175 offset:56320
	s_add_u32 s98, s36, 0x80
	s_addc_u32 s99, s37, 0
	global_load_lds_dwordx4 v152, s[98:99]
	s_mov_b32 m0, s79
	s_add_u32 s100, s36, 0x80
	s_addc_u32 s101, s37, 0
	global_load_lds_dwordx4 v154, s[100:101]
	s_setprio 1
	s_barrier
; __device__ __forceinline__ float bflo(unsigned w) { return __uint_as_float(w << 16); }
; __device__ __forceinline__ float bfhi(unsigned w) { return __uint_as_float(w & 0xffff0000u); }
; __device__ __forceinline__ u32x4 pack8u(f32x4 a, f32x4 b) { u32x4 w = {cvt_pk_bf16(a[0], a[1]), cvt_pk_bf16(a[2], a[3]), cvt_pk_bf16(b[0], b[1]), cvt_pk_bf16(b[2], b[3])}; return w; }
; #define PG8_LDA(dst, b, h) do { _Pragma("unroll") for (int m = 0; m < 4; ++m) _Pragma("unroll") for (int k = 0; k < 2; ++k) dst[m][k] = *(const LAS bf16x8*)(lds + PG8_SA(b, h) + aoff + m * 2048 + k * 1024); } while (0)
; template <class Epi>
; __device__ __forceinline__ void gemm_phase(LAS unsigned char* lds, const Gemm g, const Epi& E) {
;     ...
;             PG8_LDB(B1, 1, 1); PG8_STAGE(PG8_SB(1, 0), b3, voffB);
;             PG8_BAR; PG8_WAIT_L(0); PG8_MMA(0, 1, At, B1); PG8_BAR;
;             PG8_LDA(At, 1, 1); PG8_STAGE(PG8_SA(1, 0), a3, voffA);
;             PG8_BAR; PG8_WAIT_L(0); PG8_MMA(1, 0, At, B0); PG8_BAR; PG8_SCHED;
;             PG8_STAGE(PG8_SB(1, 1), b3 + hstep, voffB);
;             PG8_WAIT_V(6); PG8_BAR; PG8_MMA(1, 1, At, B1); PG8_BAR;
;     __device__ __forceinline__ void operator()(const AccT& acc, const Unit& u, int wr, int wc, int fr, int fq) const {
;         const int b = (u.pm * 256) / SEQ;
;         f32x4 gt[2][2];
; #pragma unroll
;         for (int bj = 0; bj < 2; ++bj)
; #pragma unroll
;             for (int n = 0; n < 2; ++n) gt[bj][n] = *(const f32x4*)(GT + (size_t)b * 6 * D + u.pn * 256 + bj * 128 + wc * 32 + fq * 8 + 4 * n);
; #pragma unroll
;         for (int ai = 0; ai < 2; ++ai)
; #pragma unroll
;             for (int m = 0; m < 4; ++m) {
;                 const int row = u.pm * 256 + ai * 128 + wr * 64 + m * 16 + fr;
; #pragma unroll
;                 for (int bj = 0; bj < 2; ++bj) {
;                     const size_t off = (size_t)row * D + u.pn * 256 + bj * 128 + wc * 32 + fq * 8;
;                     f32x4 x0, x1;
;                     if (XINF) { x0 = *(const f32x4*)(XINF + off); x1 = *(const f32x4*)(XINF + off + 4); }
;                     else { const u32x4 w = *(const u32x4*)(XIN16 + off); x0 = (f32x4){bflo(w[0]), bfhi(w[0]), bflo(w[1]), bfhi(w[1])}; x1 = (f32x4){bflo(w[2]), bfhi(w[2]), bflo(w[3]), bfhi(w[3])}; }
;                     *(u32x4*)(XOUT + off) = pack8u(x0 + gt[bj][0] * acc[ai][bj][m][0], x1 + gt[bj][1] * acc[ai][bj][m][1]);
	s_waitcnt lgkmcnt(0)
	v_mfma_f32_16x16x32_bf16 v[60:63], v[72:75], v[144:147], v[60:63]
	v_mfma_f32_16x16x32_bf16 v[56:59], v[84:87], v[144:147], v[56:59]
	v_mfma_f32_16x16x32_bf16 v[44:47], v[72:75], v[164:167], v[44:47]
	v_mfma_f32_16x16x32_bf16 v[40:43], v[84:87], v[164:167], v[40:43]
	v_mfma_f32_16x16x32_bf16 v[28:31], v[72:75], v[178:181], v[28:31]
	v_mfma_f32_16x16x32_bf16 v[24:27], v[84:87], v[178:181], v[24:27]
	v_mfma_f32_16x16x32_bf16 v[12:15], v[72:75], v[186:189], v[12:15]
	v_mfma_f32_16x16x32_bf16 v[8:11], v[84:87], v[186:189], v[8:11]
	v_mfma_f32_16x16x32_bf16 v[60:63], v[76:79], v[148:151], v[60:63]
	v_mfma_f32_16x16x32_bf16 v[56:59], v[92:95], v[148:151], v[56:59]
	v_mfma_f32_16x16x32_bf16 v[44:47], v[76:79], v[168:171], v[44:47]
	v_mfma_f32_16x16x32_bf16 v[40:43], v[92:95], v[168:171], v[40:43]
	v_mfma_f32_16x16x32_bf16 v[28:31], v[76:79], v[182:185], v[28:31]
	v_mfma_f32_16x16x32_bf16 v[24:27], v[92:95], v[182:185], v[24:27]
	v_mfma_f32_16x16x32_bf16 v[12:15], v[76:79], v[190:193], v[12:15]
	v_mfma_f32_16x16x32_bf16 v[8:11], v[92:95], v[190:193], v[8:11]
	s_barrier
	s_setprio 0
	s_add_u32 s28, s28, 0x80080
	s_addc_u32 s29, s29, 0
	s_add_i32 s34, s34, s31
	s_mov_b32 m0, s34
	s_nop 0
	global_load_lds_dwordx4 v208, s[28:29]
	s_add_i32 m0, s34, 0x2000
	s_nop 0
	global_load_lds_dwordx4 v156, s[28:29]
	s_waitcnt vmcnt(6)
	s_setprio 1
	s_barrier
	v_mfma_f32_16x16x32_bf16 v[52:55], v[194:197], v[144:147], v[52:55]
	v_mfma_f32_16x16x32_bf16 v[48:51], v[202:205], v[144:147], v[48:51]
	v_mfma_f32_16x16x32_bf16 v[36:39], v[194:197], v[164:167], v[36:39]
	v_mfma_f32_16x16x32_bf16 v[32:35], v[202:205], v[164:167], v[32:35]
	v_mfma_f32_16x16x32_bf16 v[20:23], v[194:197], v[178:181], v[20:23]
	v_mfma_f32_16x16x32_bf16 v[16:19], v[202:205], v[178:181], v[16:19]
	v_mfma_f32_16x16x32_bf16 v[4:7], v[194:197], v[186:189], v[4:7]
	v_mfma_f32_16x16x32_bf16 v[0:3], v[202:205], v[186:189], v[0:3]
	v_mfma_f32_16x16x32_bf16 v[52:55], v[198:201], v[148:151], v[52:55]
	v_mfma_f32_16x16x32_bf16 v[48:51], v[228:231], v[148:151], v[48:51]
	v_mfma_f32_16x16x32_bf16 v[36:39], v[198:201], v[168:171], v[36:39]
	v_mfma_f32_16x16x32_bf16 v[32:35], v[228:231], v[168:171], v[32:35]
	v_mfma_f32_16x16x32_bf16 v[20:23], v[198:201], v[182:185], v[20:23]
	v_mfma_f32_16x16x32_bf16 v[16:19], v[228:231], v[182:185], v[16:19]
	v_mfma_f32_16x16x32_bf16 v[4:7], v[198:201], v[190:193], v[4:7]
	v_mfma_f32_16x16x32_bf16 v[0:3], v[228:231], v[190:193], v[0:3]
	s_barrier
	s_setprio 0
	s_add_i32 vcc_lo, vcc_lo, 2
	s_add_u32 s26, s26, 0x100
	s_addc_u32 s27, s27, 0
	s_add_u32 s65, s65, 0x100
	s_addc_u32 s97, s97, 0
	s_cmp_gt_u32 vcc_lo, 29
	s_cbranch_scc0 .LBB0_120
	s_ashr_i32 s26, s42, 31
	s_lshr_b32 s26, s26, 29
	s_add_i32 s26, s42, s26
	s_ashr_i32 s26, s26, 3
	s_mul_i32 s26, s26, 6
	s_ashr_i32 s27, s26, 31
	s_lshl_b64 s[26:27], s[26:27], 13
	s_add_u32 s34, s74, s26
	s_addc_u32 s35, s76, s27
	s_lshl_b32 s26, s96, 8
	s_ashr_i32 s27, s26, 31
	s_lshl_b64 s[28:29], s[26:27], 2
	s_add_u32 s28, s34, s28
	s_addc_u32 s29, s35, s29
	s_add_u32 s28, s28, s83
	s_addc_u32 s29, s29, 0
	global_load_dwordx4 v[84:87], v176, s[28:29] offset:16
	global_load_dwordx4 v[92:95], v176, s[28:29]
	global_load_dwordx4 v[72:75], v176, s[28:29] offset:528
	global_load_dwordx4 v[76:79], v176, s[28:29] offset:512
	v_readlane_b32 s34, v255, 22
	v_readlane_b32 s35, v255, 23
	v_lshl_add_u32 v166, s42, 8, v159
	v_or_b32_e32 v167, s26, v158
	v_lshlrev_b32_e32 v164, 2, v167
	v_lshl_add_u32 v164, v166, 13, v164
	v_lshlrev_b32_e32 v165, 1, v167
	v_lshl_add_u32 v165, v166, 12, v165
	s_and_b64 vcc, exec, s[44:45]
	s_cbranch_vccnz .Lepr1_f32
	v_add_u32_e32 v166, 0x0, v165
	global_load_dwordx4 v[168:171], v166, s[34:35] offset:0
	v_add_u32_e32 v166, 0x0, v165
	global_load_dwordx4 v[178:181], v166, s[34:35] offset:256
	v_add_u32_e32 v166, 0x10000, v165
	global_load_dwordx4 v[182:185], v166, s[34:35] offset:0
	v_add_u32_e32 v166, 0x10000, v165
	global_load_dwordx4 v[186:189], v166, s[34:35] offset:256
	v_add_u32_e32 v166, 0x20000, v165
	global_load_dwordx4 v[190:193], v166, s[34:35] offset:0
	v_add_u32_e32 v166, 0x20000, v165
	global_load_dwordx4 v[194:197], v166, s[34:35] offset:256
	v_add_u32_e32 v166, 0x30000, v165
	global_load_dwordx4 v[198:201], v166, s[34:35] offset:0
	v_add_u32_e32 v166, 0x30000, v165
	global_load_dwordx4 v[202:205], v166, s[34:35] offset:256
	v_add_u32_e32 v166, 0x80000, v165
	global_load_dwordx4 v[228:231], v166, s[34:35] offset:0
	s_waitcnt vmcnt(8)
	v_lshlrev_b32_e32 v144, 16, v168
	v_and_b32_e32 v145, 0xffff0000, v168
	v_lshlrev_b32_e32 v146, 16, v169
	v_and_b32_e32 v147, 0xffff0000, v169
	v_lshlrev_b32_e32 v148, 16, v170
	v_and_b32_e32 v149, 0xffff0000, v170
	v_lshlrev_b32_e32 v150, 16, v171
	v_and_b32_e32 v151, 0xffff0000, v171
	v_pk_fma_f32 v[140:141], v[140:141], v[92:93], v[144:145]
	v_pk_fma_f32 v[142:143], v[142:143], v[94:95], v[146:147]
	v_pk_fma_f32 v[136:137], v[136:137], v[84:85], v[148:149]
	v_pk_fma_f32 v[138:139], v[138:139], v[86:87], v[150:151]
	v_cvt_pk_bf16_f32 v140, v140, v141
	v_cvt_pk_bf16_f32 v141, v142, v143
	v_cvt_pk_bf16_f32 v142, v136, v137
	v_cvt_pk_bf16_f32 v143, v138, v139
	v_add_u32_e32 v167, 0x0, v165
	global_store_dwordx4 v167, v[140:143], s[34:35] offset:0
	v_add_u32_e32 v166, 0x80000, v165
	global_load_dwordx4 v[168:171], v166, s[34:35] offset:256
	v_add_u32_e32 v166, 0x90000, v165
	global_load_dwordx4 v[136:139], v166, s[34:35] offset:0
	s_waitcnt vmcnt(10)
; __device__ __forceinline__ float bflo(unsigned w) { return __uint_as_float(w << 16); }
; __device__ __forceinline__ float bfhi(unsigned w) { return __uint_as_float(w & 0xffff0000u); }
; __device__ __forceinline__ u32x4 pack8u(f32x4 a, f32x4 b) { u32x4 w = {cvt_pk_bf16(a[0], a[1]), cvt_pk_bf16(a[2], a[3]), cvt_pk_bf16(b[0], b[1]), cvt_pk_bf16(b[2], b[3])}; return w; }
;     __device__ __forceinline__ void operator()(const AccT& acc, const Unit& u, int wr, int wc, int fr, int fq) const {
;     ...
;                 for (int bj = 0; bj < 2; ++bj) {
;                     const size_t off = (size_t)row * D + u.pn * 256 + bj * 128 + wc * 32 + fq * 8;
;                     f32x4 x0, x1;
;                     if (XINF) { x0 = *(const f32x4*)(XINF + off); x1 = *(const f32x4*)(XINF + off + 4); }
;                     else { const u32x4 w = *(const u32x4*)(XIN16 + off); x0 = (f32x4){bflo(w[0]), bfhi(w[0]), bflo(w[1]), bfhi(w[1])}; x1 = (f32x4){bflo(w[2]), bfhi(w[2]), bflo(w[3]), bfhi(w[3])}; }
;                     *(u32x4*)(XOUT + off) = pack8u(x0 + gt[bj][0] * acc[ai][bj][m][0], x1 + gt[bj][1] * acc[ai][bj][m][1]);
	v_lshlrev_b32_e32 v144, 16, v178
	v_and_b32_e32 v145, 0xffff0000, v178
	v_lshlrev_b32_e32 v146, 16, v179
	v_and_b32_e32 v147, 0xffff0000, v179
	v_lshlrev_b32_e32 v148, 16, v180
	v_and_b32_e32 v149, 0xffff0000, v180
	v_lshlrev_b32_e32 v150, 16, v181
	v_and_b32_e32 v151, 0xffff0000, v181
	v_pk_fma_f32 v[132:133], v[132:133], v[76:77], v[144:145]
	v_pk_fma_f32 v[134:135], v[134:135], v[78:79], v[146:147]
	v_pk_fma_f32 v[128:129], v[128:129], v[72:73], v[148:149]
	v_pk_fma_f32 v[130:131], v[130:131], v[74:75], v[150:151]
	v_cvt_pk_bf16_f32 v132, v132, v133
	v_cvt_pk_bf16_f32 v133, v134, v135
	v_cvt_pk_bf16_f32 v134, v128, v129
	v_cvt_pk_bf16_f32 v135, v130, v131
	v_add_u32_e32 v167, 0x0, v165
	global_store_dwordx4 v167, v[132:135], s[34:35] offset:256
	v_add_u32_e32 v166, 0x90000, v165
	global_load_dwordx4 v[178:181], v166, s[34:35] offset:256
	v_add_u32_e32 v166, 0xa0000, v165
	global_load_dwordx4 v[128:131], v166, s[34:35] offset:0
	s_waitcnt vmcnt(12)
	v_lshlrev_b32_e32 v144, 16, v182
	v_and_b32_e32 v145, 0xffff0000, v182
	v_lshlrev_b32_e32 v146, 16, v183
	v_and_b32_e32 v147, 0xffff0000, v183
	v_lshlrev_b32_e32 v148, 16, v184
	v_and_b32_e32 v149, 0xffff0000, v184
	v_lshlrev_b32_e32 v150, 16, v185
	v_and_b32_e32 v151, 0xffff0000, v185
	v_pk_fma_f32 v[124:125], v[124:125], v[92:93], v[144:145]
	v_pk_fma_f32 v[126:127], v[126:127], v[94:95], v[146:147]
	v_pk_fma_f32 v[120:121], v[120:121], v[84:85], v[148:149]
	v_pk_fma_f32 v[122:123], v[122:123], v[86:87], v[150:151]
	v_cvt_pk_bf16_f32 v124, v124, v125
	v_cvt_pk_bf16_f32 v125, v126, v127
	v_cvt_pk_bf16_f32 v126, v120, v121
	v_cvt_pk_bf16_f32 v127, v122, v123
	v_add_u32_e32 v167, 0x10000, v165
	global_store_dwordx4 v167, v[124:127], s[34:35] offset:0
	v_add_u32_e32 v166, 0xa0000, v165
	global_load_dwordx4 v[182:185], v166, s[34:35] offset:256
	v_add_u32_e32 v166, 0xb0000, v165
	global_load_dwordx4 v[120:123], v166, s[34:35] offset:0
	s_waitcnt vmcnt(14)
	v_lshlrev_b32_e32 v144, 16, v186
	v_and_b32_e32 v145, 0xffff0000, v186
	v_lshlrev_b32_e32 v146, 16, v187
	v_and_b32_e32 v147, 0xffff0000, v187
	v_lshlrev_b32_e32 v148, 16, v188
	v_and_b32_e32 v149, 0xffff0000, v188
	v_lshlrev_b32_e32 v150, 16, v189
	v_and_b32_e32 v151, 0xffff0000, v189
	v_pk_fma_f32 v[116:117], v[116:117], v[76:77], v[144:145]
	v_pk_fma_f32 v[118:119], v[118:119], v[78:79], v[146:147]
	v_pk_fma_f32 v[112:113], v[112:113], v[72:73], v[148:149]
	v_pk_fma_f32 v[114:115], v[114:115], v[74:75], v[150:151]
	v_cvt_pk_bf16_f32 v116, v116, v117
	v_cvt_pk_bf16_f32 v117, v118, v119
	v_cvt_pk_bf16_f32 v118, v112, v113
	v_cvt_pk_bf16_f32 v119, v114, v115
	v_add_u32_e32 v167, 0x10000, v165
	global_store_dwordx4 v167, v[116:119], s[34:35] offset:256
	v_add_u32_e32 v166, 0xb0000, v165
	global_load_dwordx4 v[186:189], v166, s[34:35] offset:256
	s_waitcnt vmcnt(15)
	v_lshlrev_b32_e32 v144, 16, v190
	v_and_b32_e32 v145, 0xffff0000, v190
	v_lshlrev_b32_e32 v146, 16, v191
	v_and_b32_e32 v147, 0xffff0000, v191
	v_lshlrev_b32_e32 v148, 16, v192
	v_and_b32_e32 v149, 0xffff0000, v192
	v_lshlrev_b32_e32 v150, 16, v193
	v_and_b32_e32 v151, 0xffff0000, v193
	v_pk_fma_f32 v[108:109], v[108:109], v[92:93], v[144:145]
	v_pk_fma_f32 v[110:111], v[110:111], v[94:95], v[146:147]
	v_pk_fma_f32 v[104:105], v[104:105], v[84:85], v[148:149]
	v_pk_fma_f32 v[106:107], v[106:107], v[86:87], v[150:151]
	v_cvt_pk_bf16_f32 v108, v108, v109
	v_cvt_pk_bf16_f32 v109, v110, v111
	v_cvt_pk_bf16_f32 v110, v104, v105
	v_cvt_pk_bf16_f32 v111, v106, v107
	v_add_u32_e32 v167, 0x20000, v165
	global_store_dwordx4 v167, v[108:111], s[34:35] offset:0
	s_waitcnt vmcnt(15)
	v_lshlrev_b32_e32 v144, 16, v194
	v_and_b32_e32 v145, 0xffff0000, v194
	v_lshlrev_b32_e32 v146, 16, v195
	v_and_b32_e32 v147, 0xffff0000, v195
	v_lshlrev_b32_e32 v148, 16, v196
	v_and_b32_e32 v149, 0xffff0000, v196
	v_lshlrev_b32_e32 v150, 16, v197
	v_and_b32_e32 v151, 0xffff0000, v197
	v_pk_fma_f32 v[100:101], v[100:101], v[76:77], v[144:145]
	v_pk_fma_f32 v[102:103], v[102:103], v[78:79], v[146:147]
	v_pk_fma_f32 v[96:97], v[96:97], v[72:73], v[148:149]
	v_pk_fma_f32 v[98:99], v[98:99], v[74:75], v[150:151]
	v_cvt_pk_bf16_f32 v100, v100, v101
	v_cvt_pk_bf16_f32 v101, v102, v103
	v_cvt_pk_bf16_f32 v102, v96, v97
	v_cvt_pk_bf16_f32 v103, v98, v99
	v_add_u32_e32 v167, 0x20000, v165
	global_store_dwordx4 v167, v[100:103], s[34:35] offset:256
	s_waitcnt vmcnt(15)
	v_lshlrev_b32_e32 v144, 16, v198
	v_and_b32_e32 v145, 0xffff0000, v198
	v_lshlrev_b32_e32 v146, 16, v199
	v_and_b32_e32 v147, 0xffff0000, v199
	v_lshlrev_b32_e32 v148, 16, v200
	v_and_b32_e32 v149, 0xffff0000, v200
	v_lshlrev_b32_e32 v150, 16, v201
	v_and_b32_e32 v151, 0xffff0000, v201
	v_pk_fma_f32 v[88:89], v[88:89], v[92:93], v[144:145]
	v_pk_fma_f32 v[90:91], v[90:91], v[94:95], v[146:147]
	v_pk_fma_f32 v[80:81], v[80:81], v[84:85], v[148:149]
	v_pk_fma_f32 v[82:83], v[82:83], v[86:87], v[150:151]
	v_cvt_pk_bf16_f32 v88, v88, v89
	v_cvt_pk_bf16_f32 v89, v90, v91
	v_cvt_pk_bf16_f32 v90, v80, v81
	v_cvt_pk_bf16_f32 v91, v82, v83
	v_add_u32_e32 v167, 0x30000, v165
	global_store_dwordx4 v167, v[88:91], s[34:35] offset:0
	s_waitcnt vmcnt(15)
	v_lshlrev_b32_e32 v144, 16, v202
	v_and_b32_e32 v145, 0xffff0000, v202
	v_lshlrev_b32_e32 v146, 16, v203
	v_and_b32_e32 v147, 0xffff0000, v203
	v_lshlrev_b32_e32 v148, 16, v204
	v_and_b32_e32 v149, 0xffff0000, v204
	v_lshlrev_b32_e32 v150, 16, v205
	v_and_b32_e32 v151, 0xffff0000, v205
	v_pk_fma_f32 v[68:69], v[68:69], v[76:77], v[144:145]
	v_pk_fma_f32 v[70:71], v[70:71], v[78:79], v[146:147]
	v_pk_fma_f32 v[64:65], v[64:65], v[72:73], v[148:149]
	v_pk_fma_f32 v[66:67], v[66:67], v[74:75], v[150:151]
	v_cvt_pk_bf16_f32 v68, v68, v69
	v_cvt_pk_bf16_f32 v69, v70, v71
	v_cvt_pk_bf16_f32 v70, v64, v65
	v_cvt_pk_bf16_f32 v71, v66, v67
	v_add_u32_e32 v167, 0x30000, v165
	global_store_dwordx4 v167, v[68:71], s[34:35] offset:256
	s_waitcnt vmcnt(15)
; __device__ __forceinline__ float bflo(unsigned w) { return __uint_as_float(w << 16); }
; __device__ __forceinline__ float bfhi(unsigned w) { return __uint_as_float(w & 0xffff0000u); }
; __device__ __forceinline__ u32x4 pack8u(f32x4 a, f32x4 b) { u32x4 w = {cvt_pk_bf16(a[0], a[1]), cvt_pk_bf16(a[2], a[3]), cvt_pk_bf16(b[0], b[1]), cvt_pk_bf16(b[2], b[3])}; return w; }
;     __device__ __forceinline__ void operator()(const AccT& acc, const Unit& u, int wr, int wc, int fr, int fq) const {
;     ...
;                 for (int bj = 0; bj < 2; ++bj) {
;                     const size_t off = (size_t)row * D + u.pn * 256 + bj * 128 + wc * 32 + fq * 8;
;                     f32x4 x0, x1;
;                     if (XINF) { x0 = *(const f32x4*)(XINF + off); x1 = *(const f32x4*)(XINF + off + 4); }
;                     else { const u32x4 w = *(const u32x4*)(XIN16 + off); x0 = (f32x4){bflo(w[0]), bfhi(w[0]), bflo(w[1]), bfhi(w[1])}; x1 = (f32x4){bflo(w[2]), bfhi(w[2]), bflo(w[3]), bfhi(w[3])}; }
;                     *(u32x4*)(XOUT + off) = pack8u(x0 + gt[bj][0] * acc[ai][bj][m][0], x1 + gt[bj][1] * acc[ai][bj][m][1]);
	v_lshlrev_b32_e32 v144, 16, v228
	v_and_b32_e32 v145, 0xffff0000, v228
	v_lshlrev_b32_e32 v146, 16, v229
	v_and_b32_e32 v147, 0xffff0000, v229
	v_lshlrev_b32_e32 v148, 16, v230
	v_and_b32_e32 v149, 0xffff0000, v230
	v_lshlrev_b32_e32 v150, 16, v231
	v_and_b32_e32 v151, 0xffff0000, v231
	v_pk_fma_f32 v[60:61], v[60:61], v[92:93], v[144:145]
	v_pk_fma_f32 v[62:63], v[62:63], v[94:95], v[146:147]
	v_pk_fma_f32 v[56:57], v[56:57], v[84:85], v[148:149]
	v_pk_fma_f32 v[58:59], v[58:59], v[86:87], v[150:151]
	v_cvt_pk_bf16_f32 v60, v60, v61
	v_cvt_pk_bf16_f32 v61, v62, v63
	v_cvt_pk_bf16_f32 v62, v56, v57
	v_cvt_pk_bf16_f32 v63, v58, v59
	v_add_u32_e32 v167, 0x80000, v165
	global_store_dwordx4 v167, v[60:63], s[34:35] offset:0
	s_waitcnt vmcnt(14)
	v_lshlrev_b32_e32 v144, 16, v168
	v_and_b32_e32 v145, 0xffff0000, v168
	v_lshlrev_b32_e32 v146, 16, v169
	v_and_b32_e32 v147, 0xffff0000, v169
	v_lshlrev_b32_e32 v148, 16, v170
	v_and_b32_e32 v149, 0xffff0000, v170
	v_lshlrev_b32_e32 v150, 16, v171
	v_and_b32_e32 v151, 0xffff0000, v171
	v_pk_fma_f32 v[52:53], v[52:53], v[76:77], v[144:145]
	v_pk_fma_f32 v[54:55], v[54:55], v[78:79], v[146:147]
	v_pk_fma_f32 v[48:49], v[48:49], v[72:73], v[148:149]
	v_pk_fma_f32 v[50:51], v[50:51], v[74:75], v[150:151]
	v_cvt_pk_bf16_f32 v52, v52, v53
	v_cvt_pk_bf16_f32 v53, v54, v55
	v_cvt_pk_bf16_f32 v54, v48, v49
	v_cvt_pk_bf16_f32 v55, v50, v51
	v_add_u32_e32 v167, 0x80000, v165
	global_store_dwordx4 v167, v[52:55], s[34:35] offset:256
	s_waitcnt vmcnt(14)
	v_lshlrev_b32_e32 v144, 16, v136
	v_and_b32_e32 v145, 0xffff0000, v136
	v_lshlrev_b32_e32 v146, 16, v137
	v_and_b32_e32 v147, 0xffff0000, v137
	v_lshlrev_b32_e32 v148, 16, v138
	v_and_b32_e32 v149, 0xffff0000, v138
	v_lshlrev_b32_e32 v150, 16, v139
	v_and_b32_e32 v151, 0xffff0000, v139
	v_pk_fma_f32 v[44:45], v[44:45], v[92:93], v[144:145]
	v_pk_fma_f32 v[46:47], v[46:47], v[94:95], v[146:147]
	v_pk_fma_f32 v[40:41], v[40:41], v[84:85], v[148:149]
	v_pk_fma_f32 v[42:43], v[42:43], v[86:87], v[150:151]
	v_cvt_pk_bf16_f32 v44, v44, v45
	v_cvt_pk_bf16_f32 v45, v46, v47
	v_cvt_pk_bf16_f32 v46, v40, v41
	v_cvt_pk_bf16_f32 v47, v42, v43
	v_add_u32_e32 v167, 0x90000, v165
	global_store_dwordx4 v167, v[44:47], s[34:35] offset:0
	s_waitcnt vmcnt(13)
	v_lshlrev_b32_e32 v144, 16, v178
	v_and_b32_e32 v145, 0xffff0000, v178
	v_lshlrev_b32_e32 v146, 16, v179
	v_and_b32_e32 v147, 0xffff0000, v179
	v_lshlrev_b32_e32 v148, 16, v180
	v_and_b32_e32 v149, 0xffff0000, v180
	v_lshlrev_b32_e32 v150, 16, v181
	v_and_b32_e32 v151, 0xffff0000, v181
	v_pk_fma_f32 v[36:37], v[36:37], v[76:77], v[144:145]
	v_pk_fma_f32 v[38:39], v[38:39], v[78:79], v[146:147]
	v_pk_fma_f32 v[32:33], v[32:33], v[72:73], v[148:149]
	v_pk_fma_f32 v[34:35], v[34:35], v[74:75], v[150:151]
	v_cvt_pk_bf16_f32 v36, v36, v37
	v_cvt_pk_bf16_f32 v37, v38, v39
	v_cvt_pk_bf16_f32 v38, v32, v33
	v_cvt_pk_bf16_f32 v39, v34, v35
	v_add_u32_e32 v167, 0x90000, v165
	global_store_dwordx4 v167, v[36:39], s[34:35] offset:256
	s_waitcnt vmcnt(13)
	v_lshlrev_b32_e32 v144, 16, v128
	v_and_b32_e32 v145, 0xffff0000, v128
	v_lshlrev_b32_e32 v146, 16, v129
	v_and_b32_e32 v147, 0xffff0000, v129
	v_lshlrev_b32_e32 v148, 16, v130
	v_and_b32_e32 v149, 0xffff0000, v130
	v_lshlrev_b32_e32 v150, 16, v131
	v_and_b32_e32 v151, 0xffff0000, v131
	v_pk_fma_f32 v[28:29], v[28:29], v[92:93], v[144:145]
	v_pk_fma_f32 v[30:31], v[30:31], v[94:95], v[146:147]
	v_pk_fma_f32 v[24:25], v[24:25], v[84:85], v[148:149]
	v_pk_fma_f32 v[26:27], v[26:27], v[86:87], v[150:151]
	v_cvt_pk_bf16_f32 v28, v28, v29
	v_cvt_pk_bf16_f32 v29, v30, v31
	v_cvt_pk_bf16_f32 v30, v24, v25
	v_cvt_pk_bf16_f32 v31, v26, v27
	v_add_u32_e32 v167, 0xa0000, v165
	global_store_dwordx4 v167, v[28:31], s[34:35] offset:0
	s_waitcnt vmcnt(12)
	v_lshlrev_b32_e32 v144, 16, v182
	v_and_b32_e32 v145, 0xffff0000, v182
	v_lshlrev_b32_e32 v146, 16, v183
	v_and_b32_e32 v147, 0xffff0000, v183
	v_lshlrev_b32_e32 v148, 16, v184
	v_and_b32_e32 v149, 0xffff0000, v184
	v_lshlrev_b32_e32 v150, 16, v185
	v_and_b32_e32 v151, 0xffff0000, v185
	v_pk_fma_f32 v[20:21], v[20:21], v[76:77], v[144:145]
	v_pk_fma_f32 v[22:23], v[22:23], v[78:79], v[146:147]
	v_pk_fma_f32 v[16:17], v[16:17], v[72:73], v[148:149]
	v_pk_fma_f32 v[18:19], v[18:19], v[74:75], v[150:151]
	v_cvt_pk_bf16_f32 v20, v20, v21
	v_cvt_pk_bf16_f32 v21, v22, v23
	v_cvt_pk_bf16_f32 v22, v16, v17
	v_cvt_pk_bf16_f32 v23, v18, v19
	v_add_u32_e32 v167, 0xa0000, v165
	global_store_dwordx4 v167, v[20:23], s[34:35] offset:256
	s_waitcnt vmcnt(12)
	v_lshlrev_b32_e32 v144, 16, v120
	v_and_b32_e32 v145, 0xffff0000, v120
	v_lshlrev_b32_e32 v146, 16, v121
	v_and_b32_e32 v147, 0xffff0000, v121
	v_lshlrev_b32_e32 v148, 16, v122
	v_and_b32_e32 v149, 0xffff0000, v122
	v_lshlrev_b32_e32 v150, 16, v123
	v_and_b32_e32 v151, 0xffff0000, v123
	v_pk_fma_f32 v[12:13], v[12:13], v[92:93], v[144:145]
	v_pk_fma_f32 v[14:15], v[14:15], v[94:95], v[146:147]
	v_pk_fma_f32 v[8:9], v[8:9], v[84:85], v[148:149]
	v_pk_fma_f32 v[10:11], v[10:11], v[86:87], v[150:151]
	v_cvt_pk_bf16_f32 v12, v12, v13
	v_cvt_pk_bf16_f32 v13, v14, v15
	v_cvt_pk_bf16_f32 v14, v8, v9
	v_cvt_pk_bf16_f32 v15, v10, v11
	v_add_u32_e32 v167, 0xb0000, v165
	global_store_dwordx4 v167, v[12:15], s[34:35] offset:0
	s_waitcnt vmcnt(11)
	v_lshlrev_b32_e32 v144, 16, v186
	v_and_b32_e32 v145, 0xffff0000, v186
	v_lshlrev_b32_e32 v146, 16, v187
	v_and_b32_e32 v147, 0xffff0000, v187
	v_lshlrev_b32_e32 v148, 16, v188
	v_and_b32_e32 v149, 0xffff0000, v188
	v_lshlrev_b32_e32 v150, 16, v189
	v_and_b32_e32 v151, 0xffff0000, v189
	v_pk_fma_f32 v[4:5], v[4:5], v[76:77], v[144:145]
	v_pk_fma_f32 v[6:7], v[6:7], v[78:79], v[146:147]
	v_pk_fma_f32 v[0:1], v[0:1], v[72:73], v[148:149]
	v_pk_fma_f32 v[2:3], v[2:3], v[74:75], v[150:151]
	v_cvt_pk_bf16_f32 v4, v4, v5
	v_cvt_pk_bf16_f32 v5, v6, v7
	v_cvt_pk_bf16_f32 v6, v0, v1
	v_cvt_pk_bf16_f32 v7, v2, v3
	v_add_u32_e32 v167, 0xb0000, v165
	global_store_dwordx4 v167, v[4:7], s[34:35] offset:256
	s_mov_b64 s[42:43], exec
	s_branch .Lepr1_latch

; #define PG8_STAGE(bufoff, gbase, voff) do { _Pragma("unroll") for (int _i = 0; _i < 2; ++_i) \
;         __builtin_amdgcn_global_load_lds((const unsigned*)((const char*)(gbase) + (voff)[_i]), (LAS unsigned*)(lds + (bufoff) + ldsw + _i * 8192), 16, 0, 0); } while (0)
; #define PG8_LDA(dst, b, h) do { _Pragma("unroll") for (int m = 0; m < 4; ++m) _Pragma("unroll") for (int k = 0; k < 2; ++k) dst[m][k] = *(const LAS bf16x8*)(lds + PG8_SA(b, h) + aoff + m * 2048 + k * 1024); } while (0)
; #define PG8_LDB(dst, b, h) do { _Pragma("unroll") for (int n = 0; n < 2; ++n) _Pragma("unroll") for (int k = 0; k < 2; ++k) dst[n][k] = *(const LAS bf16x8*)(lds + PG8_SB(b, h) + boff + n * 2048 + k * 1024); } while (0)
; #define PG8_MMA(ai, bj, At, Bt) do { __builtin_amdgcn_s_setprio(1); _Pragma("unroll") for (int m = 0; m < 4; ++m) _Pragma("unroll") for (int n = 0; n < 2; ++n) _Pragma("unroll") for (int k = 0; k < 2; ++k) \
;         acc[ai][bj][m][n] = __builtin_amdgcn_mfma_f32_16x16x32_bf16(Bt[n][k], At[m][k], acc[ai][bj][m][n], 0, 0, 0); __builtin_amdgcn_s_setprio(0); } while (0)
; #define PG8_WAIT_V(n) asm volatile("s_waitcnt vmcnt(" #n ")" ::: "memory")
; #define PG8_WAIT_L(n) asm volatile("s_waitcnt lgkmcnt(" #n ")" ::: "memory")
; #define PG8_BAR __builtin_amdgcn_s_barrier()
; template <class Epi>
; __device__ __forceinline__ void gemm_phase(LAS unsigned char* lds, const Gemm g, const Epi& E) {
;     ...
;         for (int t = 0; t < nt; t += 2) {
;             const bool last = (t == nt - 2);
;             const char* a1 = cA + (size_t)(t + 1) * kstep;
;             const char* a2 = last ? nA : cA + (size_t)(t + 2) * kstep; const char* b2 = last ? nB : cB + (size_t)(t + 2) * kstep;
;             const char* a3 = a2 + kstep; const char* b3 = b2 + kstep;
;             PG8_LDB(B0, 0, 0); PG8_SCHED; PG8_LDA(At, 0, 0); PG8_STAGE(PG8_SA(1, 1), a1 + hstep, voffA);
;             PG8_WAIT_L(8); PG8_BAR; PG8_WAIT_L(0); PG8_MMA(0, 0, At, B0); PG8_BAR; PG8_SCHED;
;             PG8_LDB(B1, 0, 1); PG8_STAGE(PG8_SB(0, 0), b2, voffB);
;             PG8_BAR; PG8_WAIT_L(0); PG8_MMA(0, 1, At, B1); PG8_BAR;
;             PG8_LDA(At, 0, 1); PG8_STAGE(PG8_SA(0, 0), a2, voffA);
;             PG8_BAR; PG8_WAIT_L(0); PG8_MMA(1, 0, At, B0); PG8_BAR; PG8_SCHED;
;             PG8_STAGE(PG8_SB(0, 1), b2 + hstep, voffB);
;             PG8_WAIT_V(6); PG8_BAR; PG8_MMA(1, 1, At, B1); PG8_BAR;
.LBB0_211:
	s_add_u32 s28, s26, 0xfffc0080
	s_addc_u32 s29, s27, -1
	s_add_i32 s34, 0, 0x10000
	v_add_u32_e32 v150, s34, v159
	ds_read_b128 v[138:141], v150
	ds_read_b128 v[142:145], v150 offset:1024
	ds_read_b128 v[146:149], v150 offset:2048
	ds_read_b128 v[150:153], v150 offset:3072
	s_cmp_eq_u32 vcc_hi, 12
	s_cselect_b32 s37, s38, s29
	s_cselect_b32 s36, s39, s28
	s_cselect_b32 s29, s43, vcc_lo
	s_cselect_b32 s28, s49, s65
	s_add_i32 m0, s74, 0xc000
	ds_read_b128 v[154:157], v161
	ds_read_b128 v[162:165], v161 offset:1024
	ds_read_b128 v[166:169], v161 offset:2048
	ds_read_b128 v[170:173], v161 offset:3072
	ds_read_b128 v[174:177], v161 offset:4096
	ds_read_b128 v[178:181], v161 offset:5120
	ds_read_b128 v[182:185], v161 offset:6144
	ds_read_b128 v[186:189], v161 offset:7168
	global_load_lds_dwordx4 v134, s[26:27]
	s_add_i32 m0, s74, 0xe000
	s_nop 0
	global_load_lds_dwordx4 v136, s[26:27]
	s_waitcnt lgkmcnt(8)
	s_setprio 1
	s_barrier
	s_waitcnt lgkmcnt(0)
	v_mfma_f32_16x16x32_bf16 v[124:127], v[138:141], v[154:157], v[124:127]
	v_mfma_f32_16x16x32_bf16 v[120:123], v[146:149], v[154:157], v[120:123]
	v_mfma_f32_16x16x32_bf16 v[108:111], v[138:141], v[166:169], v[108:111]
	v_mfma_f32_16x16x32_bf16 v[104:107], v[146:149], v[166:169], v[104:107]
	v_mfma_f32_16x16x32_bf16 v[92:95], v[138:141], v[174:177], v[92:95]
	v_mfma_f32_16x16x32_bf16 v[88:91], v[146:149], v[174:177], v[88:91]
	v_mfma_f32_16x16x32_bf16 v[76:79], v[138:141], v[182:185], v[76:79]
	v_mfma_f32_16x16x32_bf16 v[72:75], v[146:149], v[182:185], v[72:75]
	v_mfma_f32_16x16x32_bf16 v[124:127], v[142:145], v[162:165], v[124:127]
	v_mfma_f32_16x16x32_bf16 v[120:123], v[150:153], v[162:165], v[120:123]
	v_mfma_f32_16x16x32_bf16 v[108:111], v[142:145], v[170:173], v[108:111]
	v_mfma_f32_16x16x32_bf16 v[104:107], v[150:153], v[170:173], v[104:107]
	v_mfma_f32_16x16x32_bf16 v[92:95], v[142:145], v[178:181], v[92:95]
	v_mfma_f32_16x16x32_bf16 v[88:91], v[150:153], v[178:181], v[88:91]
	v_mfma_f32_16x16x32_bf16 v[76:79], v[142:145], v[186:189], v[76:79]
	v_mfma_f32_16x16x32_bf16 v[72:75], v[150:153], v[186:189], v[72:75]
	s_barrier
	s_setprio 0
	s_add_i32 s46, 0, 0x14000
	s_add_i32 s34, s34, s71
	v_add_u32_e32 v202, s46, v159
	s_mov_b32 m0, s34
	ds_read_b128 v[190:193], v202
	ds_read_b128 v[194:197], v202 offset:1024
	ds_read_b128 v[198:201], v202 offset:2048
	ds_read_b128 v[202:205], v202 offset:3072
	global_load_lds_dwordx4 v208, s[28:29]
	s_add_i32 m0, s34, 0x2000
	s_nop 0
	global_load_lds_dwordx4 v132, s[28:29]
	s_setprio 1
	s_barrier
	s_waitcnt lgkmcnt(0)
	v_mfma_f32_16x16x32_bf16 v[116:119], v[190:193], v[154:157], v[116:119]
	v_mfma_f32_16x16x32_bf16 v[112:115], v[198:201], v[154:157], v[112:115]
	v_mfma_f32_16x16x32_bf16 v[100:103], v[190:193], v[166:169], v[100:103]
	v_mfma_f32_16x16x32_bf16 v[96:99], v[198:201], v[166:169], v[96:99]
	v_mfma_f32_16x16x32_bf16 v[84:87], v[190:193], v[174:177], v[84:87]
	v_mfma_f32_16x16x32_bf16 v[80:83], v[198:201], v[174:177], v[80:83]
	v_mfma_f32_16x16x32_bf16 v[68:71], v[190:193], v[182:185], v[68:71]
	v_mfma_f32_16x16x32_bf16 v[64:67], v[198:201], v[182:185], v[64:67]
	v_mfma_f32_16x16x32_bf16 v[116:119], v[194:197], v[162:165], v[116:119]
	v_mfma_f32_16x16x32_bf16 v[112:115], v[202:205], v[162:165], v[112:115]
	v_mfma_f32_16x16x32_bf16 v[100:103], v[194:197], v[170:173], v[100:103]
	v_mfma_f32_16x16x32_bf16 v[96:99], v[202:205], v[170:173], v[96:99]
	v_mfma_f32_16x16x32_bf16 v[84:87], v[194:197], v[178:181], v[84:87]
	v_mfma_f32_16x16x32_bf16 v[80:83], v[202:205], v[178:181], v[80:83]
	v_mfma_f32_16x16x32_bf16 v[68:71], v[194:197], v[186:189], v[68:71]
	v_mfma_f32_16x16x32_bf16 v[64:67], v[202:205], v[186:189], v[64:67]
	s_barrier
	s_setprio 0
	s_mov_b32 m0, s74
	ds_read_b128 v[154:157], v161 offset:16384
	ds_read_b128 v[162:165], v161 offset:17408
	ds_read_b128 v[166:169], v161 offset:18432
	ds_read_b128 v[170:173], v161 offset:19456
	ds_read_b128 v[174:177], v161 offset:20480
	ds_read_b128 v[178:181], v161 offset:21504
	ds_read_b128 v[182:185], v161 offset:22528
	ds_read_b128 v[186:189], v161 offset:23552
	global_load_lds_dwordx4 v128, s[36:37]
	s_mov_b32 m0, s76
	s_nop 0
	global_load_lds_dwordx4 v130, s[36:37]
	s_setprio 1
	s_barrier
	s_waitcnt lgkmcnt(0)
	v_mfma_f32_16x16x32_bf16 v[60:63], v[138:141], v[154:157], v[60:63]
	v_mfma_f32_16x16x32_bf16 v[56:59], v[146:149], v[154:157], v[56:59]
	v_mfma_f32_16x16x32_bf16 v[44:47], v[138:141], v[166:169], v[44:47]
	v_mfma_f32_16x16x32_bf16 v[40:43], v[146:149], v[166:169], v[40:43]
	v_mfma_f32_16x16x32_bf16 v[28:31], v[138:141], v[174:177], v[28:31]
	v_mfma_f32_16x16x32_bf16 v[24:27], v[146:149], v[174:177], v[24:27]
	v_mfma_f32_16x16x32_bf16 v[12:15], v[138:141], v[182:185], v[12:15]
	v_mfma_f32_16x16x32_bf16 v[8:11], v[146:149], v[182:185], v[8:11]
	v_mfma_f32_16x16x32_bf16 v[60:63], v[142:145], v[162:165], v[60:63]
	v_mfma_f32_16x16x32_bf16 v[56:59], v[150:153], v[162:165], v[56:59]
	v_mfma_f32_16x16x32_bf16 v[44:47], v[142:145], v[170:173], v[44:47]
	v_mfma_f32_16x16x32_bf16 v[40:43], v[150:153], v[170:173], v[40:43]
	v_mfma_f32_16x16x32_bf16 v[28:31], v[142:145], v[178:181], v[28:31]
	v_mfma_f32_16x16x32_bf16 v[24:27], v[150:153], v[178:181], v[24:27]
	v_mfma_f32_16x16x32_bf16 v[12:15], v[142:145], v[186:189], v[12:15]
	v_mfma_f32_16x16x32_bf16 v[8:11], v[150:153], v[186:189], v[8:11]
	s_barrier
	s_setprio 0
	s_add_u32 s34, s28, 0x40000
	s_addc_u32 s35, s29, 0
	s_add_i32 s46, s46, s71
	s_mov_b32 m0, s46
	s_nop 0
	global_load_lds_dwordx4 v208, s[34:35]
	s_add_i32 m0, s46, 0x2000
	s_nop 0
	global_load_lds_dwordx4 v132, s[34:35]
	s_waitcnt vmcnt(6)
	s_setprio 1
	s_barrier
; #define PG8_STAGE(bufoff, gbase, voff) do { _Pragma("unroll") for (int _i = 0; _i < 2; ++_i) \
;         __builtin_amdgcn_global_load_lds((const unsigned*)((const char*)(gbase) + (voff)[_i]), (LAS unsigned*)(lds + (bufoff) + ldsw + _i * 8192), 16, 0, 0); } while (0)
; #define PG8_LDA(dst, b, h) do { _Pragma("unroll") for (int m = 0; m < 4; ++m) _Pragma("unroll") for (int k = 0; k < 2; ++k) dst[m][k] = *(const LAS bf16x8*)(lds + PG8_SA(b, h) + aoff + m * 2048 + k * 1024); } while (0)
; #define PG8_LDB(dst, b, h) do { _Pragma("unroll") for (int n = 0; n < 2; ++n) _Pragma("unroll") for (int k = 0; k < 2; ++k) dst[n][k] = *(const LAS bf16x8*)(lds + PG8_SB(b, h) + boff + n * 2048 + k * 1024); } while (0)
; #define PG8_MMA(ai, bj, At, Bt) do { __builtin_amdgcn_s_setprio(1); _Pragma("unroll") for (int m = 0; m < 4; ++m) _Pragma("unroll") for (int n = 0; n < 2; ++n) _Pragma("unroll") for (int k = 0; k < 2; ++k) \
;         acc[ai][bj][m][n] = __builtin_amdgcn_mfma_f32_16x16x32_bf16(Bt[n][k], At[m][k], acc[ai][bj][m][n], 0, 0, 0); __builtin_amdgcn_s_setprio(0); } while (0)
; #define PG8_WAIT_V(n) asm volatile("s_waitcnt vmcnt(" #n ")" ::: "memory")
; #define PG8_WAIT_L(n) asm volatile("s_waitcnt lgkmcnt(" #n ")" ::: "memory")
; #define PG8_BAR __builtin_amdgcn_s_barrier()
; #define PG8_SCHED __builtin_amdgcn_sched_barrier(0)
; template <class Epi>
; __device__ __forceinline__ void gemm_phase(LAS unsigned char* lds, const Gemm g, const Epi& E) {
;     ...
;             PG8_WAIT_V(6); PG8_BAR; PG8_MMA(1, 1, At, B1); PG8_BAR;
;             PG8_LDB(B0, 1, 0); PG8_SCHED; PG8_LDA(At, 1, 0); PG8_STAGE(PG8_SA(0, 1), a2 + hstep, voffA);
;             PG8_WAIT_L(8); PG8_BAR; PG8_WAIT_L(0); PG8_MMA(0, 0, At, B0); PG8_BAR; PG8_SCHED;
;             PG8_LDB(B1, 1, 1); PG8_STAGE(PG8_SB(1, 0), b3, voffB);
;             PG8_BAR; PG8_WAIT_L(0); PG8_MMA(0, 1, At, B1); PG8_BAR;
;             PG8_LDA(At, 1, 1); PG8_STAGE(PG8_SA(1, 0), a3, voffA);
;             PG8_BAR; PG8_WAIT_L(0); PG8_MMA(1, 0, At, B0); PG8_BAR; PG8_SCHED;
;             PG8_STAGE(PG8_SB(1, 1), b3 + hstep, voffB);
	v_mfma_f32_16x16x32_bf16 v[52:55], v[190:193], v[154:157], v[52:55]
	v_mfma_f32_16x16x32_bf16 v[48:51], v[198:201], v[154:157], v[48:51]
	v_mfma_f32_16x16x32_bf16 v[36:39], v[190:193], v[166:169], v[36:39]
	v_mfma_f32_16x16x32_bf16 v[32:35], v[198:201], v[166:169], v[32:35]
	v_mfma_f32_16x16x32_bf16 v[20:23], v[190:193], v[174:177], v[20:23]
	v_mfma_f32_16x16x32_bf16 v[16:19], v[198:201], v[174:177], v[16:19]
	v_mfma_f32_16x16x32_bf16 v[4:7], v[190:193], v[182:185], v[4:7]
	v_mfma_f32_16x16x32_bf16 v[0:3], v[198:201], v[182:185], v[0:3]
	v_mfma_f32_16x16x32_bf16 v[52:55], v[194:197], v[162:165], v[52:55]
	v_mfma_f32_16x16x32_bf16 v[48:51], v[202:205], v[162:165], v[48:51]
	v_mfma_f32_16x16x32_bf16 v[36:39], v[194:197], v[170:173], v[36:39]
	v_mfma_f32_16x16x32_bf16 v[32:35], v[202:205], v[170:173], v[32:35]
	v_mfma_f32_16x16x32_bf16 v[20:23], v[194:197], v[178:181], v[20:23]
	v_mfma_f32_16x16x32_bf16 v[16:19], v[202:205], v[178:181], v[16:19]
	v_mfma_f32_16x16x32_bf16 v[4:7], v[194:197], v[186:189], v[4:7]
	v_mfma_f32_16x16x32_bf16 v[0:3], v[202:205], v[186:189], v[0:3]
	s_barrier
	s_setprio 0
	s_add_i32 s46, 0, 0x18000
	v_add_u32_e32 v150, s46, v159
	ds_read_b128 v[138:141], v150
	ds_read_b128 v[142:145], v150 offset:1024
	ds_read_b128 v[146:149], v150 offset:2048
	ds_read_b128 v[150:153], v150 offset:3072
	s_add_u32 s34, s36, 0x40000
	s_addc_u32 s35, s37, 0
	s_mov_b32 m0, s78
	ds_read_b128 v[154:157], v161 offset:32768
	ds_read_b128 v[162:165], v161 offset:33792
	ds_read_b128 v[166:169], v161 offset:34816
	ds_read_b128 v[170:173], v161 offset:35840
	ds_read_b128 v[174:177], v161 offset:36864
	ds_read_b128 v[178:181], v161 offset:37888
	ds_read_b128 v[182:185], v161 offset:38912
	ds_read_b128 v[186:189], v161 offset:39936
	global_load_lds_dwordx4 v128, s[34:35]
	s_mov_b32 m0, s79
	s_nop 0
	global_load_lds_dwordx4 v130, s[34:35]
	s_waitcnt lgkmcnt(8)
	s_setprio 1
	s_barrier
	s_waitcnt lgkmcnt(0)
	v_mfma_f32_16x16x32_bf16 v[124:127], v[138:141], v[154:157], v[124:127]
	v_mfma_f32_16x16x32_bf16 v[120:123], v[146:149], v[154:157], v[120:123]
	v_mfma_f32_16x16x32_bf16 v[108:111], v[138:141], v[166:169], v[108:111]
	v_mfma_f32_16x16x32_bf16 v[104:107], v[146:149], v[166:169], v[104:107]
	v_mfma_f32_16x16x32_bf16 v[92:95], v[138:141], v[174:177], v[92:95]
	v_mfma_f32_16x16x32_bf16 v[88:91], v[146:149], v[174:177], v[88:91]
	v_mfma_f32_16x16x32_bf16 v[76:79], v[138:141], v[182:185], v[76:79]
	v_mfma_f32_16x16x32_bf16 v[72:75], v[146:149], v[182:185], v[72:75]
	v_mfma_f32_16x16x32_bf16 v[124:127], v[142:145], v[162:165], v[124:127]
	v_mfma_f32_16x16x32_bf16 v[120:123], v[150:153], v[162:165], v[120:123]
	v_mfma_f32_16x16x32_bf16 v[108:111], v[142:145], v[170:173], v[108:111]
	v_mfma_f32_16x16x32_bf16 v[104:107], v[150:153], v[170:173], v[104:107]
	v_mfma_f32_16x16x32_bf16 v[92:95], v[142:145], v[178:181], v[92:95]
	v_mfma_f32_16x16x32_bf16 v[88:91], v[150:153], v[178:181], v[88:91]
	v_mfma_f32_16x16x32_bf16 v[76:79], v[142:145], v[186:189], v[76:79]
	v_mfma_f32_16x16x32_bf16 v[72:75], v[150:153], v[186:189], v[72:75]
	s_barrier
	s_setprio 0
	s_add_i32 s34, 0, 0x1c000
	s_add_i32 s35, s46, s71
	v_add_u32_e32 v202, s34, v159
	s_mov_b32 m0, s35
	ds_read_b128 v[190:193], v202
	ds_read_b128 v[194:197], v202 offset:1024
	ds_read_b128 v[198:201], v202 offset:2048
	ds_read_b128 v[202:205], v202 offset:3072
	s_add_u32 s98, s28, 0x80
	s_addc_u32 s99, s29, 0
	global_load_lds_dwordx4 v208, s[98:99]
	s_add_i32 m0, s35, 0x2000
	s_add_u32 s100, s28, 0x80
	s_addc_u32 s101, s29, 0
	global_load_lds_dwordx4 v132, s[100:101]
	s_setprio 1
	s_barrier
	s_waitcnt lgkmcnt(0)
	v_mfma_f32_16x16x32_bf16 v[116:119], v[190:193], v[154:157], v[116:119]
	v_mfma_f32_16x16x32_bf16 v[112:115], v[198:201], v[154:157], v[112:115]
	v_mfma_f32_16x16x32_bf16 v[100:103], v[190:193], v[166:169], v[100:103]
	v_mfma_f32_16x16x32_bf16 v[96:99], v[198:201], v[166:169], v[96:99]
	v_mfma_f32_16x16x32_bf16 v[84:87], v[190:193], v[174:177], v[84:87]
	v_mfma_f32_16x16x32_bf16 v[80:83], v[198:201], v[174:177], v[80:83]
	v_mfma_f32_16x16x32_bf16 v[68:71], v[190:193], v[182:185], v[68:71]
	v_mfma_f32_16x16x32_bf16 v[64:67], v[198:201], v[182:185], v[64:67]
	v_mfma_f32_16x16x32_bf16 v[116:119], v[194:197], v[162:165], v[116:119]
	v_mfma_f32_16x16x32_bf16 v[112:115], v[202:205], v[162:165], v[112:115]
	v_mfma_f32_16x16x32_bf16 v[100:103], v[194:197], v[170:173], v[100:103]
	v_mfma_f32_16x16x32_bf16 v[96:99], v[202:205], v[170:173], v[96:99]
	v_mfma_f32_16x16x32_bf16 v[84:87], v[194:197], v[178:181], v[84:87]
	v_mfma_f32_16x16x32_bf16 v[80:83], v[202:205], v[178:181], v[80:83]
	v_mfma_f32_16x16x32_bf16 v[68:71], v[194:197], v[186:189], v[68:71]
	v_mfma_f32_16x16x32_bf16 v[64:67], v[202:205], v[186:189], v[64:67]
	s_barrier
	s_setprio 0
	s_mov_b32 m0, s82
	ds_read_b128 v[154:157], v161 offset:49152
	ds_read_b128 v[162:165], v161 offset:50176
	ds_read_b128 v[166:169], v161 offset:51200
	ds_read_b128 v[170:173], v161 offset:52224
	ds_read_b128 v[174:177], v161 offset:53248
	ds_read_b128 v[178:181], v161 offset:54272
	ds_read_b128 v[182:185], v161 offset:55296
	ds_read_b128 v[186:189], v161 offset:56320
	s_add_u32 s98, s36, 0x80
	s_addc_u32 s99, s37, 0
	global_load_lds_dwordx4 v128, s[98:99]
	s_mov_b32 m0, s83
	s_add_u32 s100, s36, 0x80
	s_addc_u32 s101, s37, 0
	global_load_lds_dwordx4 v130, s[100:101]
	s_setprio 1
	s_barrier
; __device__ __forceinline__ float bflo(unsigned w) { return __uint_as_float(w << 16); }
; __device__ __forceinline__ float bfhi(unsigned w) { return __uint_as_float(w & 0xffff0000u); }
; __device__ __forceinline__ u32x4 pack8u(f32x4 a, f32x4 b) { u32x4 w = {cvt_pk_bf16(a[0], a[1]), cvt_pk_bf16(a[2], a[3]), cvt_pk_bf16(b[0], b[1]), cvt_pk_bf16(b[2], b[3])}; return w; }
; #define PG8_STAGE(bufoff, gbase, voff) do { _Pragma("unroll") for (int _i = 0; _i < 2; ++_i) \
;         __builtin_amdgcn_global_load_lds((const unsigned*)((const char*)(gbase) + (voff)[_i]), (LAS unsigned*)(lds + (bufoff) + ldsw + _i * 8192), 16, 0, 0); } while (0)
; #define PG8_LDA(dst, b, h) do { _Pragma("unroll") for (int m = 0; m < 4; ++m) _Pragma("unroll") for (int k = 0; k < 2; ++k) dst[m][k] = *(const LAS bf16x8*)(lds + PG8_SA(b, h) + aoff + m * 2048 + k * 1024); } while (0)
; #define PG8_WAIT_V(n) asm volatile("s_waitcnt vmcnt(" #n ")" ::: "memory")
; template <class Epi>
; __device__ __forceinline__ void gemm_phase(LAS unsigned char* lds, const Gemm g, const Epi& E) {
;     ...
;             PG8_LDB(B1, 1, 1); PG8_STAGE(PG8_SB(1, 0), b3, voffB);
;             PG8_BAR; PG8_WAIT_L(0); PG8_MMA(0, 1, At, B1); PG8_BAR;
;             PG8_LDA(At, 1, 1); PG8_STAGE(PG8_SA(1, 0), a3, voffA);
;             PG8_BAR; PG8_WAIT_L(0); PG8_MMA(1, 0, At, B0); PG8_BAR; PG8_SCHED;
;             PG8_STAGE(PG8_SB(1, 1), b3 + hstep, voffB);
;             PG8_WAIT_V(6); PG8_BAR; PG8_MMA(1, 1, At, B1); PG8_BAR;
;     __device__ __forceinline__ void operator()(const AccT& acc, const Unit& u, int wr, int wc, int fr, int fq) const {
;     ...
;         for (int ai = 0; ai < 2; ++ai)
; #pragma unroll
;             for (int m = 0; m < 4; ++m) {
;                 const int row = u.pm * 256 + ai * 128 + wr * 64 + m * 16 + fr;
; #pragma unroll
;                 for (int bj = 0; bj < 2; ++bj) {
;                     const int c8 = u.pn * 256 + bj * 128 + wc * 32 + fq * 8;
;                     const u32x4 gw = *(const u32x4*)(GATE + (size_t)row * 4096 + SECOND * 2048 + c8);
;                     const f32x4 g0 = {bflo(gw[0]), bfhi(gw[0]), bflo(gw[1]), bfhi(gw[1])}, g1 = {bflo(gw[2]), bfhi(gw[2]), bflo(gw[3]), bfhi(gw[3])};
;                     bf16_t* tp = (bf16_t*)TMP + (size_t)row * 2048 + c8;
;                     if (SECOND == 0) { *(u32x4*)tp = pack8u(g0 * acc[ai][bj][m][0], g1 * acc[ai][bj][m][1]); }
	s_waitcnt lgkmcnt(0)
	v_mfma_f32_16x16x32_bf16 v[60:63], v[138:141], v[154:157], v[60:63]
	v_mfma_f32_16x16x32_bf16 v[56:59], v[146:149], v[154:157], v[56:59]
	v_mfma_f32_16x16x32_bf16 v[44:47], v[138:141], v[166:169], v[44:47]
	v_mfma_f32_16x16x32_bf16 v[40:43], v[146:149], v[166:169], v[40:43]
	v_mfma_f32_16x16x32_bf16 v[28:31], v[138:141], v[174:177], v[28:31]
	v_mfma_f32_16x16x32_bf16 v[24:27], v[146:149], v[174:177], v[24:27]
	v_mfma_f32_16x16x32_bf16 v[12:15], v[138:141], v[182:185], v[12:15]
	v_mfma_f32_16x16x32_bf16 v[8:11], v[146:149], v[182:185], v[8:11]
	v_mfma_f32_16x16x32_bf16 v[60:63], v[142:145], v[162:165], v[60:63]
	v_mfma_f32_16x16x32_bf16 v[56:59], v[150:153], v[162:165], v[56:59]
	v_mfma_f32_16x16x32_bf16 v[44:47], v[142:145], v[170:173], v[44:47]
	v_mfma_f32_16x16x32_bf16 v[40:43], v[150:153], v[170:173], v[40:43]
	v_mfma_f32_16x16x32_bf16 v[28:31], v[142:145], v[178:181], v[28:31]
	v_mfma_f32_16x16x32_bf16 v[24:27], v[150:153], v[178:181], v[24:27]
	v_mfma_f32_16x16x32_bf16 v[12:15], v[142:145], v[186:189], v[12:15]
	v_mfma_f32_16x16x32_bf16 v[8:11], v[150:153], v[186:189], v[8:11]
	s_barrier
	s_setprio 0
	s_add_u32 s28, s28, 0x40080
	s_addc_u32 s29, s29, 0
	s_add_i32 s34, s34, s71
	s_mov_b32 m0, s34
	s_nop 0
	global_load_lds_dwordx4 v208, s[28:29]
	s_add_i32 m0, s34, 0x2000
	s_nop 0
	global_load_lds_dwordx4 v132, s[28:29]
	s_waitcnt vmcnt(6)
	s_setprio 1
	s_barrier
	v_mfma_f32_16x16x32_bf16 v[52:55], v[190:193], v[154:157], v[52:55]
	v_mfma_f32_16x16x32_bf16 v[48:51], v[198:201], v[154:157], v[48:51]
	v_mfma_f32_16x16x32_bf16 v[36:39], v[190:193], v[166:169], v[36:39]
	v_mfma_f32_16x16x32_bf16 v[32:35], v[198:201], v[166:169], v[32:35]
	v_mfma_f32_16x16x32_bf16 v[20:23], v[190:193], v[174:177], v[20:23]
	v_mfma_f32_16x16x32_bf16 v[16:19], v[198:201], v[174:177], v[16:19]
	v_mfma_f32_16x16x32_bf16 v[4:7], v[190:193], v[182:185], v[4:7]
	v_mfma_f32_16x16x32_bf16 v[0:3], v[198:201], v[182:185], v[0:3]
	v_mfma_f32_16x16x32_bf16 v[52:55], v[194:197], v[162:165], v[52:55]
	v_mfma_f32_16x16x32_bf16 v[48:51], v[202:205], v[162:165], v[48:51]
	v_mfma_f32_16x16x32_bf16 v[36:39], v[194:197], v[170:173], v[36:39]
	v_mfma_f32_16x16x32_bf16 v[32:35], v[202:205], v[170:173], v[32:35]
	v_mfma_f32_16x16x32_bf16 v[20:23], v[194:197], v[178:181], v[20:23]
	v_mfma_f32_16x16x32_bf16 v[16:19], v[202:205], v[178:181], v[16:19]
	v_mfma_f32_16x16x32_bf16 v[4:7], v[194:197], v[186:189], v[4:7]
	v_mfma_f32_16x16x32_bf16 v[0:3], v[202:205], v[186:189], v[0:3]
	s_barrier
	s_setprio 0
	s_add_i32 vcc_hi, vcc_hi, 2
	s_add_u32 s26, s26, 0x100
	s_addc_u32 s27, s27, 0
	s_add_u32 s65, s65, 0x100
	s_addc_u32 vcc_lo, vcc_lo, 0
	s_cmp_gt_u32 vcc_hi, 13
	s_cbranch_scc0 .LBB0_211
	v_lshl_add_u32 v140, s42, 8, v158
	v_lshl_or_b32 v141, s96, 8, v160
	v_lshlrev_b32_e32 v141, 1, v141
	v_lshl_add_u32 v138, v140, 13, v141
	v_lshl_add_u32 v139, v140, 12, v141
	s_and_b64 vcc, exec, s[0:1]
	s_cbranch_vccnz .Lepo_second
	v_add_u32_e32 v140, 0x0, v138
	global_load_dwordx4 v[162:165], v140, s[44:45]
	v_add_u32_e32 v140, 0x0, v138
	global_load_dwordx4 v[166:169], v140, s[44:45] offset:256
	v_add_u32_e32 v140, 0x20000, v138
	global_load_dwordx4 v[170:173], v140, s[44:45]
	v_add_u32_e32 v140, 0x20000, v138
	global_load_dwordx4 v[174:177], v140, s[44:45] offset:256
	v_add_u32_e32 v140, 0x40000, v138
	global_load_dwordx4 v[178:181], v140, s[44:45]
	v_add_u32_e32 v140, 0x40000, v138
	global_load_dwordx4 v[182:185], v140, s[44:45] offset:256
	v_add_u32_e32 v140, 0x60000, v138
	global_load_dwordx4 v[186:189], v140, s[44:45]
	v_add_u32_e32 v140, 0x60000, v138
	global_load_dwordx4 v[190:193], v140, s[44:45] offset:256
	v_add_u32_e32 v140, 0x100000, v138
	global_load_dwordx4 v[194:197], v140, s[44:45]
	v_add_u32_e32 v140, 0x100000, v138
	global_load_dwordx4 v[198:201], v140, s[44:45] offset:256
	v_add_u32_e32 v140, 0x120000, v138
	global_load_dwordx4 v[202:205], v140, s[44:45]
	v_add_u32_e32 v140, 0x120000, v138
	global_load_dwordx4 v[228:231], v140, s[44:45] offset:256
	s_waitcnt vmcnt(11)
	v_lshlrev_b32_e32 v142, 16, v162
	v_and_b32_e32 v143, 0xffff0000, v162
	v_lshlrev_b32_e32 v144, 16, v163
	v_and_b32_e32 v145, 0xffff0000, v163
	v_lshlrev_b32_e32 v146, 16, v164
	v_and_b32_e32 v147, 0xffff0000, v164
	v_lshlrev_b32_e32 v148, 16, v165
	v_and_b32_e32 v149, 0xffff0000, v165
	v_pk_mul_f32 v[124:125], v[124:125], v[142:143]
	v_pk_mul_f32 v[126:127], v[126:127], v[144:145]
	v_pk_mul_f32 v[120:121], v[120:121], v[146:147]
	v_pk_mul_f32 v[122:123], v[122:123], v[148:149]
	v_cvt_pk_bf16_f32 v124, v124, v125
	v_cvt_pk_bf16_f32 v125, v126, v127
	v_cvt_pk_bf16_f32 v126, v120, v121
	v_cvt_pk_bf16_f32 v127, v122, v123
	v_add_u32_e32 v141, 0x0, v139
	global_store_dwordx4 v141, v[124:127], s[92:93]
	v_add_u32_e32 v140, 0x140000, v138
	global_load_dwordx4 v[162:165], v140, s[44:45]
	v_add_u32_e32 v140, 0x140000, v138
	global_load_dwordx4 v[120:123], v140, s[44:45] offset:256
	s_waitcnt vmcnt(13)
	v_lshlrev_b32_e32 v142, 16, v166
	v_and_b32_e32 v143, 0xffff0000, v166
	v_lshlrev_b32_e32 v144, 16, v167
	v_and_b32_e32 v145, 0xffff0000, v167
	v_lshlrev_b32_e32 v146, 16, v168
	v_and_b32_e32 v147, 0xffff0000, v168
	v_lshlrev_b32_e32 v148, 16, v169
	v_and_b32_e32 v149, 0xffff0000, v169
	v_pk_mul_f32 v[116:117], v[116:117], v[142:143]
	v_pk_mul_f32 v[118:119], v[118:119], v[144:145]
	v_pk_mul_f32 v[112:113], v[112:113], v[146:147]
	v_pk_mul_f32 v[114:115], v[114:115], v[148:149]
	v_cvt_pk_bf16_f32 v116, v116, v117
	v_cvt_pk_bf16_f32 v117, v118, v119
	v_cvt_pk_bf16_f32 v118, v112, v113
	v_cvt_pk_bf16_f32 v119, v114, v115
	v_add_u32_e32 v141, 0x0, v139
	global_store_dwordx4 v141, v[116:119], s[92:93] offset:256
	v_add_u32_e32 v140, 0x160000, v138
	global_load_dwordx4 v[166:169], v140, s[44:45]
	v_add_u32_e32 v140, 0x160000, v138
	global_load_dwordx4 v[112:115], v140, s[44:45] offset:256
	s_waitcnt vmcnt(15)
; __device__ __forceinline__ float bflo(unsigned w) { return __uint_as_float(w << 16); }
; __device__ __forceinline__ float bfhi(unsigned w) { return __uint_as_float(w & 0xffff0000u); }
; __device__ __forceinline__ u32x4 pack8u(f32x4 a, f32x4 b) { u32x4 w = {cvt_pk_bf16(a[0], a[1]), cvt_pk_bf16(a[2], a[3]), cvt_pk_bf16(b[0], b[1]), cvt_pk_bf16(b[2], b[3])}; return w; }
;     __device__ __forceinline__ void operator()(const AccT& acc, const Unit& u, int wr, int wc, int fr, int fq) const {
;     ...
; #pragma unroll
;                 for (int bj = 0; bj < 2; ++bj) {
;                     const int c8 = u.pn * 256 + bj * 128 + wc * 32 + fq * 8;
;                     const u32x4 gw = *(const u32x4*)(GATE + (size_t)row * 4096 + SECOND * 2048 + c8);
;                     const f32x4 g0 = {bflo(gw[0]), bfhi(gw[0]), bflo(gw[1]), bfhi(gw[1])}, g1 = {bflo(gw[2]), bfhi(gw[2]), bflo(gw[3]), bfhi(gw[3])};
;                     bf16_t* tp = (bf16_t*)TMP + (size_t)row * 2048 + c8;
;                     if (SECOND == 0) { *(u32x4*)tp = pack8u(g0 * acc[ai][bj][m][0], g1 * acc[ai][bj][m][1]); }
	v_lshlrev_b32_e32 v142, 16, v170
	v_and_b32_e32 v143, 0xffff0000, v170
	v_lshlrev_b32_e32 v144, 16, v171
	v_and_b32_e32 v145, 0xffff0000, v171
	v_lshlrev_b32_e32 v146, 16, v172
	v_and_b32_e32 v147, 0xffff0000, v172
	v_lshlrev_b32_e32 v148, 16, v173
	v_and_b32_e32 v149, 0xffff0000, v173
	v_pk_mul_f32 v[108:109], v[108:109], v[142:143]
	v_pk_mul_f32 v[110:111], v[110:111], v[144:145]
	v_pk_mul_f32 v[104:105], v[104:105], v[146:147]
	v_pk_mul_f32 v[106:107], v[106:107], v[148:149]
	v_cvt_pk_bf16_f32 v108, v108, v109
	v_cvt_pk_bf16_f32 v109, v110, v111
	v_cvt_pk_bf16_f32 v110, v104, v105
	v_cvt_pk_bf16_f32 v111, v106, v107
	v_add_u32_e32 v141, 0x10000, v139
	global_store_dwordx4 v141, v[108:111], s[92:93]
	s_waitcnt vmcnt(15)
	v_lshlrev_b32_e32 v142, 16, v174
	v_and_b32_e32 v143, 0xffff0000, v174
	v_lshlrev_b32_e32 v144, 16, v175
	v_and_b32_e32 v145, 0xffff0000, v175
	v_lshlrev_b32_e32 v146, 16, v176
	v_and_b32_e32 v147, 0xffff0000, v176
	v_lshlrev_b32_e32 v148, 16, v177
	v_and_b32_e32 v149, 0xffff0000, v177
	v_pk_mul_f32 v[100:101], v[100:101], v[142:143]
	v_pk_mul_f32 v[102:103], v[102:103], v[144:145]
	v_pk_mul_f32 v[96:97], v[96:97], v[146:147]
	v_pk_mul_f32 v[98:99], v[98:99], v[148:149]
	v_cvt_pk_bf16_f32 v100, v100, v101
	v_cvt_pk_bf16_f32 v101, v102, v103
	v_cvt_pk_bf16_f32 v102, v96, v97
	v_cvt_pk_bf16_f32 v103, v98, v99
	v_add_u32_e32 v141, 0x10000, v139
	global_store_dwordx4 v141, v[100:103], s[92:93] offset:256
	s_waitcnt vmcnt(15)
	v_lshlrev_b32_e32 v142, 16, v178
	v_and_b32_e32 v143, 0xffff0000, v178
	v_lshlrev_b32_e32 v144, 16, v179
	v_and_b32_e32 v145, 0xffff0000, v179
	v_lshlrev_b32_e32 v146, 16, v180
	v_and_b32_e32 v147, 0xffff0000, v180
	v_lshlrev_b32_e32 v148, 16, v181
	v_and_b32_e32 v149, 0xffff0000, v181
	v_pk_mul_f32 v[92:93], v[92:93], v[142:143]
	v_pk_mul_f32 v[94:95], v[94:95], v[144:145]
	v_pk_mul_f32 v[88:89], v[88:89], v[146:147]
	v_pk_mul_f32 v[90:91], v[90:91], v[148:149]
	v_cvt_pk_bf16_f32 v92, v92, v93
	v_cvt_pk_bf16_f32 v93, v94, v95
	v_cvt_pk_bf16_f32 v94, v88, v89
	v_cvt_pk_bf16_f32 v95, v90, v91
	v_add_u32_e32 v141, 0x20000, v139
	global_store_dwordx4 v141, v[92:95], s[92:93]
	s_waitcnt vmcnt(15)
	v_lshlrev_b32_e32 v142, 16, v182
	v_and_b32_e32 v143, 0xffff0000, v182
	v_lshlrev_b32_e32 v144, 16, v183
	v_and_b32_e32 v145, 0xffff0000, v183
	v_lshlrev_b32_e32 v146, 16, v184
	v_and_b32_e32 v147, 0xffff0000, v184
	v_lshlrev_b32_e32 v148, 16, v185
	v_and_b32_e32 v149, 0xffff0000, v185
	v_pk_mul_f32 v[84:85], v[84:85], v[142:143]
	v_pk_mul_f32 v[86:87], v[86:87], v[144:145]
	v_pk_mul_f32 v[80:81], v[80:81], v[146:147]
	v_pk_mul_f32 v[82:83], v[82:83], v[148:149]
	v_cvt_pk_bf16_f32 v84, v84, v85
	v_cvt_pk_bf16_f32 v85, v86, v87
	v_cvt_pk_bf16_f32 v86, v80, v81
	v_cvt_pk_bf16_f32 v87, v82, v83
	v_add_u32_e32 v141, 0x20000, v139
	global_store_dwordx4 v141, v[84:87], s[92:93] offset:256
	s_waitcnt vmcnt(15)
	v_lshlrev_b32_e32 v142, 16, v186
	v_and_b32_e32 v143, 0xffff0000, v186
	v_lshlrev_b32_e32 v144, 16, v187
	v_and_b32_e32 v145, 0xffff0000, v187
	v_lshlrev_b32_e32 v146, 16, v188
	v_and_b32_e32 v147, 0xffff0000, v188
	v_lshlrev_b32_e32 v148, 16, v189
	v_and_b32_e32 v149, 0xffff0000, v189
	v_pk_mul_f32 v[76:77], v[76:77], v[142:143]
	v_pk_mul_f32 v[78:79], v[78:79], v[144:145]
	v_pk_mul_f32 v[72:73], v[72:73], v[146:147]
	v_pk_mul_f32 v[74:75], v[74:75], v[148:149]
	v_cvt_pk_bf16_f32 v76, v76, v77
	v_cvt_pk_bf16_f32 v77, v78, v79
	v_cvt_pk_bf16_f32 v78, v72, v73
	v_cvt_pk_bf16_f32 v79, v74, v75
	v_add_u32_e32 v141, 0x30000, v139
	global_store_dwordx4 v141, v[76:79], s[92:93]
	s_waitcnt vmcnt(15)
	v_lshlrev_b32_e32 v142, 16, v190
	v_and_b32_e32 v143, 0xffff0000, v190
	v_lshlrev_b32_e32 v144, 16, v191
	v_and_b32_e32 v145, 0xffff0000, v191
	v_lshlrev_b32_e32 v146, 16, v192
	v_and_b32_e32 v147, 0xffff0000, v192
	v_lshlrev_b32_e32 v148, 16, v193
	v_and_b32_e32 v149, 0xffff0000, v193
	v_pk_mul_f32 v[68:69], v[68:69], v[142:143]
	v_pk_mul_f32 v[70:71], v[70:71], v[144:145]
	v_pk_mul_f32 v[64:65], v[64:65], v[146:147]
	v_pk_mul_f32 v[66:67], v[66:67], v[148:149]
	v_cvt_pk_bf16_f32 v68, v68, v69
	v_cvt_pk_bf16_f32 v69, v70, v71
	v_cvt_pk_bf16_f32 v70, v64, v65
	v_cvt_pk_bf16_f32 v71, v66, v67
	v_add_u32_e32 v141, 0x30000, v139
	global_store_dwordx4 v141, v[68:71], s[92:93] offset:256
	s_waitcnt vmcnt(15)
	v_lshlrev_b32_e32 v142, 16, v194
	v_and_b32_e32 v143, 0xffff0000, v194
	v_lshlrev_b32_e32 v144, 16, v195
	v_and_b32_e32 v145, 0xffff0000, v195
	v_lshlrev_b32_e32 v146, 16, v196
	v_and_b32_e32 v147, 0xffff0000, v196
	v_lshlrev_b32_e32 v148, 16, v197
	v_and_b32_e32 v149, 0xffff0000, v197
	v_pk_mul_f32 v[60:61], v[60:61], v[142:143]
	v_pk_mul_f32 v[62:63], v[62:63], v[144:145]
	v_pk_mul_f32 v[56:57], v[56:57], v[146:147]
	v_pk_mul_f32 v[58:59], v[58:59], v[148:149]
	v_cvt_pk_bf16_f32 v60, v60, v61
	v_cvt_pk_bf16_f32 v61, v62, v63
	v_cvt_pk_bf16_f32 v62, v56, v57
	v_cvt_pk_bf16_f32 v63, v58, v59
	v_add_u32_e32 v141, 0x80000, v139
	global_store_dwordx4 v141, v[60:63], s[92:93]
	s_waitcnt vmcnt(15)
; __device__ __forceinline__ float bflo(unsigned w) { return __uint_as_float(w << 16); }
; __device__ __forceinline__ float bfhi(unsigned w) { return __uint_as_float(w & 0xffff0000u); }
; __device__ __forceinline__ u32x4 pack8u(f32x4 a, f32x4 b) { u32x4 w = {cvt_pk_bf16(a[0], a[1]), cvt_pk_bf16(a[2], a[3]), cvt_pk_bf16(b[0], b[1]), cvt_pk_bf16(b[2], b[3])}; return w; }
;     __device__ __forceinline__ void operator()(const AccT& acc, const Unit& u, int wr, int wc, int fr, int fq) const {
;     ...
; #pragma unroll
;                 for (int bj = 0; bj < 2; ++bj) {
;                     const int c8 = u.pn * 256 + bj * 128 + wc * 32 + fq * 8;
;                     const u32x4 gw = *(const u32x4*)(GATE + (size_t)row * 4096 + SECOND * 2048 + c8);
;                     const f32x4 g0 = {bflo(gw[0]), bfhi(gw[0]), bflo(gw[1]), bfhi(gw[1])}, g1 = {bflo(gw[2]), bfhi(gw[2]), bflo(gw[3]), bfhi(gw[3])};
;                     bf16_t* tp = (bf16_t*)TMP + (size_t)row * 2048 + c8;
;                     if (SECOND == 0) { *(u32x4*)tp = pack8u(g0 * acc[ai][bj][m][0], g1 * acc[ai][bj][m][1]); }
	v_lshlrev_b32_e32 v142, 16, v198
	v_and_b32_e32 v143, 0xffff0000, v198
	v_lshlrev_b32_e32 v144, 16, v199
	v_and_b32_e32 v145, 0xffff0000, v199
	v_lshlrev_b32_e32 v146, 16, v200
	v_and_b32_e32 v147, 0xffff0000, v200
	v_lshlrev_b32_e32 v148, 16, v201
	v_and_b32_e32 v149, 0xffff0000, v201
	v_pk_mul_f32 v[52:53], v[52:53], v[142:143]
	v_pk_mul_f32 v[54:55], v[54:55], v[144:145]
	v_pk_mul_f32 v[48:49], v[48:49], v[146:147]
	v_pk_mul_f32 v[50:51], v[50:51], v[148:149]
	v_cvt_pk_bf16_f32 v52, v52, v53
	v_cvt_pk_bf16_f32 v53, v54, v55
	v_cvt_pk_bf16_f32 v54, v48, v49
	v_cvt_pk_bf16_f32 v55, v50, v51
	v_add_u32_e32 v141, 0x80000, v139
	global_store_dwordx4 v141, v[52:55], s[92:93] offset:256
	s_waitcnt vmcnt(15)
	v_lshlrev_b32_e32 v142, 16, v202
	v_and_b32_e32 v143, 0xffff0000, v202
	v_lshlrev_b32_e32 v144, 16, v203
	v_and_b32_e32 v145, 0xffff0000, v203
	v_lshlrev_b32_e32 v146, 16, v204
	v_and_b32_e32 v147, 0xffff0000, v204
	v_lshlrev_b32_e32 v148, 16, v205
	v_and_b32_e32 v149, 0xffff0000, v205
	v_pk_mul_f32 v[44:45], v[44:45], v[142:143]
	v_pk_mul_f32 v[46:47], v[46:47], v[144:145]
	v_pk_mul_f32 v[40:41], v[40:41], v[146:147]
	v_pk_mul_f32 v[42:43], v[42:43], v[148:149]
	v_cvt_pk_bf16_f32 v44, v44, v45
	v_cvt_pk_bf16_f32 v45, v46, v47
	v_cvt_pk_bf16_f32 v46, v40, v41
	v_cvt_pk_bf16_f32 v47, v42, v43
	v_add_u32_e32 v141, 0x90000, v139
	global_store_dwordx4 v141, v[44:47], s[92:93]
	s_waitcnt vmcnt(15)
	v_lshlrev_b32_e32 v142, 16, v228
	v_and_b32_e32 v143, 0xffff0000, v228
	v_lshlrev_b32_e32 v144, 16, v229
	v_and_b32_e32 v145, 0xffff0000, v229
	v_lshlrev_b32_e32 v146, 16, v230
	v_and_b32_e32 v147, 0xffff0000, v230
	v_lshlrev_b32_e32 v148, 16, v231
	v_and_b32_e32 v149, 0xffff0000, v231
	v_pk_mul_f32 v[36:37], v[36:37], v[142:143]
	v_pk_mul_f32 v[38:39], v[38:39], v[144:145]
	v_pk_mul_f32 v[32:33], v[32:33], v[146:147]
	v_pk_mul_f32 v[34:35], v[34:35], v[148:149]
	v_cvt_pk_bf16_f32 v36, v36, v37
	v_cvt_pk_bf16_f32 v37, v38, v39
	v_cvt_pk_bf16_f32 v38, v32, v33
	v_cvt_pk_bf16_f32 v39, v34, v35
	v_add_u32_e32 v141, 0x90000, v139
	global_store_dwordx4 v141, v[36:39], s[92:93] offset:256
	s_waitcnt vmcnt(14)
	v_lshlrev_b32_e32 v142, 16, v162
	v_and_b32_e32 v143, 0xffff0000, v162
	v_lshlrev_b32_e32 v144, 16, v163
	v_and_b32_e32 v145, 0xffff0000, v163
	v_lshlrev_b32_e32 v146, 16, v164
	v_and_b32_e32 v147, 0xffff0000, v164
	v_lshlrev_b32_e32 v148, 16, v165
	v_and_b32_e32 v149, 0xffff0000, v165
	v_pk_mul_f32 v[28:29], v[28:29], v[142:143]
	v_pk_mul_f32 v[30:31], v[30:31], v[144:145]
	v_pk_mul_f32 v[24:25], v[24:25], v[146:147]
	v_pk_mul_f32 v[26:27], v[26:27], v[148:149]
	v_cvt_pk_bf16_f32 v28, v28, v29
	v_cvt_pk_bf16_f32 v29, v30, v31
	v_cvt_pk_bf16_f32 v30, v24, v25
	v_cvt_pk_bf16_f32 v31, v26, v27
	v_add_u32_e32 v141, 0xa0000, v139
	global_store_dwordx4 v141, v[28:31], s[92:93]
	s_waitcnt vmcnt(14)
	v_lshlrev_b32_e32 v142, 16, v120
	v_and_b32_e32 v143, 0xffff0000, v120
	v_lshlrev_b32_e32 v144, 16, v121
	v_and_b32_e32 v145, 0xffff0000, v121
	v_lshlrev_b32_e32 v146, 16, v122
	v_and_b32_e32 v147, 0xffff0000, v122
	v_lshlrev_b32_e32 v148, 16, v123
	v_and_b32_e32 v149, 0xffff0000, v123
	v_pk_mul_f32 v[20:21], v[20:21], v[142:143]
	v_pk_mul_f32 v[22:23], v[22:23], v[144:145]
	v_pk_mul_f32 v[16:17], v[16:17], v[146:147]
	v_pk_mul_f32 v[18:19], v[18:19], v[148:149]
	v_cvt_pk_bf16_f32 v20, v20, v21
	v_cvt_pk_bf16_f32 v21, v22, v23
	v_cvt_pk_bf16_f32 v22, v16, v17
	v_cvt_pk_bf16_f32 v23, v18, v19
	v_add_u32_e32 v141, 0xa0000, v139
	global_store_dwordx4 v141, v[20:23], s[92:93] offset:256
	s_waitcnt vmcnt(13)
	v_lshlrev_b32_e32 v142, 16, v166
	v_and_b32_e32 v143, 0xffff0000, v166
	v_lshlrev_b32_e32 v144, 16, v167
	v_and_b32_e32 v145, 0xffff0000, v167
	v_lshlrev_b32_e32 v146, 16, v168
	v_and_b32_e32 v147, 0xffff0000, v168
	v_lshlrev_b32_e32 v148, 16, v169
	v_and_b32_e32 v149, 0xffff0000, v169
	v_pk_mul_f32 v[12:13], v[12:13], v[142:143]
	v_pk_mul_f32 v[14:15], v[14:15], v[144:145]
	v_pk_mul_f32 v[8:9], v[8:9], v[146:147]
	v_pk_mul_f32 v[10:11], v[10:11], v[148:149]
	v_cvt_pk_bf16_f32 v12, v12, v13
	v_cvt_pk_bf16_f32 v13, v14, v15
	v_cvt_pk_bf16_f32 v14, v8, v9
	v_cvt_pk_bf16_f32 v15, v10, v11
	v_add_u32_e32 v141, 0xb0000, v139
	global_store_dwordx4 v141, v[12:15], s[92:93]
	s_waitcnt vmcnt(13)
	v_lshlrev_b32_e32 v142, 16, v112
	v_and_b32_e32 v143, 0xffff0000, v112
	v_lshlrev_b32_e32 v144, 16, v113
	v_and_b32_e32 v145, 0xffff0000, v113
	v_lshlrev_b32_e32 v146, 16, v114
	v_and_b32_e32 v147, 0xffff0000, v114
	v_lshlrev_b32_e32 v148, 16, v115
	v_and_b32_e32 v149, 0xffff0000, v115
	v_pk_mul_f32 v[4:5], v[4:5], v[142:143]
	v_pk_mul_f32 v[6:7], v[6:7], v[144:145]
	v_pk_mul_f32 v[0:1], v[0:1], v[146:147]
	v_pk_mul_f32 v[2:3], v[2:3], v[148:149]
	v_cvt_pk_bf16_f32 v4, v4, v5
	v_cvt_pk_bf16_f32 v5, v6, v7
	v_cvt_pk_bf16_f32 v6, v0, v1
	v_cvt_pk_bf16_f32 v7, v2, v3
	v_add_u32_e32 v141, 0xb0000, v139
	global_store_dwordx4 v141, v[4:7], s[92:93] offset:256
	s_mov_b64 s[26:27], -1
	s_mov_b64 s[42:43], exec
	s_mov_b64 vcc, 0
	s_branch .LBB0_203

; #define PG8_STAGE(bufoff, gbase, voff) do { _Pragma("unroll") for (int _i = 0; _i < 2; ++_i) \
;         __builtin_amdgcn_global_load_lds((const unsigned*)((const char*)(gbase) + (voff)[_i]), (LAS unsigned*)(lds + (bufoff) + ldsw + _i * 8192), 16, 0, 0); } while (0)
; #define PG8_LDA(dst, b, h) do { _Pragma("unroll") for (int m = 0; m < 4; ++m) _Pragma("unroll") for (int k = 0; k < 2; ++k) dst[m][k] = *(const LAS bf16x8*)(lds + PG8_SA(b, h) + aoff + m * 2048 + k * 1024); } while (0)
; #define PG8_LDB(dst, b, h) do { _Pragma("unroll") for (int n = 0; n < 2; ++n) _Pragma("unroll") for (int k = 0; k < 2; ++k) dst[n][k] = *(const LAS bf16x8*)(lds + PG8_SB(b, h) + boff + n * 2048 + k * 1024); } while (0)
; #define PG8_MMA(ai, bj, At, Bt) do { __builtin_amdgcn_s_setprio(1); _Pragma("unroll") for (int m = 0; m < 4; ++m) _Pragma("unroll") for (int n = 0; n < 2; ++n) _Pragma("unroll") for (int k = 0; k < 2; ++k) \
;         acc[ai][bj][m][n] = __builtin_amdgcn_mfma_f32_16x16x32_bf16(Bt[n][k], At[m][k], acc[ai][bj][m][n], 0, 0, 0); __builtin_amdgcn_s_setprio(0); } while (0)
; #define PG8_WAIT_V(n) asm volatile("s_waitcnt vmcnt(" #n ")" ::: "memory")
; #define PG8_WAIT_L(n) asm volatile("s_waitcnt lgkmcnt(" #n ")" ::: "memory")
; #define PG8_BAR __builtin_amdgcn_s_barrier()
; template <class Epi>
; __device__ __forceinline__ void gemm_phase(LAS unsigned char* lds, const Gemm g, const Epi& E) {
;     ...
;         for (int t = 0; t < nt; t += 2) {
;             const bool last = (t == nt - 2);
;             const char* a1 = cA + (size_t)(t + 1) * kstep;
;             const char* a2 = last ? nA : cA + (size_t)(t + 2) * kstep; const char* b2 = last ? nB : cB + (size_t)(t + 2) * kstep;
;             const char* a3 = a2 + kstep; const char* b3 = b2 + kstep;
;             PG8_LDB(B0, 0, 0); PG8_SCHED; PG8_LDA(At, 0, 0); PG8_STAGE(PG8_SA(1, 1), a1 + hstep, voffA);
;             PG8_WAIT_L(8); PG8_BAR; PG8_WAIT_L(0); PG8_MMA(0, 0, At, B0); PG8_BAR; PG8_SCHED;
;             PG8_LDB(B1, 0, 1); PG8_STAGE(PG8_SB(0, 0), b2, voffB);
;             PG8_BAR; PG8_WAIT_L(0); PG8_MMA(0, 1, At, B1); PG8_BAR;
;             PG8_LDA(At, 0, 1); PG8_STAGE(PG8_SA(0, 0), a2, voffA);
;             PG8_BAR; PG8_WAIT_L(0); PG8_MMA(1, 0, At, B0); PG8_BAR; PG8_SCHED;
;             PG8_STAGE(PG8_SB(0, 1), b2 + hstep, voffB);
;             PG8_WAIT_V(6); PG8_BAR; PG8_MMA(1, 1, At, B1); PG8_BAR;
.LBB0_499:
	s_add_u32 s28, s26, 0xfffe0080
	s_addc_u32 s29, s27, -1
	s_add_i32 s34, 0, 0x10000
	v_add_u32_e32 v156, s34, v159
	ds_read_b128 v[144:147], v156
	ds_read_b128 v[148:151], v156 offset:1024
	ds_read_b128 v[152:155], v156 offset:2048
	ds_read_b128 v[162:165], v156 offset:3072
	s_cmp_eq_u32 vcc_lo, 4
	s_cselect_b32 s37, s1, s29
	s_cselect_b32 s36, s31, s28
	s_cselect_b32 s29, s42, s65
	s_cselect_b32 s28, s43, s45
	s_add_i32 m0, s95, 0xc000
	ds_read_b128 v[166:169], v161
	ds_read_b128 v[170:173], v161 offset:1024
	ds_read_b128 v[174:177], v161 offset:2048
	ds_read_b128 v[178:181], v161 offset:3072
	ds_read_b128 v[182:185], v161 offset:4096
	ds_read_b128 v[186:189], v161 offset:5120
	ds_read_b128 v[190:193], v161 offset:6144
	ds_read_b128 v[194:197], v161 offset:7168
	global_load_lds_dwordx4 v140, s[26:27]
	s_add_i32 m0, s95, 0xe000
	s_nop 0
	global_load_lds_dwordx4 v142, s[26:27]
	s_waitcnt lgkmcnt(8)
	s_setprio 1
	s_barrier
	s_waitcnt lgkmcnt(0)
	v_mfma_f32_16x16x32_bf16 v[124:127], v[144:147], v[166:169], v[124:127]
	v_mfma_f32_16x16x32_bf16 v[120:123], v[152:155], v[166:169], v[120:123]
	v_mfma_f32_16x16x32_bf16 v[108:111], v[144:147], v[174:177], v[108:111]
	v_mfma_f32_16x16x32_bf16 v[104:107], v[152:155], v[174:177], v[104:107]
	v_mfma_f32_16x16x32_bf16 v[92:95], v[144:147], v[182:185], v[92:95]
	v_mfma_f32_16x16x32_bf16 v[88:91], v[152:155], v[182:185], v[88:91]
	v_mfma_f32_16x16x32_bf16 v[76:79], v[144:147], v[190:193], v[76:79]
	v_mfma_f32_16x16x32_bf16 v[72:75], v[152:155], v[190:193], v[72:75]
	v_mfma_f32_16x16x32_bf16 v[124:127], v[148:151], v[170:173], v[124:127]
	v_mfma_f32_16x16x32_bf16 v[120:123], v[162:165], v[170:173], v[120:123]
	v_mfma_f32_16x16x32_bf16 v[108:111], v[148:151], v[178:181], v[108:111]
	v_mfma_f32_16x16x32_bf16 v[104:107], v[162:165], v[178:181], v[104:107]
	v_mfma_f32_16x16x32_bf16 v[92:95], v[148:151], v[186:189], v[92:95]
	v_mfma_f32_16x16x32_bf16 v[88:91], v[162:165], v[186:189], v[88:91]
	v_mfma_f32_16x16x32_bf16 v[76:79], v[148:151], v[194:197], v[76:79]
	v_mfma_f32_16x16x32_bf16 v[72:75], v[162:165], v[194:197], v[72:75]
	s_barrier
	s_setprio 0
	s_add_i32 vcc_hi, 0, 0x14000
	v_add_u32_e32 v156, vcc_hi, v159
	s_add_i32 s34, s34, s83
	ds_read_b128 v[198:201], v156
	ds_read_b128 v[202:205], v156 offset:1024
	ds_read_b128 v[238:241], v156 offset:2048
	ds_read_b128 v[242:245], v156 offset:3072
	s_mov_b32 m0, s34
	s_nop 0
	global_load_lds_dwordx4 v130, s[28:29]
	s_add_i32 m0, s34, 0x2000
	s_nop 0
	global_load_lds_dwordx4 v134, s[28:29]
	s_setprio 1
	s_barrier
	s_waitcnt lgkmcnt(0)
	v_mfma_f32_16x16x32_bf16 v[116:119], v[198:201], v[166:169], v[116:119]
	v_mfma_f32_16x16x32_bf16 v[112:115], v[238:241], v[166:169], v[112:115]
	v_mfma_f32_16x16x32_bf16 v[100:103], v[198:201], v[174:177], v[100:103]
	v_mfma_f32_16x16x32_bf16 v[96:99], v[238:241], v[174:177], v[96:99]
	v_mfma_f32_16x16x32_bf16 v[84:87], v[198:201], v[182:185], v[84:87]
	v_mfma_f32_16x16x32_bf16 v[80:83], v[238:241], v[182:185], v[80:83]
	v_mfma_f32_16x16x32_bf16 v[68:71], v[198:201], v[190:193], v[68:71]
	v_mfma_f32_16x16x32_bf16 v[64:67], v[238:241], v[190:193], v[64:67]
	v_mfma_f32_16x16x32_bf16 v[116:119], v[202:205], v[170:173], v[116:119]
	v_mfma_f32_16x16x32_bf16 v[112:115], v[242:245], v[170:173], v[112:115]
	v_mfma_f32_16x16x32_bf16 v[100:103], v[202:205], v[178:181], v[100:103]
	v_mfma_f32_16x16x32_bf16 v[96:99], v[242:245], v[178:181], v[96:99]
	v_mfma_f32_16x16x32_bf16 v[84:87], v[202:205], v[186:189], v[84:87]
	v_mfma_f32_16x16x32_bf16 v[80:83], v[242:245], v[186:189], v[80:83]
	v_mfma_f32_16x16x32_bf16 v[68:71], v[202:205], v[194:197], v[68:71]
	v_mfma_f32_16x16x32_bf16 v[64:67], v[242:245], v[194:197], v[64:67]
	s_barrier
	s_setprio 0
	s_mov_b32 m0, s95
	ds_read_b128 v[166:169], v161 offset:16384
	ds_read_b128 v[170:173], v161 offset:17408
	ds_read_b128 v[174:177], v161 offset:18432
	ds_read_b128 v[178:181], v161 offset:19456
	ds_read_b128 v[182:185], v161 offset:20480
	ds_read_b128 v[186:189], v161 offset:21504
	ds_read_b128 v[190:193], v161 offset:22528
	ds_read_b128 v[194:197], v161 offset:23552
	global_load_lds_dwordx4 v128, s[36:37]
	s_mov_b32 m0, s82
	s_nop 0
	global_load_lds_dwordx4 v132, s[36:37]
	s_setprio 1
	s_barrier
	s_waitcnt lgkmcnt(0)
	v_mfma_f32_16x16x32_bf16 v[60:63], v[144:147], v[166:169], v[60:63]
	v_mfma_f32_16x16x32_bf16 v[56:59], v[152:155], v[166:169], v[56:59]
	v_mfma_f32_16x16x32_bf16 v[44:47], v[144:147], v[174:177], v[44:47]
	v_mfma_f32_16x16x32_bf16 v[40:43], v[152:155], v[174:177], v[40:43]
	v_mfma_f32_16x16x32_bf16 v[28:31], v[144:147], v[182:185], v[28:31]
	v_mfma_f32_16x16x32_bf16 v[24:27], v[152:155], v[182:185], v[24:27]
	v_mfma_f32_16x16x32_bf16 v[12:15], v[144:147], v[190:193], v[12:15]
	v_mfma_f32_16x16x32_bf16 v[8:11], v[152:155], v[190:193], v[8:11]
	v_mfma_f32_16x16x32_bf16 v[60:63], v[148:151], v[170:173], v[60:63]
	v_mfma_f32_16x16x32_bf16 v[56:59], v[162:165], v[170:173], v[56:59]
	v_mfma_f32_16x16x32_bf16 v[44:47], v[148:151], v[178:181], v[44:47]
	v_mfma_f32_16x16x32_bf16 v[40:43], v[162:165], v[178:181], v[40:43]
	v_mfma_f32_16x16x32_bf16 v[28:31], v[148:151], v[186:189], v[28:31]
	v_mfma_f32_16x16x32_bf16 v[24:27], v[162:165], v[186:189], v[24:27]
	v_mfma_f32_16x16x32_bf16 v[12:15], v[148:151], v[194:197], v[12:15]
	v_mfma_f32_16x16x32_bf16 v[8:11], v[162:165], v[194:197], v[8:11]
	s_barrier
	s_setprio 0
	s_add_u32 s34, s28, 0x20000
	s_addc_u32 s35, s29, 0
	s_add_i32 vcc_hi, vcc_hi, s83
	s_mov_b32 m0, vcc_hi
	s_nop 0
	global_load_lds_dwordx4 v130, s[34:35]
	s_add_i32 m0, vcc_hi, 0x2000
	s_nop 0
	global_load_lds_dwordx4 v134, s[34:35]
	s_waitcnt vmcnt(6)
	s_setprio 1
	s_barrier
; #define PG8_STAGE(bufoff, gbase, voff) do { _Pragma("unroll") for (int _i = 0; _i < 2; ++_i) \
;         __builtin_amdgcn_global_load_lds((const unsigned*)((const char*)(gbase) + (voff)[_i]), (LAS unsigned*)(lds + (bufoff) + ldsw + _i * 8192), 16, 0, 0); } while (0)
; #define PG8_LDA(dst, b, h) do { _Pragma("unroll") for (int m = 0; m < 4; ++m) _Pragma("unroll") for (int k = 0; k < 2; ++k) dst[m][k] = *(const LAS bf16x8*)(lds + PG8_SA(b, h) + aoff + m * 2048 + k * 1024); } while (0)
; #define PG8_LDB(dst, b, h) do { _Pragma("unroll") for (int n = 0; n < 2; ++n) _Pragma("unroll") for (int k = 0; k < 2; ++k) dst[n][k] = *(const LAS bf16x8*)(lds + PG8_SB(b, h) + boff + n * 2048 + k * 1024); } while (0)
; #define PG8_MMA(ai, bj, At, Bt) do { __builtin_amdgcn_s_setprio(1); _Pragma("unroll") for (int m = 0; m < 4; ++m) _Pragma("unroll") for (int n = 0; n < 2; ++n) _Pragma("unroll") for (int k = 0; k < 2; ++k) \
;         acc[ai][bj][m][n] = __builtin_amdgcn_mfma_f32_16x16x32_bf16(Bt[n][k], At[m][k], acc[ai][bj][m][n], 0, 0, 0); __builtin_amdgcn_s_setprio(0); } while (0)
; #define PG8_WAIT_V(n) asm volatile("s_waitcnt vmcnt(" #n ")" ::: "memory")
; #define PG8_WAIT_L(n) asm volatile("s_waitcnt lgkmcnt(" #n ")" ::: "memory")
; #define PG8_BAR __builtin_amdgcn_s_barrier()
; #define PG8_SCHED __builtin_amdgcn_sched_barrier(0)
; template <class Epi>
; __device__ __forceinline__ void gemm_phase(LAS unsigned char* lds, const Gemm g, const Epi& E) {
;     ...
;             PG8_WAIT_V(6); PG8_BAR; PG8_MMA(1, 1, At, B1); PG8_BAR;
;             PG8_LDB(B0, 1, 0); PG8_SCHED; PG8_LDA(At, 1, 0); PG8_STAGE(PG8_SA(0, 1), a2 + hstep, voffA);
;             PG8_WAIT_L(8); PG8_BAR; PG8_WAIT_L(0); PG8_MMA(0, 0, At, B0); PG8_BAR; PG8_SCHED;
;             PG8_LDB(B1, 1, 1); PG8_STAGE(PG8_SB(1, 0), b3, voffB);
;             PG8_BAR; PG8_WAIT_L(0); PG8_MMA(0, 1, At, B1); PG8_BAR;
;             PG8_LDA(At, 1, 1); PG8_STAGE(PG8_SA(1, 0), a3, voffA);
;             PG8_BAR; PG8_WAIT_L(0); PG8_MMA(1, 0, At, B0); PG8_BAR; PG8_SCHED;
;             PG8_STAGE(PG8_SB(1, 1), b3 + hstep, voffB);
	v_mfma_f32_16x16x32_bf16 v[52:55], v[198:201], v[166:169], v[52:55]
	v_mfma_f32_16x16x32_bf16 v[48:51], v[238:241], v[166:169], v[48:51]
	v_mfma_f32_16x16x32_bf16 v[36:39], v[198:201], v[174:177], v[36:39]
	v_mfma_f32_16x16x32_bf16 v[32:35], v[238:241], v[174:177], v[32:35]
	v_mfma_f32_16x16x32_bf16 v[20:23], v[198:201], v[182:185], v[20:23]
	v_mfma_f32_16x16x32_bf16 v[16:19], v[238:241], v[182:185], v[16:19]
	v_mfma_f32_16x16x32_bf16 v[4:7], v[198:201], v[190:193], v[4:7]
	v_mfma_f32_16x16x32_bf16 v[0:3], v[238:241], v[190:193], v[0:3]
	v_mfma_f32_16x16x32_bf16 v[52:55], v[202:205], v[170:173], v[52:55]
	v_mfma_f32_16x16x32_bf16 v[48:51], v[242:245], v[170:173], v[48:51]
	v_mfma_f32_16x16x32_bf16 v[36:39], v[202:205], v[178:181], v[36:39]
	v_mfma_f32_16x16x32_bf16 v[32:35], v[242:245], v[178:181], v[32:35]
	v_mfma_f32_16x16x32_bf16 v[20:23], v[202:205], v[186:189], v[20:23]
	v_mfma_f32_16x16x32_bf16 v[16:19], v[242:245], v[186:189], v[16:19]
	v_mfma_f32_16x16x32_bf16 v[4:7], v[202:205], v[194:197], v[4:7]
	v_mfma_f32_16x16x32_bf16 v[0:3], v[242:245], v[194:197], v[0:3]
	s_barrier
	s_setprio 0
	s_add_i32 vcc_hi, 0, 0x18000
	v_add_u32_e32 v162, vcc_hi, v159
	ds_read_b128 v[144:147], v162
	ds_read_b128 v[148:151], v162 offset:1024
	ds_read_b128 v[152:155], v162 offset:2048
	ds_read_b128 v[162:165], v162 offset:3072
	s_add_u32 s34, s36, 0x20000
	s_addc_u32 s35, s37, 0
	s_mov_b32 m0, s78
	ds_read_b128 v[166:169], v161 offset:32768
	ds_read_b128 v[170:173], v161 offset:33792
	ds_read_b128 v[174:177], v161 offset:34816
	ds_read_b128 v[178:181], v161 offset:35840
	ds_read_b128 v[182:185], v161 offset:36864
	ds_read_b128 v[186:189], v161 offset:37888
	ds_read_b128 v[190:193], v161 offset:38912
	ds_read_b128 v[194:197], v161 offset:39936
	global_load_lds_dwordx4 v128, s[34:35]
	s_mov_b32 m0, s76
	s_nop 0
	global_load_lds_dwordx4 v132, s[34:35]
	s_waitcnt lgkmcnt(8)
	s_setprio 1
	s_barrier
	s_waitcnt lgkmcnt(0)
	v_mfma_f32_16x16x32_bf16 v[124:127], v[144:147], v[166:169], v[124:127]
	v_mfma_f32_16x16x32_bf16 v[120:123], v[152:155], v[166:169], v[120:123]
	v_mfma_f32_16x16x32_bf16 v[108:111], v[144:147], v[174:177], v[108:111]
	v_mfma_f32_16x16x32_bf16 v[104:107], v[152:155], v[174:177], v[104:107]
	v_mfma_f32_16x16x32_bf16 v[92:95], v[144:147], v[182:185], v[92:95]
	v_mfma_f32_16x16x32_bf16 v[88:91], v[152:155], v[182:185], v[88:91]
	v_mfma_f32_16x16x32_bf16 v[76:79], v[144:147], v[190:193], v[76:79]
	v_mfma_f32_16x16x32_bf16 v[72:75], v[152:155], v[190:193], v[72:75]
	v_mfma_f32_16x16x32_bf16 v[124:127], v[148:151], v[170:173], v[124:127]
	v_mfma_f32_16x16x32_bf16 v[120:123], v[162:165], v[170:173], v[120:123]
	v_mfma_f32_16x16x32_bf16 v[108:111], v[148:151], v[178:181], v[108:111]
	v_mfma_f32_16x16x32_bf16 v[104:107], v[162:165], v[178:181], v[104:107]
	v_mfma_f32_16x16x32_bf16 v[92:95], v[148:151], v[186:189], v[92:95]
	v_mfma_f32_16x16x32_bf16 v[88:91], v[162:165], v[186:189], v[88:91]
	v_mfma_f32_16x16x32_bf16 v[76:79], v[148:151], v[194:197], v[76:79]
	v_mfma_f32_16x16x32_bf16 v[72:75], v[162:165], v[194:197], v[72:75]
	s_barrier
	s_setprio 0
	s_add_i32 s34, 0, 0x1c000
	s_add_i32 s35, vcc_hi, s83
	v_add_u32_e32 v208, s34, v159
	s_mov_b32 m0, s35
	ds_read_b128 v[198:201], v208
	ds_read_b128 v[202:205], v208 offset:1024
	ds_read_b128 v[238:241], v208 offset:2048
	ds_read_b128 v[242:245], v208 offset:3072
	s_add_u32 s98, s28, 0x80
	s_addc_u32 s99, s29, 0
	global_load_lds_dwordx4 v130, s[98:99]
	s_add_i32 m0, s35, 0x2000
	s_add_u32 s100, s28, 0x80
	s_addc_u32 s101, s29, 0
	global_load_lds_dwordx4 v134, s[100:101]
	s_setprio 1
	s_barrier
	s_waitcnt lgkmcnt(0)
	v_mfma_f32_16x16x32_bf16 v[116:119], v[198:201], v[166:169], v[116:119]
	v_mfma_f32_16x16x32_bf16 v[112:115], v[238:241], v[166:169], v[112:115]
	v_mfma_f32_16x16x32_bf16 v[100:103], v[198:201], v[174:177], v[100:103]
	v_mfma_f32_16x16x32_bf16 v[96:99], v[238:241], v[174:177], v[96:99]
	v_mfma_f32_16x16x32_bf16 v[84:87], v[198:201], v[182:185], v[84:87]
	v_mfma_f32_16x16x32_bf16 v[80:83], v[238:241], v[182:185], v[80:83]
	v_mfma_f32_16x16x32_bf16 v[68:71], v[198:201], v[190:193], v[68:71]
	v_mfma_f32_16x16x32_bf16 v[64:67], v[238:241], v[190:193], v[64:67]
	v_mfma_f32_16x16x32_bf16 v[116:119], v[202:205], v[170:173], v[116:119]
	v_mfma_f32_16x16x32_bf16 v[112:115], v[242:245], v[170:173], v[112:115]
	v_mfma_f32_16x16x32_bf16 v[100:103], v[202:205], v[178:181], v[100:103]
	v_mfma_f32_16x16x32_bf16 v[96:99], v[242:245], v[178:181], v[96:99]
	v_mfma_f32_16x16x32_bf16 v[84:87], v[202:205], v[186:189], v[84:87]
	v_mfma_f32_16x16x32_bf16 v[80:83], v[242:245], v[186:189], v[80:83]
	v_mfma_f32_16x16x32_bf16 v[68:71], v[202:205], v[194:197], v[68:71]
	v_mfma_f32_16x16x32_bf16 v[64:67], v[242:245], v[194:197], v[64:67]
	s_barrier
	s_setprio 0
	s_mov_b32 m0, s68
	ds_read_b128 v[166:169], v161 offset:49152
	ds_read_b128 v[170:173], v161 offset:50176
	ds_read_b128 v[174:177], v161 offset:51200
	ds_read_b128 v[178:181], v161 offset:52224
	ds_read_b128 v[182:185], v161 offset:53248
	ds_read_b128 v[186:189], v161 offset:54272
	ds_read_b128 v[190:193], v161 offset:55296
	ds_read_b128 v[194:197], v161 offset:56320
	s_add_u32 s98, s36, 0x80
	s_addc_u32 s99, s37, 0
	global_load_lds_dwordx4 v128, s[98:99]
	s_mov_b32 m0, s74
	s_add_u32 s100, s36, 0x80
	s_addc_u32 s101, s37, 0
	global_load_lds_dwordx4 v132, s[100:101]
	s_setprio 1
	s_barrier
; #define PG8_BAR __builtin_amdgcn_s_barrier()
; template <class Epi>
; __device__ __forceinline__ void gemm_phase(LAS unsigned char* lds, const Gemm g, const Epi& E) {
;     ...
;             PG8_LDB(B1, 1, 1); PG8_STAGE(PG8_SB(1, 0), b3, voffB);
;             PG8_BAR; PG8_WAIT_L(0); PG8_MMA(0, 1, At, B1); PG8_BAR;
;             PG8_LDA(At, 1, 1); PG8_STAGE(PG8_SA(1, 0), a3, voffA);
;             PG8_BAR; PG8_WAIT_L(0); PG8_MMA(1, 0, At, B0); PG8_BAR; PG8_SCHED;
;             PG8_STAGE(PG8_SB(1, 1), b3 + hstep, voffB);
;             PG8_WAIT_V(6); PG8_BAR; PG8_MMA(1, 1, At, B1); PG8_BAR;
;     __device__ __forceinline__ void operator()(const AccT& acc, const Unit& u, int wr, int wc, int fr, int fq) const {
;     ...
;                 const int row = u.pm * 256 + ai * 128 + wr * 64 + m * 16 + fr; const int b = row / SEQ, t = row % SEQ;
;                 const f32x4 s0 = *(const f32x4*)(SSQ + (size_t)row * 16 + mode * 8), s1 = *(const f32x4*)(SSQ + (size_t)row * 16 + mode * 8 + 4);
;                 const float ssq = (s0[0] + s0[1]) + (s0[2] + s0[3]) + (s1[0] + s1[1]) + (s1[2] + s1[3]);
;                 float rs = rsqrtf(ssq * (1.0f / 512.0f) + EPS);
;                 if (mode == 0) {
;                     rs *= (0.07216878364870322f * 1.4426950408889634f);
; #pragma unroll
;                     for (int bj = 0; bj < 2; ++bj) {
;                         const int c8 = u.pn * 256 + bj * 128 + wc * 32 + fq * 8; const int head = c8 / DQK, d0 = c8 % DQK;
;                         bf16_t* qp = Q + ((size_t)(b * NH + head) * SEQ + t) * DQK;
;                         const f32x4 v0 = acc[ai][bj][m][0] * rs, v1 = acc[ai][bj][m][1] * rs;
;                         if (d0 < 128) { *(u32x4*)(qp + d0) = pack8u(v0, v1); }
;                         else { const int i0 = 4 * ((d0 - 128) >> 3);
;                             const f32x4 cs = *(const f32x4*)(COS + (size_t)row * 32 + i0), sn = *(const f32x4*)(SIN + (size_t)row * 32 + i0);
;                             const f32x4 o1 = v0 * cs - v1 * sn, o2 = v1 * cs + v0 * sn;
;                             *(u32x2*)(qp + 128 + i0) = pack4u(o1); *(u32x2*)(qp + 160 + i0) = pack4u(o2); }
;                     }
;                 } else {
;                     const size_t bh = (size_t)(b * NH + u.pn) * SEQ + t; const int d = wc * 32 + fq * 8;
;                     *(u32x4*)(Kb + bh * DQK + d) = pack8u(acc[ai][0][m][0] * rs, acc[ai][0][m][1] * rs);
	s_waitcnt lgkmcnt(0)
	v_mfma_f32_16x16x32_bf16 v[60:63], v[144:147], v[166:169], v[60:63]
	v_mfma_f32_16x16x32_bf16 v[56:59], v[152:155], v[166:169], v[56:59]
	v_mfma_f32_16x16x32_bf16 v[44:47], v[144:147], v[174:177], v[44:47]
	v_mfma_f32_16x16x32_bf16 v[40:43], v[152:155], v[174:177], v[40:43]
	v_mfma_f32_16x16x32_bf16 v[28:31], v[144:147], v[182:185], v[28:31]
	v_mfma_f32_16x16x32_bf16 v[24:27], v[152:155], v[182:185], v[24:27]
	v_mfma_f32_16x16x32_bf16 v[12:15], v[144:147], v[190:193], v[12:15]
	v_mfma_f32_16x16x32_bf16 v[8:11], v[152:155], v[190:193], v[8:11]
	v_mfma_f32_16x16x32_bf16 v[60:63], v[148:151], v[170:173], v[60:63]
	v_mfma_f32_16x16x32_bf16 v[56:59], v[162:165], v[170:173], v[56:59]
	v_mfma_f32_16x16x32_bf16 v[44:47], v[148:151], v[178:181], v[44:47]
	v_mfma_f32_16x16x32_bf16 v[40:43], v[162:165], v[178:181], v[40:43]
	v_mfma_f32_16x16x32_bf16 v[28:31], v[148:151], v[186:189], v[28:31]
	v_mfma_f32_16x16x32_bf16 v[24:27], v[162:165], v[186:189], v[24:27]
	v_mfma_f32_16x16x32_bf16 v[12:15], v[148:151], v[194:197], v[12:15]
	v_mfma_f32_16x16x32_bf16 v[8:11], v[162:165], v[194:197], v[8:11]
	s_barrier
	s_setprio 0
	s_add_u32 s28, s28, 0x20080
	s_addc_u32 s29, s29, 0
	s_add_i32 s34, s34, s83
	s_mov_b32 m0, s34
	s_nop 0
	global_load_lds_dwordx4 v130, s[28:29]
	s_add_i32 m0, s34, 0x2000
	s_nop 0
	global_load_lds_dwordx4 v134, s[28:29]
	s_waitcnt vmcnt(6)
	s_setprio 1
	s_barrier
	v_mfma_f32_16x16x32_bf16 v[52:55], v[198:201], v[166:169], v[52:55]
	v_mfma_f32_16x16x32_bf16 v[48:51], v[238:241], v[166:169], v[48:51]
	v_mfma_f32_16x16x32_bf16 v[36:39], v[198:201], v[174:177], v[36:39]
	v_mfma_f32_16x16x32_bf16 v[32:35], v[238:241], v[174:177], v[32:35]
	v_mfma_f32_16x16x32_bf16 v[20:23], v[198:201], v[182:185], v[20:23]
	v_mfma_f32_16x16x32_bf16 v[16:19], v[238:241], v[182:185], v[16:19]
	v_mfma_f32_16x16x32_bf16 v[4:7], v[198:201], v[190:193], v[4:7]
	v_mfma_f32_16x16x32_bf16 v[0:3], v[238:241], v[190:193], v[0:3]
	v_mfma_f32_16x16x32_bf16 v[52:55], v[202:205], v[170:173], v[52:55]
	v_mfma_f32_16x16x32_bf16 v[48:51], v[242:245], v[170:173], v[48:51]
	v_mfma_f32_16x16x32_bf16 v[36:39], v[202:205], v[178:181], v[36:39]
	v_mfma_f32_16x16x32_bf16 v[32:35], v[242:245], v[178:181], v[32:35]
	v_mfma_f32_16x16x32_bf16 v[20:23], v[202:205], v[186:189], v[20:23]
	v_mfma_f32_16x16x32_bf16 v[16:19], v[242:245], v[186:189], v[16:19]
	v_mfma_f32_16x16x32_bf16 v[4:7], v[202:205], v[194:197], v[4:7]
	v_mfma_f32_16x16x32_bf16 v[0:3], v[242:245], v[194:197], v[0:3]
	s_barrier
	s_setprio 0
	s_add_i32 vcc_lo, vcc_lo, 2
	s_add_u32 s26, s26, 0x100
	s_addc_u32 s27, s27, 0
	s_add_u32 s45, s45, 0x100
	s_addc_u32 s65, s65, 0
	s_cmp_gt_u32 vcc_lo, 5
	s_cbranch_scc0 .LBB0_499
	v_lshl_add_u32 v144, s0, 8, v158
	v_lshlrev_b32_e32 v220, 6, v144
	v_add_u32_e32 v221, 0x2000, v220
	global_load_dwordx4 v[176:179], v220, s[48:49] offset:16
	global_load_dwordx4 v[180:183], v220, s[48:49]
	global_load_dwordx4 v[184:187], v220, s[48:49] offset:1040
	global_load_dwordx4 v[188:191], v220, s[48:49] offset:1024
	global_load_dwordx4 v[192:195], v220, s[48:49] offset:2064
	global_load_dwordx4 v[196:199], v220, s[48:49] offset:2048
	global_load_dwordx4 v[200:203], v220, s[48:49] offset:3088
	global_load_dwordx4 v[204:207], v220, s[48:49] offset:3072
	v_ashrrev_i32_e32 v145, 31, v144
	v_lshlrev_b64 v[150:151], 6, v[144:145]
	v_lshl_add_u64 v[154:155], s[48:49], 0, v[150:151]
	s_waitcnt vmcnt(6)
	v_mov_b32_e32 v150, v176
	v_mov_b32_e32 v151, v177
	v_mov_b32_e32 v152, v178
	v_mov_b32_e32 v153, v179
	s_nop 0
	v_mov_b32_e32 v154, v180
	v_mov_b32_e32 v155, v181
	v_mov_b32_e32 v156, v182
	v_mov_b32_e32 v157, v183
	global_load_dwordx4 v[176:179], v221, s[48:49] offset:16
	global_load_dwordx4 v[180:183], v221, s[48:49]
	v_lshrrev_b32_e32 v146, 21, v145
	v_add_u32_e32 v146, v144, v146
	v_ashrrev_i32_e32 v149, 11, v146
	v_mul_i32_i24_e32 v146, 0x800, v149
	v_sub_u32_e32 v146, v144, v146
	s_mov_b64 s[0:1], -1
	s_nop 0
	v_mov_b32_e32 v162, v155
	v_mov_b32_e32 v163, v156
	v_mov_b32_e32 v155, v157
	v_pk_add_f32 v[154:155], v[162:163], v[154:155]
	v_mov_b32_e32 v156, v152
	v_mov_b32_e32 v157, v150
	v_mov_b32_e32 v150, v153
	v_pk_add_f32 v[150:151], v[156:157], v[150:151]
	v_add_f32_e32 v147, v154, v155
	v_add_f32_e32 v147, v147, v151
	v_add_f32_e32 v147, v150, v147
	v_fmamk_f32 v147, v147, 0x3b000000, v223
	v_cmp_gt_f32_e32 vcc, s60, v147
	v_mul_f32_e32 v148, 0x4b800000, v147
	s_nop 0
	v_cndmask_b32_e32 v147, v147, v148, vcc
	v_rsq_f32_e32 v147, v147
	s_nop 0
	v_mul_f32_e32 v148, 0x45800000, v147
	v_cndmask_b32_e32 v148, v147, v148, vcc
	s_and_b64 vcc, exec, s[46:47]
	v_ashrrev_i32_e32 v147, 31, v146
	s_cbranch_vccz .LBB0_502
	v_lshl_add_u32 v150, v149, 3, s94
	v_ashrrev_i32_e32 v151, 31, v150
	v_lshlrev_b64 v[150:151], 11, v[150:151]
	v_lshl_add_u64 v[154:155], v[150:151], 0, v[146:147]
	v_pk_mul_f32 v[152:153], v[126:127], v[148:149] op_sel_hi:[1,0]
	v_pk_mul_f32 v[150:151], v[124:125], v[148:149] op_sel_hi:[1,0]
	v_pk_mul_f32 v[156:157], v[122:123], v[148:149] op_sel_hi:[1,0]
	v_pk_mul_f32 v[162:163], v[120:121], v[148:149] op_sel_hi:[1,0]
	v_cvt_pk_bf16_f32 v150, v150, v151
	v_cvt_pk_bf16_f32 v151, v152, v153
	v_cvt_pk_bf16_f32 v153, v156, v157
	v_mad_u64_u32 v[156:157], s[0:1], v154, s33, v[136:137]
	v_cvt_pk_bf16_f32 v152, v162, v163
	v_mad_i32_i24 v157, v155, s33, v157
	global_store_dwordx4 v[156:157], v[150:153], off
	v_pk_mul_f32 v[156:157], v[114:115], v[148:149] op_sel_hi:[1,0]
	v_pk_mul_f32 v[162:163], v[112:113], v[148:149] op_sel_hi:[1,0]
	v_pk_mul_f32 v[152:153], v[118:119], v[148:149] op_sel_hi:[1,0]
	v_pk_mul_f32 v[150:151], v[116:117], v[148:149] op_sel_hi:[1,0]
	v_lshlrev_b64 v[154:155], 8, v[154:155]
	v_cvt_pk_bf16_f32 v150, v150, v151
	v_cvt_pk_bf16_f32 v151, v152, v153
	v_cvt_pk_bf16_f32 v152, v162, v163
	v_cvt_pk_bf16_f32 v153, v156, v157
	v_lshl_add_u64 v[154:155], v[138:139], 0, v[154:155]
	global_store_dwordx4 v[154:155], v[150:153], off
	s_mov_b64 s[0:1], 0

; #define PG8_STAGE(bufoff, gbase, voff) do { _Pragma("unroll") for (int _i = 0; _i < 2; ++_i) \
;         __builtin_amdgcn_global_load_lds((const unsigned*)((const char*)(gbase) + (voff)[_i]), (LAS unsigned*)(lds + (bufoff) + ldsw + _i * 8192), 16, 0, 0); } while (0)
; #define PG8_LDA(dst, b, h) do { _Pragma("unroll") for (int m = 0; m < 4; ++m) _Pragma("unroll") for (int k = 0; k < 2; ++k) dst[m][k] = *(const LAS bf16x8*)(lds + PG8_SA(b, h) + aoff + m * 2048 + k * 1024); } while (0)
; #define PG8_LDB(dst, b, h) do { _Pragma("unroll") for (int n = 0; n < 2; ++n) _Pragma("unroll") for (int k = 0; k < 2; ++k) dst[n][k] = *(const LAS bf16x8*)(lds + PG8_SB(b, h) + boff + n * 2048 + k * 1024); } while (0)
; #define PG8_MMA(ai, bj, At, Bt) do { __builtin_amdgcn_s_setprio(1); _Pragma("unroll") for (int m = 0; m < 4; ++m) _Pragma("unroll") for (int n = 0; n < 2; ++n) _Pragma("unroll") for (int k = 0; k < 2; ++k) \
;         acc[ai][bj][m][n] = __builtin_amdgcn_mfma_f32_16x16x32_bf16(Bt[n][k], At[m][k], acc[ai][bj][m][n], 0, 0, 0); __builtin_amdgcn_s_setprio(0); } while (0)
; #define PG8_WAIT_V(n) asm volatile("s_waitcnt vmcnt(" #n ")" ::: "memory")
; #define PG8_WAIT_L(n) asm volatile("s_waitcnt lgkmcnt(" #n ")" ::: "memory")
; #define PG8_BAR __builtin_amdgcn_s_barrier()
; template <class Epi>
; __device__ __forceinline__ void gemm_phase(LAS unsigned char* lds, const Gemm g, const Epi& E) {
;     ...
;         for (int t = 0; t < nt; t += 2) {
;             const bool last = (t == nt - 2);
;             const char* a1 = cA + (size_t)(t + 1) * kstep;
;             const char* a2 = last ? nA : cA + (size_t)(t + 2) * kstep; const char* b2 = last ? nB : cB + (size_t)(t + 2) * kstep;
;             const char* a3 = a2 + kstep; const char* b3 = b2 + kstep;
;             PG8_LDB(B0, 0, 0); PG8_SCHED; PG8_LDA(At, 0, 0); PG8_STAGE(PG8_SA(1, 1), a1 + hstep, voffA);
;             PG8_WAIT_L(8); PG8_BAR; PG8_WAIT_L(0); PG8_MMA(0, 0, At, B0); PG8_BAR; PG8_SCHED;
;             PG8_LDB(B1, 0, 1); PG8_STAGE(PG8_SB(0, 0), b2, voffB);
;             PG8_BAR; PG8_WAIT_L(0); PG8_MMA(0, 1, At, B1); PG8_BAR;
;             PG8_LDA(At, 0, 1); PG8_STAGE(PG8_SA(0, 0), a2, voffA);
;             PG8_BAR; PG8_WAIT_L(0); PG8_MMA(1, 0, At, B0); PG8_BAR; PG8_SCHED;
;             PG8_STAGE(PG8_SB(0, 1), b2 + hstep, voffB);
;             PG8_WAIT_V(6); PG8_BAR; PG8_MMA(1, 1, At, B1); PG8_BAR;
.LBB0_672:
	s_add_u32 s28, s26, 0xfff80080
	s_addc_u32 s29, s27, -1
	s_add_i32 s34, 0, 0x10000
	v_add_u32_e32 v160, s34, v163
	ds_read_b128 v[128:131], v160
	ds_read_b128 v[132:135], v160 offset:1024
	ds_read_b128 v[156:159], v160 offset:2048
	ds_read_b128 v[166:169], v160 offset:3072
	s_cmp_eq_u32 s39, 28
	s_cselect_b32 s37, s1, s29
	s_cselect_b32 s36, s2, s28
	s_cselect_b32 s29, s3, s38
	s_cselect_b32 s28, s30, s31
	s_add_i32 m0, s96, 0xc000
	ds_read_b128 v[170:173], v164
	ds_read_b128 v[174:177], v164 offset:1024
	ds_read_b128 v[178:181], v164 offset:2048
	ds_read_b128 v[182:185], v164 offset:3072
	ds_read_b128 v[186:189], v164 offset:4096
	ds_read_b128 v[190:193], v164 offset:5120
	ds_read_b128 v[194:197], v164 offset:6144
	ds_read_b128 v[198:201], v164 offset:7168
	global_load_lds_dwordx4 v152, s[26:27]
	s_add_i32 m0, s96, 0xe000
	s_nop 0
	global_load_lds_dwordx4 v154, s[26:27]
	s_waitcnt lgkmcnt(8)
	s_setprio 1
	s_barrier
	s_waitcnt lgkmcnt(0)
	v_mfma_f32_16x16x32_bf16 v[124:127], v[128:131], v[170:173], v[124:127]
	v_mfma_f32_16x16x32_bf16 v[120:123], v[156:159], v[170:173], v[120:123]
	v_mfma_f32_16x16x32_bf16 v[108:111], v[128:131], v[178:181], v[108:111]
	v_mfma_f32_16x16x32_bf16 v[104:107], v[156:159], v[178:181], v[104:107]
	v_mfma_f32_16x16x32_bf16 v[92:95], v[128:131], v[186:189], v[92:95]
	v_mfma_f32_16x16x32_bf16 v[88:91], v[156:159], v[186:189], v[88:91]
	v_mfma_f32_16x16x32_bf16 v[76:79], v[128:131], v[194:197], v[76:79]
	v_mfma_f32_16x16x32_bf16 v[72:75], v[156:159], v[194:197], v[72:75]
	v_mfma_f32_16x16x32_bf16 v[124:127], v[132:135], v[174:177], v[124:127]
	v_mfma_f32_16x16x32_bf16 v[120:123], v[166:169], v[174:177], v[120:123]
	v_mfma_f32_16x16x32_bf16 v[108:111], v[132:135], v[182:185], v[108:111]
	v_mfma_f32_16x16x32_bf16 v[104:107], v[166:169], v[182:185], v[104:107]
	v_mfma_f32_16x16x32_bf16 v[92:95], v[132:135], v[190:193], v[92:95]
	v_mfma_f32_16x16x32_bf16 v[88:91], v[166:169], v[190:193], v[88:91]
	v_mfma_f32_16x16x32_bf16 v[76:79], v[132:135], v[198:201], v[76:79]
	v_mfma_f32_16x16x32_bf16 v[72:75], v[166:169], v[198:201], v[72:75]
	s_barrier
	s_setprio 0
	s_add_i32 s35, 0, 0x14000
	v_add_u32_e32 v160, s35, v163
	s_add_i32 s34, s34, s71
	ds_read_b128 v[202:205], v160
	ds_read_b128 v[238:241], v160 offset:1024
	ds_read_b128 v[242:245], v160 offset:2048
	ds_read_b128 v[246:249], v160 offset:3072
	s_mov_b32 m0, s34
	s_nop 0
	global_load_lds_dwordx4 v138, s[28:29]
	s_add_i32 m0, s34, 0x2000
	s_nop 0
	global_load_lds_dwordx4 v142, s[28:29]
	s_setprio 1
	s_barrier
	s_waitcnt lgkmcnt(0)
	v_mfma_f32_16x16x32_bf16 v[116:119], v[202:205], v[170:173], v[116:119]
	v_mfma_f32_16x16x32_bf16 v[112:115], v[242:245], v[170:173], v[112:115]
	v_mfma_f32_16x16x32_bf16 v[100:103], v[202:205], v[178:181], v[100:103]
	v_mfma_f32_16x16x32_bf16 v[96:99], v[242:245], v[178:181], v[96:99]
	v_mfma_f32_16x16x32_bf16 v[84:87], v[202:205], v[186:189], v[84:87]
	v_mfma_f32_16x16x32_bf16 v[80:83], v[242:245], v[186:189], v[80:83]
	v_mfma_f32_16x16x32_bf16 v[68:71], v[202:205], v[194:197], v[68:71]
	v_mfma_f32_16x16x32_bf16 v[64:67], v[242:245], v[194:197], v[64:67]
	v_mfma_f32_16x16x32_bf16 v[116:119], v[238:241], v[174:177], v[116:119]
	v_mfma_f32_16x16x32_bf16 v[112:115], v[246:249], v[174:177], v[112:115]
	v_mfma_f32_16x16x32_bf16 v[100:103], v[238:241], v[182:185], v[100:103]
	v_mfma_f32_16x16x32_bf16 v[96:99], v[246:249], v[182:185], v[96:99]
	v_mfma_f32_16x16x32_bf16 v[84:87], v[238:241], v[190:193], v[84:87]
	v_mfma_f32_16x16x32_bf16 v[80:83], v[246:249], v[190:193], v[80:83]
	v_mfma_f32_16x16x32_bf16 v[68:71], v[238:241], v[198:201], v[68:71]
	v_mfma_f32_16x16x32_bf16 v[64:67], v[246:249], v[198:201], v[64:67]
	s_barrier
	s_setprio 0
	s_mov_b32 m0, s96
	ds_read_b128 v[170:173], v164 offset:16384
	ds_read_b128 v[174:177], v164 offset:17408
	ds_read_b128 v[178:181], v164 offset:18432
	ds_read_b128 v[182:185], v164 offset:19456
	ds_read_b128 v[186:189], v164 offset:20480
	ds_read_b128 v[190:193], v164 offset:21504
	ds_read_b128 v[194:197], v164 offset:22528
	ds_read_b128 v[198:201], v164 offset:23552
	global_load_lds_dwordx4 v136, s[36:37]
	s_mov_b32 m0, s97
	s_nop 0
	global_load_lds_dwordx4 v140, s[36:37]
	s_setprio 1
	s_barrier
	s_waitcnt lgkmcnt(0)
	v_mfma_f32_16x16x32_bf16 v[60:63], v[128:131], v[170:173], v[60:63]
	v_mfma_f32_16x16x32_bf16 v[56:59], v[156:159], v[170:173], v[56:59]
	v_mfma_f32_16x16x32_bf16 v[44:47], v[128:131], v[178:181], v[44:47]
	v_mfma_f32_16x16x32_bf16 v[40:43], v[156:159], v[178:181], v[40:43]
	v_mfma_f32_16x16x32_bf16 v[28:31], v[128:131], v[186:189], v[28:31]
	v_mfma_f32_16x16x32_bf16 v[24:27], v[156:159], v[186:189], v[24:27]
	v_mfma_f32_16x16x32_bf16 v[12:15], v[128:131], v[194:197], v[12:15]
	v_mfma_f32_16x16x32_bf16 v[8:11], v[156:159], v[194:197], v[8:11]
	v_mfma_f32_16x16x32_bf16 v[60:63], v[132:135], v[174:177], v[60:63]
	v_mfma_f32_16x16x32_bf16 v[56:59], v[166:169], v[174:177], v[56:59]
	v_mfma_f32_16x16x32_bf16 v[44:47], v[132:135], v[182:185], v[44:47]
	v_mfma_f32_16x16x32_bf16 v[40:43], v[166:169], v[182:185], v[40:43]
	v_mfma_f32_16x16x32_bf16 v[28:31], v[132:135], v[190:193], v[28:31]
	v_mfma_f32_16x16x32_bf16 v[24:27], v[166:169], v[190:193], v[24:27]
	v_mfma_f32_16x16x32_bf16 v[12:15], v[132:135], v[198:201], v[12:15]
	v_mfma_f32_16x16x32_bf16 v[8:11], v[166:169], v[198:201], v[8:11]
	s_barrier
	s_setprio 0
	s_add_u32 s48, s28, 0x80000
	s_addc_u32 s49, s29, 0
	s_add_i32 s34, s35, s71
	s_mov_b32 m0, s34
	s_nop 0
	global_load_lds_dwordx4 v138, s[48:49]
	s_add_i32 m0, s34, 0x2000
	s_nop 0
	global_load_lds_dwordx4 v142, s[48:49]
	s_waitcnt vmcnt(6)
	s_setprio 1
	s_barrier
; #define PG8_STAGE(bufoff, gbase, voff) do { _Pragma("unroll") for (int _i = 0; _i < 2; ++_i) \
;         __builtin_amdgcn_global_load_lds((const unsigned*)((const char*)(gbase) + (voff)[_i]), (LAS unsigned*)(lds + (bufoff) + ldsw + _i * 8192), 16, 0, 0); } while (0)
; #define PG8_LDA(dst, b, h) do { _Pragma("unroll") for (int m = 0; m < 4; ++m) _Pragma("unroll") for (int k = 0; k < 2; ++k) dst[m][k] = *(const LAS bf16x8*)(lds + PG8_SA(b, h) + aoff + m * 2048 + k * 1024); } while (0)
; #define PG8_LDB(dst, b, h) do { _Pragma("unroll") for (int n = 0; n < 2; ++n) _Pragma("unroll") for (int k = 0; k < 2; ++k) dst[n][k] = *(const LAS bf16x8*)(lds + PG8_SB(b, h) + boff + n * 2048 + k * 1024); } while (0)
; #define PG8_MMA(ai, bj, At, Bt) do { __builtin_amdgcn_s_setprio(1); _Pragma("unroll") for (int m = 0; m < 4; ++m) _Pragma("unroll") for (int n = 0; n < 2; ++n) _Pragma("unroll") for (int k = 0; k < 2; ++k) \
;         acc[ai][bj][m][n] = __builtin_amdgcn_mfma_f32_16x16x32_bf16(Bt[n][k], At[m][k], acc[ai][bj][m][n], 0, 0, 0); __builtin_amdgcn_s_setprio(0); } while (0)
; #define PG8_WAIT_V(n) asm volatile("s_waitcnt vmcnt(" #n ")" ::: "memory")
; #define PG8_WAIT_L(n) asm volatile("s_waitcnt lgkmcnt(" #n ")" ::: "memory")
; #define PG8_BAR __builtin_amdgcn_s_barrier()
; #define PG8_SCHED __builtin_amdgcn_sched_barrier(0)
; template <class Epi>
; __device__ __forceinline__ void gemm_phase(LAS unsigned char* lds, const Gemm g, const Epi& E) {
;     ...
;             PG8_WAIT_V(6); PG8_BAR; PG8_MMA(1, 1, At, B1); PG8_BAR;
;             PG8_LDB(B0, 1, 0); PG8_SCHED; PG8_LDA(At, 1, 0); PG8_STAGE(PG8_SA(0, 1), a2 + hstep, voffA);
;             PG8_WAIT_L(8); PG8_BAR; PG8_WAIT_L(0); PG8_MMA(0, 0, At, B0); PG8_BAR; PG8_SCHED;
;             PG8_LDB(B1, 1, 1); PG8_STAGE(PG8_SB(1, 0), b3, voffB);
;             PG8_BAR; PG8_WAIT_L(0); PG8_MMA(0, 1, At, B1); PG8_BAR;
;             PG8_LDA(At, 1, 1); PG8_STAGE(PG8_SA(1, 0), a3, voffA);
;             PG8_BAR; PG8_WAIT_L(0); PG8_MMA(1, 0, At, B0); PG8_BAR; PG8_SCHED;
	v_mfma_f32_16x16x32_bf16 v[52:55], v[202:205], v[170:173], v[52:55]
	v_mfma_f32_16x16x32_bf16 v[48:51], v[242:245], v[170:173], v[48:51]
	v_mfma_f32_16x16x32_bf16 v[36:39], v[202:205], v[178:181], v[36:39]
	v_mfma_f32_16x16x32_bf16 v[32:35], v[242:245], v[178:181], v[32:35]
	v_mfma_f32_16x16x32_bf16 v[20:23], v[202:205], v[186:189], v[20:23]
	v_mfma_f32_16x16x32_bf16 v[16:19], v[242:245], v[186:189], v[16:19]
	v_mfma_f32_16x16x32_bf16 v[4:7], v[202:205], v[194:197], v[4:7]
	v_mfma_f32_16x16x32_bf16 v[0:3], v[242:245], v[194:197], v[0:3]
	v_mfma_f32_16x16x32_bf16 v[52:55], v[238:241], v[174:177], v[52:55]
	v_mfma_f32_16x16x32_bf16 v[48:51], v[246:249], v[174:177], v[48:51]
	v_mfma_f32_16x16x32_bf16 v[36:39], v[238:241], v[182:185], v[36:39]
	v_mfma_f32_16x16x32_bf16 v[32:35], v[246:249], v[182:185], v[32:35]
	v_mfma_f32_16x16x32_bf16 v[20:23], v[238:241], v[190:193], v[20:23]
	v_mfma_f32_16x16x32_bf16 v[16:19], v[246:249], v[190:193], v[16:19]
	v_mfma_f32_16x16x32_bf16 v[4:7], v[238:241], v[198:201], v[4:7]
	v_mfma_f32_16x16x32_bf16 v[0:3], v[246:249], v[198:201], v[0:3]
	s_barrier
	s_setprio 0
	s_add_i32 s34, 0, 0x18000
	v_add_u32_e32 v165, s34, v163
	ds_read_b128 v[128:131], v165
	ds_read_b128 v[132:135], v165 offset:1024
	ds_read_b128 v[156:159], v165 offset:2048
	ds_read_b128 v[166:169], v165 offset:3072
	s_add_u32 s36, s36, 0x80000
	s_addc_u32 s37, s37, 0
	s_mov_b32 m0, s70
	ds_read_b128 v[170:173], v164 offset:32768
	ds_read_b128 v[174:177], v164 offset:33792
	ds_read_b128 v[178:181], v164 offset:34816
	ds_read_b128 v[182:185], v164 offset:35840
	ds_read_b128 v[186:189], v164 offset:36864
	ds_read_b128 v[190:193], v164 offset:37888
	ds_read_b128 v[194:197], v164 offset:38912
	ds_read_b128 v[198:201], v164 offset:39936
	global_load_lds_dwordx4 v136, s[36:37]
	s_mov_b32 m0, s69
	s_nop 0
	global_load_lds_dwordx4 v140, s[36:37]
	s_waitcnt lgkmcnt(8)
	s_setprio 1
	s_barrier
	s_waitcnt lgkmcnt(0)
	v_mfma_f32_16x16x32_bf16 v[124:127], v[128:131], v[170:173], v[124:127]
	v_mfma_f32_16x16x32_bf16 v[120:123], v[156:159], v[170:173], v[120:123]
	v_mfma_f32_16x16x32_bf16 v[108:111], v[128:131], v[178:181], v[108:111]
	v_mfma_f32_16x16x32_bf16 v[104:107], v[156:159], v[178:181], v[104:107]
	v_mfma_f32_16x16x32_bf16 v[92:95], v[128:131], v[186:189], v[92:95]
	v_mfma_f32_16x16x32_bf16 v[88:91], v[156:159], v[186:189], v[88:91]
	v_mfma_f32_16x16x32_bf16 v[76:79], v[128:131], v[194:197], v[76:79]
	v_mfma_f32_16x16x32_bf16 v[72:75], v[156:159], v[194:197], v[72:75]
	v_mfma_f32_16x16x32_bf16 v[124:127], v[132:135], v[174:177], v[124:127]
	v_mfma_f32_16x16x32_bf16 v[120:123], v[166:169], v[174:177], v[120:123]
	v_mfma_f32_16x16x32_bf16 v[108:111], v[132:135], v[182:185], v[108:111]
	v_mfma_f32_16x16x32_bf16 v[104:107], v[166:169], v[182:185], v[104:107]
	v_mfma_f32_16x16x32_bf16 v[92:95], v[132:135], v[190:193], v[92:95]
	v_mfma_f32_16x16x32_bf16 v[88:91], v[166:169], v[190:193], v[88:91]
	v_mfma_f32_16x16x32_bf16 v[76:79], v[132:135], v[198:201], v[76:79]
	v_mfma_f32_16x16x32_bf16 v[72:75], v[166:169], v[198:201], v[72:75]
	s_barrier
	s_setprio 0
	s_add_i32 s35, 0, 0x1c000
	s_add_i32 s34, s34, s71
	v_add_u32_e32 v165, s35, v163
	s_mov_b32 m0, s34
	ds_read_b128 v[202:205], v165
	ds_read_b128 v[238:241], v165 offset:1024
	ds_read_b128 v[242:245], v165 offset:2048
	ds_read_b128 v[246:249], v165 offset:3072
	s_add_u32 s98, s28, 0x80
	s_addc_u32 s99, s29, 0
	global_load_lds_dwordx4 v138, s[98:99]
	s_add_i32 m0, s34, 0x2000
	s_add_u32 s100, s28, 0x80
	s_addc_u32 s101, s29, 0
	global_load_lds_dwordx4 v142, s[100:101]
	s_setprio 1
	s_barrier
	s_waitcnt lgkmcnt(0)
	v_mfma_f32_16x16x32_bf16 v[116:119], v[202:205], v[170:173], v[116:119]
	v_mfma_f32_16x16x32_bf16 v[112:115], v[242:245], v[170:173], v[112:115]
	v_mfma_f32_16x16x32_bf16 v[100:103], v[202:205], v[178:181], v[100:103]
	v_mfma_f32_16x16x32_bf16 v[96:99], v[242:245], v[178:181], v[96:99]
	v_mfma_f32_16x16x32_bf16 v[84:87], v[202:205], v[186:189], v[84:87]
	v_mfma_f32_16x16x32_bf16 v[80:83], v[242:245], v[186:189], v[80:83]
	v_mfma_f32_16x16x32_bf16 v[68:71], v[202:205], v[194:197], v[68:71]
	v_mfma_f32_16x16x32_bf16 v[64:67], v[242:245], v[194:197], v[64:67]
	v_mfma_f32_16x16x32_bf16 v[116:119], v[238:241], v[174:177], v[116:119]
	v_mfma_f32_16x16x32_bf16 v[112:115], v[246:249], v[174:177], v[112:115]
	v_mfma_f32_16x16x32_bf16 v[100:103], v[238:241], v[182:185], v[100:103]
	v_mfma_f32_16x16x32_bf16 v[96:99], v[246:249], v[182:185], v[96:99]
	v_mfma_f32_16x16x32_bf16 v[84:87], v[238:241], v[190:193], v[84:87]
	v_mfma_f32_16x16x32_bf16 v[80:83], v[246:249], v[190:193], v[80:83]
	v_mfma_f32_16x16x32_bf16 v[68:71], v[238:241], v[198:201], v[68:71]
	v_mfma_f32_16x16x32_bf16 v[64:67], v[246:249], v[198:201], v[64:67]
	s_barrier
; __device__ __forceinline__ float sigmoidf_(float x) { return __builtin_amdgcn_rcpf(1.0f + __expf(-x)); }
; template <class Epi>
; __device__ __forceinline__ void gemm_phase(LAS unsigned char* lds, const Gemm g, const Epi& E) {
;     ...
;             PG8_BAR; PG8_WAIT_L(0); PG8_MMA(1, 0, At, B0); PG8_BAR; PG8_SCHED;
;             PG8_STAGE(PG8_SB(1, 1), b3 + hstep, voffB);
;             PG8_WAIT_V(6); PG8_BAR; PG8_MMA(1, 1, At, B1); PG8_BAR;
;     __device__ __forceinline__ void operator()(const AccT& acc, const Unit& u, int wr, int wc, int fr, int fq) const {
;     ...
;         if (pn < 36) {
;             bf16_t* base; int ld;
;             if (pn < 4) { base = (pn < 2 ? CQ : CKV) + (pn & 1) * 256; ld = 512; }
;             else if (pn < 16) { base = QKVG + (pn - 4) * 256; ld = 3072; }
;             else if (pn < 20) { base = Z + (pn - 16) * 256; ld = 1024; }
;             else { base = GATE + (pn - 20) * 256; ld = 4096; }
;             base += wc * 32 + fq * 8;
; #pragma unroll
;             for (int ai = 0; ai < 2; ++ai)
; #pragma unroll
;                 for (int m = 0; m < 4; ++m) {
;                     const int row = u.pm * 256 + ai * 128 + wr * 64 + m * 16 + fr;
;                     bf16_t* dst = base + (size_t)row * ld; float s = 0.f;
; #pragma unroll
;                     for (int bj = 0; bj < 2; ++bj) { f32x4 v0 = acc[ai][bj][m][0], v1 = acc[ai][bj][m][1];
;                         if (pn < 4) s += (v0[0] * v0[0] + v0[1] * v0[1]) + (v0[2] * v0[2] + v0[3] * v0[3]) + (v1[0] * v1[0] + v1[1] * v1[1]) + (v1[2] * v1[2] + v1[3] * v1[3]);
;                         if (pn >= 20) {
; #pragma unroll
;                             for (int j = 0; j < 4; ++j) { v0[j] = sigmoidf_(v0[j]); v1[j] = sigmoidf_(v1[j]); } }
;                         *(u32x4*)(dst + bj * 128) = pack8u(v0, v1); }
;                     if (pn < 4) { s += swz<16>(s); s = halfsum(s); if (fq == 0) SSQ[(size_t)row * 16 + pn * 4 + wc] = s; }
;                 }
;         } else {
;             const int g8 = wc * 4 + fq;
; #pragma unroll
;             for (int ai = 0; ai < 2; ++ai)
; #pragma unroll
;                 for (int m = 0; m < 4; ++m) {
;                     const int row = u.pm * 256 + ai * 128 + wr * 64 + m * 16 + fr;
;                     const f32x4 v0 = acc[ai][0][m][0], v1 = acc[ai][0][m][1];
;                     if (g8 < 8) {
;                         const int i0 = 4 * g8;
	s_setprio 0
	s_mov_b32 m0, s68
	ds_read_b128 v[170:173], v164 offset:49152
	ds_read_b128 v[174:177], v164 offset:50176
	ds_read_b128 v[178:181], v164 offset:51200
	ds_read_b128 v[182:185], v164 offset:52224
	ds_read_b128 v[186:189], v164 offset:53248
	ds_read_b128 v[190:193], v164 offset:54272
	ds_read_b128 v[194:197], v164 offset:55296
	ds_read_b128 v[198:201], v164 offset:56320
	s_add_u32 s98, s36, 0xfff80080
	s_addc_u32 s99, s37, -1
	global_load_lds_dwordx4 v136, s[98:99]
	s_mov_b32 m0, s83
	s_add_u32 s100, s36, 0xfff80080
	s_addc_u32 s101, s37, -1
	global_load_lds_dwordx4 v140, s[100:101]
	s_setprio 1
	s_barrier
	s_waitcnt lgkmcnt(0)
	v_mfma_f32_16x16x32_bf16 v[60:63], v[128:131], v[170:173], v[60:63]
	v_mfma_f32_16x16x32_bf16 v[56:59], v[156:159], v[170:173], v[56:59]
	v_mfma_f32_16x16x32_bf16 v[44:47], v[128:131], v[178:181], v[44:47]
	v_mfma_f32_16x16x32_bf16 v[40:43], v[156:159], v[178:181], v[40:43]
	v_mfma_f32_16x16x32_bf16 v[28:31], v[128:131], v[186:189], v[28:31]
	v_mfma_f32_16x16x32_bf16 v[24:27], v[156:159], v[186:189], v[24:27]
	v_mfma_f32_16x16x32_bf16 v[12:15], v[128:131], v[194:197], v[12:15]
	v_mfma_f32_16x16x32_bf16 v[8:11], v[156:159], v[194:197], v[8:11]
	v_mfma_f32_16x16x32_bf16 v[60:63], v[132:135], v[174:177], v[60:63]
	v_mfma_f32_16x16x32_bf16 v[56:59], v[166:169], v[174:177], v[56:59]
	v_mfma_f32_16x16x32_bf16 v[44:47], v[132:135], v[182:185], v[44:47]
	v_mfma_f32_16x16x32_bf16 v[40:43], v[166:169], v[182:185], v[40:43]
	v_mfma_f32_16x16x32_bf16 v[28:31], v[132:135], v[190:193], v[28:31]
	v_mfma_f32_16x16x32_bf16 v[24:27], v[166:169], v[190:193], v[24:27]
	v_mfma_f32_16x16x32_bf16 v[12:15], v[132:135], v[198:201], v[12:15]
	v_mfma_f32_16x16x32_bf16 v[8:11], v[166:169], v[198:201], v[8:11]
	s_barrier
	s_setprio 0
	s_add_u32 s28, s28, 0x80080
	s_addc_u32 s29, s29, 0
	s_add_i32 s34, s35, s71
	s_mov_b32 m0, s34
	s_nop 0
	global_load_lds_dwordx4 v138, s[28:29]
	s_add_i32 m0, s34, 0x2000
	s_nop 0
	global_load_lds_dwordx4 v142, s[28:29]
	s_waitcnt vmcnt(6)
	s_setprio 1
	s_barrier
	v_mfma_f32_16x16x32_bf16 v[52:55], v[202:205], v[170:173], v[52:55]
	v_mfma_f32_16x16x32_bf16 v[48:51], v[242:245], v[170:173], v[48:51]
	v_mfma_f32_16x16x32_bf16 v[36:39], v[202:205], v[178:181], v[36:39]
	v_mfma_f32_16x16x32_bf16 v[32:35], v[242:245], v[178:181], v[32:35]
	v_mfma_f32_16x16x32_bf16 v[20:23], v[202:205], v[186:189], v[20:23]
	v_mfma_f32_16x16x32_bf16 v[16:19], v[242:245], v[186:189], v[16:19]
	v_mfma_f32_16x16x32_bf16 v[4:7], v[202:205], v[194:197], v[4:7]
	v_mfma_f32_16x16x32_bf16 v[0:3], v[242:245], v[194:197], v[0:3]
	v_mfma_f32_16x16x32_bf16 v[52:55], v[238:241], v[174:177], v[52:55]
	v_mfma_f32_16x16x32_bf16 v[48:51], v[246:249], v[174:177], v[48:51]
	v_mfma_f32_16x16x32_bf16 v[36:39], v[238:241], v[182:185], v[36:39]
	v_mfma_f32_16x16x32_bf16 v[32:35], v[246:249], v[182:185], v[32:35]
	v_mfma_f32_16x16x32_bf16 v[20:23], v[238:241], v[190:193], v[20:23]
	v_mfma_f32_16x16x32_bf16 v[16:19], v[246:249], v[190:193], v[16:19]
	v_mfma_f32_16x16x32_bf16 v[4:7], v[238:241], v[198:201], v[4:7]
	v_mfma_f32_16x16x32_bf16 v[0:3], v[246:249], v[198:201], v[0:3]
	s_barrier
	s_setprio 0
	s_add_i32 s39, s39, 2
	s_add_u32 s26, s26, 0x100
	s_addc_u32 s27, s27, 0
	s_add_u32 s31, s31, 0x100
	s_addc_u32 s38, s38, 0
	s_cmp_gt_u32 s39, 29
	s_cbranch_scc0 .LBB0_672
	s_mov_b64 s[26:27], -1
	s_cmp_gt_i32 s64, 35
	v_lshl_add_u32 v156, s46, 8, v162
	s_movk_i32 s95, 0x1ff
	s_cbranch_scc0 .LBB0_723
	v_mov_b32_e32 v220, v156
	v_ashrrev_i32_e32 v221, 31, v156
	v_lshlrev_b64 v[220:221], 7, v[220:221]
	v_lshl_add_u64 v[200:201], v[146:147], 0, v[220:221]
	v_lshl_add_u64 v[202:203], v[148:149], 0, v[220:221]
	s_mov_b64 s[98:99], 0x1000
	v_lshl_add_u64 v[204:205], v[200:201], 0, s[98:99]
	v_lshl_add_u64 v[206:207], v[202:203], 0, s[98:99]
	global_load_dwordx4 v[168:171], v[200:201], off
	global_load_dwordx4 v[172:175], v[202:203], off
	global_load_dwordx4 v[176:179], v[200:201], off offset:2048
	global_load_dwordx4 v[180:183], v[202:203], off offset:2048
	global_load_dwordx4 v[184:187], v[204:205], off
	global_load_dwordx4 v[188:191], v[206:207], off
	global_load_dwordx4 v[192:195], v[204:205], off offset:2048
	global_load_dwordx4 v[196:199], v[206:207], off offset:2048
	s_mov_b64 s[98:99], 0x4000
	v_lshl_add_u64 v[200:201], v[200:201], 0, s[98:99]
	v_lshl_add_u64 v[202:203], v[202:203], 0, s[98:99]
	v_lshl_add_u64 v[204:205], v[204:205], 0, s[98:99]
	v_lshl_add_u64 v[206:207], v[206:207], 0, s[98:99]
	s_and_b64 vcc, exec, s[52:53]
	s_cbranch_vccz .LBB0_678
	s_and_saveexec_b64 s[26:27], s[54:55]
	s_cbranch_execz .LBB0_677
	v_ashrrev_i32_e32 v157, 31, v156
	v_lshlrev_b64 v[128:129], 6, v[156:157]
	v_lshl_add_u64 v[128:129], v[144:145], 0, v[128:129]
	global_store_dwordx4 v[128:129], v[124:127], off offset:-256
	global_store_dwordx4 v[128:129], v[120:123], off offset:-240

; #define PG8_STAGE(bufoff, gbase, voff) do { _Pragma("unroll") for (int _i = 0; _i < 2; ++_i) \
;         __builtin_amdgcn_global_load_lds((const unsigned*)((const char*)(gbase) + (voff)[_i]), (LAS unsigned*)(lds + (bufoff) + ldsw + _i * 8192), 16, 0, 0); } while (0)
; #define PG8_LDA(dst, b, h) do { _Pragma("unroll") for (int m = 0; m < 4; ++m) _Pragma("unroll") for (int k = 0; k < 2; ++k) dst[m][k] = *(const LAS bf16x8*)(lds + PG8_SA(b, h) + aoff + m * 2048 + k * 1024); } while (0)
; #define PG8_LDB(dst, b, h) do { _Pragma("unroll") for (int n = 0; n < 2; ++n) _Pragma("unroll") for (int k = 0; k < 2; ++k) dst[n][k] = *(const LAS bf16x8*)(lds + PG8_SB(b, h) + boff + n * 2048 + k * 1024); } while (0)
; #define PG8_MMA(ai, bj, At, Bt) do { __builtin_amdgcn_s_setprio(1); _Pragma("unroll") for (int m = 0; m < 4; ++m) _Pragma("unroll") for (int n = 0; n < 2; ++n) _Pragma("unroll") for (int k = 0; k < 2; ++k) \
;         acc[ai][bj][m][n] = __builtin_amdgcn_mfma_f32_16x16x32_bf16(Bt[n][k], At[m][k], acc[ai][bj][m][n], 0, 0, 0); __builtin_amdgcn_s_setprio(0); } while (0)
; #define PG8_WAIT_V(n) asm volatile("s_waitcnt vmcnt(" #n ")" ::: "memory")
; #define PG8_WAIT_L(n) asm volatile("s_waitcnt lgkmcnt(" #n ")" ::: "memory")
; #define PG8_BAR __builtin_amdgcn_s_barrier()
; template <class Epi>
; __device__ __forceinline__ void gemm_phase(LAS unsigned char* lds, const Gemm g, const Epi& E) {
;     ...
;         for (int t = 0; t < nt; t += 2) {
;             const bool last = (t == nt - 2);
;             const char* a1 = cA + (size_t)(t + 1) * kstep;
;             const char* a2 = last ? nA : cA + (size_t)(t + 2) * kstep; const char* b2 = last ? nB : cB + (size_t)(t + 2) * kstep;
;             const char* a3 = a2 + kstep; const char* b3 = b2 + kstep;
;             PG8_LDB(B0, 0, 0); PG8_SCHED; PG8_LDA(At, 0, 0); PG8_STAGE(PG8_SA(1, 1), a1 + hstep, voffA);
;             PG8_WAIT_L(8); PG8_BAR; PG8_WAIT_L(0); PG8_MMA(0, 0, At, B0); PG8_BAR; PG8_SCHED;
;             PG8_LDB(B1, 0, 1); PG8_STAGE(PG8_SB(0, 0), b2, voffB);
;             PG8_BAR; PG8_WAIT_L(0); PG8_MMA(0, 1, At, B1); PG8_BAR;
;             PG8_LDA(At, 0, 1); PG8_STAGE(PG8_SA(0, 0), a2, voffA);
;             PG8_BAR; PG8_WAIT_L(0); PG8_MMA(1, 0, At, B0); PG8_BAR; PG8_SCHED;
;             PG8_STAGE(PG8_SB(0, 1), b2 + hstep, voffB);
;             PG8_WAIT_V(6); PG8_BAR; PG8_MMA(1, 1, At, B1); PG8_BAR;
.LBB0_873:
	s_add_u32 s28, s26, 0x100
	s_addc_u32 s29, s27, 0
	s_add_i32 s34, 0, 0x10000
	v_add_u32_e32 v140, s34, v160
	ds_read_b128 v[128:131], v140
	ds_read_b128 v[132:135], v140 offset:1024
	ds_read_b128 v[136:139], v140 offset:2048
	ds_read_b128 v[140:143], v140 offset:3072
	s_cmpk_eq_i32 s82, 0x54
	s_cselect_b32 s39, s1, s29
	s_cselect_b32 s38, s0, s28
	s_cselect_b32 s37, s43, s79
	s_cselect_b32 s36, s42, s78
	s_add_i32 m0, s44, 0xc000
	ds_read_b128 v[156:159], v161
	ds_read_b128 v[164:167], v161 offset:1024
	ds_read_b128 v[168:171], v161 offset:2048
	ds_read_b128 v[172:175], v161 offset:3072
	ds_read_b128 v[176:179], v161 offset:4096
	ds_read_b128 v[180:183], v161 offset:5120
	ds_read_b128 v[184:187], v161 offset:6144
	ds_read_b128 v[188:191], v161 offset:7168
	global_load_lds_dwordx4 v152, s[26:27]
	s_add_i32 m0, s44, 0xe000
	s_nop 0
	global_load_lds_dwordx4 v154, s[26:27]
	s_waitcnt lgkmcnt(8)
	s_setprio 1
	s_barrier
	s_waitcnt lgkmcnt(0)
	v_mfma_f32_16x16x32_bf16 v[124:127], v[128:131], v[156:159], v[124:127]
	v_mfma_f32_16x16x32_bf16 v[120:123], v[136:139], v[156:159], v[120:123]
	v_mfma_f32_16x16x32_bf16 v[108:111], v[128:131], v[168:171], v[108:111]
	v_mfma_f32_16x16x32_bf16 v[104:107], v[136:139], v[168:171], v[104:107]
	v_mfma_f32_16x16x32_bf16 v[92:95], v[128:131], v[176:179], v[92:95]
	v_mfma_f32_16x16x32_bf16 v[88:91], v[136:139], v[176:179], v[88:91]
	v_mfma_f32_16x16x32_bf16 v[76:79], v[128:131], v[184:187], v[76:79]
	v_mfma_f32_16x16x32_bf16 v[72:75], v[136:139], v[184:187], v[72:75]
	v_mfma_f32_16x16x32_bf16 v[124:127], v[132:135], v[164:167], v[124:127]
	v_mfma_f32_16x16x32_bf16 v[120:123], v[140:143], v[164:167], v[120:123]
	v_mfma_f32_16x16x32_bf16 v[108:111], v[132:135], v[172:175], v[108:111]
	v_mfma_f32_16x16x32_bf16 v[104:107], v[140:143], v[172:175], v[104:107]
	v_mfma_f32_16x16x32_bf16 v[92:95], v[132:135], v[180:183], v[92:95]
	v_mfma_f32_16x16x32_bf16 v[88:91], v[140:143], v[180:183], v[88:91]
	v_mfma_f32_16x16x32_bf16 v[76:79], v[132:135], v[188:191], v[76:79]
	v_mfma_f32_16x16x32_bf16 v[72:75], v[140:143], v[188:191], v[72:75]
	s_barrier
	s_setprio 0
	s_add_i32 s35, 0, 0x14000
	s_add_i32 s26, s34, s31
	v_add_u32_e32 v163, s35, v160
	s_mov_b32 m0, s26
	ds_read_b128 v[192:195], v163
	ds_read_b128 v[196:199], v163 offset:1024
	ds_read_b128 v[200:203], v163 offset:2048
	ds_read_b128 v[204:207], v163 offset:3072
	global_load_lds_dwordx4 v208, s[36:37]
	s_add_i32 m0, s26, 0x2000
	s_nop 0
	global_load_lds_dwordx4 v148, s[36:37]
	s_setprio 1
	s_barrier
	s_waitcnt lgkmcnt(0)
	v_mfma_f32_16x16x32_bf16 v[116:119], v[192:195], v[156:159], v[116:119]
	v_mfma_f32_16x16x32_bf16 v[112:115], v[200:203], v[156:159], v[112:115]
	v_mfma_f32_16x16x32_bf16 v[100:103], v[192:195], v[168:171], v[100:103]
	v_mfma_f32_16x16x32_bf16 v[96:99], v[200:203], v[168:171], v[96:99]
	v_mfma_f32_16x16x32_bf16 v[84:87], v[192:195], v[176:179], v[84:87]
	v_mfma_f32_16x16x32_bf16 v[80:83], v[200:203], v[176:179], v[80:83]
	v_mfma_f32_16x16x32_bf16 v[68:71], v[192:195], v[184:187], v[68:71]
	v_mfma_f32_16x16x32_bf16 v[64:67], v[200:203], v[184:187], v[64:67]
	v_mfma_f32_16x16x32_bf16 v[116:119], v[196:199], v[164:167], v[116:119]
	v_mfma_f32_16x16x32_bf16 v[112:115], v[204:207], v[164:167], v[112:115]
	v_mfma_f32_16x16x32_bf16 v[100:103], v[196:199], v[172:175], v[100:103]
	v_mfma_f32_16x16x32_bf16 v[96:99], v[204:207], v[172:175], v[96:99]
	v_mfma_f32_16x16x32_bf16 v[84:87], v[196:199], v[180:183], v[84:87]
	v_mfma_f32_16x16x32_bf16 v[80:83], v[204:207], v[180:183], v[80:83]
	v_mfma_f32_16x16x32_bf16 v[68:71], v[196:199], v[188:191], v[68:71]
	v_mfma_f32_16x16x32_bf16 v[64:67], v[204:207], v[188:191], v[64:67]
	s_barrier
	s_setprio 0
	s_mov_b32 m0, s44
	ds_read_b128 v[156:159], v161 offset:16384
	ds_read_b128 v[164:167], v161 offset:17408
	ds_read_b128 v[168:171], v161 offset:18432
	ds_read_b128 v[172:175], v161 offset:19456
	ds_read_b128 v[176:179], v161 offset:20480
	ds_read_b128 v[180:183], v161 offset:21504
	ds_read_b128 v[184:187], v161 offset:22528
	ds_read_b128 v[188:191], v161 offset:23552
	global_load_lds_dwordx4 v144, s[38:39]
	s_mov_b32 m0, s45
	s_nop 0
	global_load_lds_dwordx4 v146, s[38:39]
	s_setprio 1
	s_barrier
	s_waitcnt lgkmcnt(0)
	v_mfma_f32_16x16x32_bf16 v[60:63], v[128:131], v[156:159], v[60:63]
	v_mfma_f32_16x16x32_bf16 v[56:59], v[136:139], v[156:159], v[56:59]
	v_mfma_f32_16x16x32_bf16 v[44:47], v[128:131], v[168:171], v[44:47]
	v_mfma_f32_16x16x32_bf16 v[40:43], v[136:139], v[168:171], v[40:43]
	v_mfma_f32_16x16x32_bf16 v[28:31], v[128:131], v[176:179], v[28:31]
	v_mfma_f32_16x16x32_bf16 v[24:27], v[136:139], v[176:179], v[24:27]
	v_mfma_f32_16x16x32_bf16 v[12:15], v[128:131], v[184:187], v[12:15]
	v_mfma_f32_16x16x32_bf16 v[8:11], v[136:139], v[184:187], v[8:11]
	v_mfma_f32_16x16x32_bf16 v[60:63], v[132:135], v[164:167], v[60:63]
	v_mfma_f32_16x16x32_bf16 v[56:59], v[140:143], v[164:167], v[56:59]
	v_mfma_f32_16x16x32_bf16 v[44:47], v[132:135], v[172:175], v[44:47]
	v_mfma_f32_16x16x32_bf16 v[40:43], v[140:143], v[172:175], v[40:43]
	v_mfma_f32_16x16x32_bf16 v[28:31], v[132:135], v[180:183], v[28:31]
	v_mfma_f32_16x16x32_bf16 v[24:27], v[140:143], v[180:183], v[24:27]
	v_mfma_f32_16x16x32_bf16 v[12:15], v[132:135], v[188:191], v[12:15]
	v_mfma_f32_16x16x32_bf16 v[8:11], v[140:143], v[188:191], v[8:11]
	s_barrier
	s_setprio 0
	s_add_u32 s26, s36, 0x160000
	s_addc_u32 s27, s37, 0
	s_add_i32 s34, s35, s31
	s_mov_b32 m0, s34
	s_nop 0
	global_load_lds_dwordx4 v208, s[26:27]
	s_add_i32 m0, s34, 0x2000
	s_nop 0
	global_load_lds_dwordx4 v148, s[26:27]
	s_waitcnt vmcnt(6)
	s_setprio 1
	s_barrier
; #define PG8_STAGE(bufoff, gbase, voff) do { _Pragma("unroll") for (int _i = 0; _i < 2; ++_i) \
;         __builtin_amdgcn_global_load_lds((const unsigned*)((const char*)(gbase) + (voff)[_i]), (LAS unsigned*)(lds + (bufoff) + ldsw + _i * 8192), 16, 0, 0); } while (0)
; #define PG8_LDA(dst, b, h) do { _Pragma("unroll") for (int m = 0; m < 4; ++m) _Pragma("unroll") for (int k = 0; k < 2; ++k) dst[m][k] = *(const LAS bf16x8*)(lds + PG8_SA(b, h) + aoff + m * 2048 + k * 1024); } while (0)
; #define PG8_LDB(dst, b, h) do { _Pragma("unroll") for (int n = 0; n < 2; ++n) _Pragma("unroll") for (int k = 0; k < 2; ++k) dst[n][k] = *(const LAS bf16x8*)(lds + PG8_SB(b, h) + boff + n * 2048 + k * 1024); } while (0)
; #define PG8_MMA(ai, bj, At, Bt) do { __builtin_amdgcn_s_setprio(1); _Pragma("unroll") for (int m = 0; m < 4; ++m) _Pragma("unroll") for (int n = 0; n < 2; ++n) _Pragma("unroll") for (int k = 0; k < 2; ++k) \
;         acc[ai][bj][m][n] = __builtin_amdgcn_mfma_f32_16x16x32_bf16(Bt[n][k], At[m][k], acc[ai][bj][m][n], 0, 0, 0); __builtin_amdgcn_s_setprio(0); } while (0)
; #define PG8_WAIT_V(n) asm volatile("s_waitcnt vmcnt(" #n ")" ::: "memory")
; #define PG8_WAIT_L(n) asm volatile("s_waitcnt lgkmcnt(" #n ")" ::: "memory")
; #define PG8_BAR __builtin_amdgcn_s_barrier()
; #define PG8_SCHED __builtin_amdgcn_sched_barrier(0)
; template <class Epi>
; __device__ __forceinline__ void gemm_phase(LAS unsigned char* lds, const Gemm g, const Epi& E) {
;     ...
;             PG8_WAIT_V(6); PG8_BAR; PG8_MMA(1, 1, At, B1); PG8_BAR;
;             PG8_LDB(B0, 1, 0); PG8_SCHED; PG8_LDA(At, 1, 0); PG8_STAGE(PG8_SA(0, 1), a2 + hstep, voffA);
;             PG8_WAIT_L(8); PG8_BAR; PG8_WAIT_L(0); PG8_MMA(0, 0, At, B0); PG8_BAR; PG8_SCHED;
;             PG8_LDB(B1, 1, 1); PG8_STAGE(PG8_SB(1, 0), b3, voffB);
;             PG8_BAR; PG8_WAIT_L(0); PG8_MMA(0, 1, At, B1); PG8_BAR;
;             PG8_LDA(At, 1, 1); PG8_STAGE(PG8_SA(1, 0), a3, voffA);
;             PG8_BAR; PG8_WAIT_L(0); PG8_MMA(1, 0, At, B0); PG8_BAR; PG8_SCHED;
;             PG8_STAGE(PG8_SB(1, 1), b3 + hstep, voffB);
	v_mfma_f32_16x16x32_bf16 v[52:55], v[192:195], v[156:159], v[52:55]
	v_mfma_f32_16x16x32_bf16 v[48:51], v[200:203], v[156:159], v[48:51]
	v_mfma_f32_16x16x32_bf16 v[36:39], v[192:195], v[168:171], v[36:39]
	v_mfma_f32_16x16x32_bf16 v[32:35], v[200:203], v[168:171], v[32:35]
	v_mfma_f32_16x16x32_bf16 v[20:23], v[192:195], v[176:179], v[20:23]
	v_mfma_f32_16x16x32_bf16 v[16:19], v[200:203], v[176:179], v[16:19]
	v_mfma_f32_16x16x32_bf16 v[4:7], v[192:195], v[184:187], v[4:7]
	v_mfma_f32_16x16x32_bf16 v[0:3], v[200:203], v[184:187], v[0:3]
	v_mfma_f32_16x16x32_bf16 v[52:55], v[196:199], v[164:167], v[52:55]
	v_mfma_f32_16x16x32_bf16 v[48:51], v[204:207], v[164:167], v[48:51]
	v_mfma_f32_16x16x32_bf16 v[36:39], v[196:199], v[172:175], v[36:39]
	v_mfma_f32_16x16x32_bf16 v[32:35], v[204:207], v[172:175], v[32:35]
	v_mfma_f32_16x16x32_bf16 v[20:23], v[196:199], v[180:183], v[20:23]
	v_mfma_f32_16x16x32_bf16 v[16:19], v[204:207], v[180:183], v[16:19]
	v_mfma_f32_16x16x32_bf16 v[4:7], v[196:199], v[188:191], v[4:7]
	v_mfma_f32_16x16x32_bf16 v[0:3], v[204:207], v[188:191], v[0:3]
	s_barrier
	s_setprio 0
	s_add_i32 s34, 0, 0x18000
	v_add_u32_e32 v140, s34, v160
	ds_read_b128 v[128:131], v140
	ds_read_b128 v[132:135], v140 offset:1024
	ds_read_b128 v[136:139], v140 offset:2048
	ds_read_b128 v[140:143], v140 offset:3072
	s_add_u32 s26, s38, 0x160000
	s_addc_u32 s27, s39, 0
	s_mov_b32 m0, s46
	ds_read_b128 v[156:159], v161 offset:32768
	ds_read_b128 v[164:167], v161 offset:33792
	ds_read_b128 v[168:171], v161 offset:34816
	ds_read_b128 v[172:175], v161 offset:35840
	ds_read_b128 v[176:179], v161 offset:36864
	ds_read_b128 v[180:183], v161 offset:37888
	ds_read_b128 v[184:187], v161 offset:38912
	ds_read_b128 v[188:191], v161 offset:39936
	global_load_lds_dwordx4 v144, s[26:27]
	s_mov_b32 m0, s47
	s_nop 0
	global_load_lds_dwordx4 v146, s[26:27]
	s_waitcnt lgkmcnt(8)
	s_setprio 1
	s_barrier
	s_waitcnt lgkmcnt(0)
	v_mfma_f32_16x16x32_bf16 v[124:127], v[128:131], v[156:159], v[124:127]
	v_mfma_f32_16x16x32_bf16 v[120:123], v[136:139], v[156:159], v[120:123]
	v_mfma_f32_16x16x32_bf16 v[108:111], v[128:131], v[168:171], v[108:111]
	v_mfma_f32_16x16x32_bf16 v[104:107], v[136:139], v[168:171], v[104:107]
	v_mfma_f32_16x16x32_bf16 v[92:95], v[128:131], v[176:179], v[92:95]
	v_mfma_f32_16x16x32_bf16 v[88:91], v[136:139], v[176:179], v[88:91]
	v_mfma_f32_16x16x32_bf16 v[76:79], v[128:131], v[184:187], v[76:79]
	v_mfma_f32_16x16x32_bf16 v[72:75], v[136:139], v[184:187], v[72:75]
	v_mfma_f32_16x16x32_bf16 v[124:127], v[132:135], v[164:167], v[124:127]
	v_mfma_f32_16x16x32_bf16 v[120:123], v[140:143], v[164:167], v[120:123]
	v_mfma_f32_16x16x32_bf16 v[108:111], v[132:135], v[172:175], v[108:111]
	v_mfma_f32_16x16x32_bf16 v[104:107], v[140:143], v[172:175], v[104:107]
	v_mfma_f32_16x16x32_bf16 v[92:95], v[132:135], v[180:183], v[92:95]
	v_mfma_f32_16x16x32_bf16 v[88:91], v[140:143], v[180:183], v[88:91]
	v_mfma_f32_16x16x32_bf16 v[76:79], v[132:135], v[188:191], v[76:79]
	v_mfma_f32_16x16x32_bf16 v[72:75], v[140:143], v[188:191], v[72:75]
	s_barrier
	s_setprio 0
	s_add_i32 s35, 0, 0x1c000
	s_add_i32 s26, s34, s31
	v_add_u32_e32 v163, s35, v160
	s_mov_b32 m0, s26
	ds_read_b128 v[192:195], v163
	ds_read_b128 v[196:199], v163 offset:1024
	ds_read_b128 v[200:203], v163 offset:2048
	ds_read_b128 v[204:207], v163 offset:3072
	s_add_u32 s98, s36, 0x80
	s_addc_u32 s99, s37, 0
	global_load_lds_dwordx4 v208, s[98:99]
	s_add_i32 m0, s26, 0x2000
	s_add_u32 s100, s36, 0x80
	s_addc_u32 s101, s37, 0
	global_load_lds_dwordx4 v148, s[100:101]
	s_setprio 1
	s_barrier
	s_waitcnt lgkmcnt(0)
	v_mfma_f32_16x16x32_bf16 v[116:119], v[192:195], v[156:159], v[116:119]
	v_mfma_f32_16x16x32_bf16 v[112:115], v[200:203], v[156:159], v[112:115]
	v_mfma_f32_16x16x32_bf16 v[100:103], v[192:195], v[168:171], v[100:103]
	v_mfma_f32_16x16x32_bf16 v[96:99], v[200:203], v[168:171], v[96:99]
	v_mfma_f32_16x16x32_bf16 v[84:87], v[192:195], v[176:179], v[84:87]
	v_mfma_f32_16x16x32_bf16 v[80:83], v[200:203], v[176:179], v[80:83]
	v_mfma_f32_16x16x32_bf16 v[68:71], v[192:195], v[184:187], v[68:71]
	v_mfma_f32_16x16x32_bf16 v[64:67], v[200:203], v[184:187], v[64:67]
	v_mfma_f32_16x16x32_bf16 v[116:119], v[196:199], v[164:167], v[116:119]
	v_mfma_f32_16x16x32_bf16 v[112:115], v[204:207], v[164:167], v[112:115]
	v_mfma_f32_16x16x32_bf16 v[100:103], v[196:199], v[172:175], v[100:103]
	v_mfma_f32_16x16x32_bf16 v[96:99], v[204:207], v[172:175], v[96:99]
	v_mfma_f32_16x16x32_bf16 v[84:87], v[196:199], v[180:183], v[84:87]
	v_mfma_f32_16x16x32_bf16 v[80:83], v[204:207], v[180:183], v[80:83]
	v_mfma_f32_16x16x32_bf16 v[68:71], v[196:199], v[188:191], v[68:71]
	v_mfma_f32_16x16x32_bf16 v[64:67], v[204:207], v[188:191], v[64:67]
	s_barrier
	s_setprio 0
	s_mov_b32 m0, s64
	ds_read_b128 v[156:159], v161 offset:49152
	ds_read_b128 v[164:167], v161 offset:50176
	ds_read_b128 v[168:171], v161 offset:51200
	ds_read_b128 v[172:175], v161 offset:52224
	ds_read_b128 v[176:179], v161 offset:53248
	ds_read_b128 v[180:183], v161 offset:54272
	ds_read_b128 v[184:187], v161 offset:55296
	ds_read_b128 v[188:191], v161 offset:56320
	s_add_u32 s98, s38, 0x80
	s_addc_u32 s99, s39, 0
	global_load_lds_dwordx4 v144, s[98:99]
	s_mov_b32 m0, s65
	s_add_u32 s100, s38, 0x80
	s_addc_u32 s101, s39, 0
	global_load_lds_dwordx4 v146, s[100:101]
	s_setprio 1
	s_barrier
; __device__ __forceinline__ float bflo(unsigned w) { return __uint_as_float(w << 16); }
; __device__ __forceinline__ float bfhi(unsigned w) { return __uint_as_float(w & 0xffff0000u); }
; __device__ __forceinline__ u32x4 pack8u(f32x4 a, f32x4 b) { u32x4 w = {cvt_pk_bf16(a[0], a[1]), cvt_pk_bf16(a[2], a[3]), cvt_pk_bf16(b[0], b[1]), cvt_pk_bf16(b[2], b[3])}; return w; }
; #define PG8_STAGE(bufoff, gbase, voff) do { _Pragma("unroll") for (int _i = 0; _i < 2; ++_i) \
;         __builtin_amdgcn_global_load_lds((const unsigned*)((const char*)(gbase) + (voff)[_i]), (LAS unsigned*)(lds + (bufoff) + ldsw + _i * 8192), 16, 0, 0); } while (0)
; template <class Epi>
; __device__ __forceinline__ void gemm_phase(LAS unsigned char* lds, const Gemm g, const Epi& E) {
;     ...
;             PG8_BAR; PG8_WAIT_L(0); PG8_MMA(0, 1, At, B1); PG8_BAR;
;             PG8_LDA(At, 1, 1); PG8_STAGE(PG8_SA(1, 0), a3, voffA);
;             PG8_BAR; PG8_WAIT_L(0); PG8_MMA(1, 0, At, B0); PG8_BAR; PG8_SCHED;
;             PG8_STAGE(PG8_SB(1, 1), b3 + hstep, voffB);
;             PG8_WAIT_V(6); PG8_BAR; PG8_MMA(1, 1, At, B1); PG8_BAR;
;     __device__ __forceinline__ void operator()(const AccT& acc, const Unit& u, int wr, int wc, int fr, int fq) const {
;         const int b = (u.pm * 256) / SEQ;
;         f32x4 gt[2][2];
; #pragma unroll
;         for (int bj = 0; bj < 2; ++bj)
; #pragma unroll
;             for (int n = 0; n < 2; ++n) gt[bj][n] = *(const f32x4*)(GT + (size_t)b * 6 * D + u.pn * 256 + bj * 128 + wc * 32 + fq * 8 + 4 * n);
; #pragma unroll
;         for (int ai = 0; ai < 2; ++ai)
; #pragma unroll
;             for (int m = 0; m < 4; ++m) {
;                 const int row = u.pm * 256 + ai * 128 + wr * 64 + m * 16 + fr;
; #pragma unroll
;                 for (int bj = 0; bj < 2; ++bj) {
;                     const size_t off = (size_t)row * D + u.pn * 256 + bj * 128 + wc * 32 + fq * 8;
;                     f32x4 x0, x1;
;                     if (XINF) { x0 = *(const f32x4*)(XINF + off); x1 = *(const f32x4*)(XINF + off + 4); }
;                     else { const u32x4 w = *(const u32x4*)(XIN16 + off); x0 = (f32x4){bflo(w[0]), bfhi(w[0]), bflo(w[1]), bfhi(w[1])}; x1 = (f32x4){bflo(w[2]), bfhi(w[2]), bflo(w[3]), bfhi(w[3])}; }
;                     *(u32x4*)(XOUT + off) = pack8u(x0 + gt[bj][0] * acc[ai][bj][m][0], x1 + gt[bj][1] * acc[ai][bj][m][1]);
	s_waitcnt lgkmcnt(0)
	v_mfma_f32_16x16x32_bf16 v[60:63], v[128:131], v[156:159], v[60:63]
	v_mfma_f32_16x16x32_bf16 v[56:59], v[136:139], v[156:159], v[56:59]
	v_mfma_f32_16x16x32_bf16 v[44:47], v[128:131], v[168:171], v[44:47]
	v_mfma_f32_16x16x32_bf16 v[40:43], v[136:139], v[168:171], v[40:43]
	v_mfma_f32_16x16x32_bf16 v[28:31], v[128:131], v[176:179], v[28:31]
	v_mfma_f32_16x16x32_bf16 v[24:27], v[136:139], v[176:179], v[24:27]
	v_mfma_f32_16x16x32_bf16 v[12:15], v[128:131], v[184:187], v[12:15]
	v_mfma_f32_16x16x32_bf16 v[8:11], v[136:139], v[184:187], v[8:11]
	v_mfma_f32_16x16x32_bf16 v[60:63], v[132:135], v[164:167], v[60:63]
	v_mfma_f32_16x16x32_bf16 v[56:59], v[140:143], v[164:167], v[56:59]
	v_mfma_f32_16x16x32_bf16 v[44:47], v[132:135], v[172:175], v[44:47]
	v_mfma_f32_16x16x32_bf16 v[40:43], v[140:143], v[172:175], v[40:43]
	v_mfma_f32_16x16x32_bf16 v[28:31], v[132:135], v[180:183], v[28:31]
	v_mfma_f32_16x16x32_bf16 v[24:27], v[140:143], v[180:183], v[24:27]
	v_mfma_f32_16x16x32_bf16 v[12:15], v[132:135], v[188:191], v[12:15]
	v_mfma_f32_16x16x32_bf16 v[8:11], v[140:143], v[188:191], v[8:11]
	s_barrier
	s_setprio 0
	s_add_u32 s26, s36, 0x160080
	s_addc_u32 s27, s37, 0
	s_add_i32 s34, s35, s31
	s_mov_b32 m0, s34
	s_nop 0
	global_load_lds_dwordx4 v208, s[26:27]
	s_add_i32 m0, s34, 0x2000
	s_nop 0
	global_load_lds_dwordx4 v148, s[26:27]
	s_waitcnt vmcnt(6)
	s_setprio 1
	s_barrier
	v_mfma_f32_16x16x32_bf16 v[52:55], v[192:195], v[156:159], v[52:55]
	v_mfma_f32_16x16x32_bf16 v[48:51], v[200:203], v[156:159], v[48:51]
	v_mfma_f32_16x16x32_bf16 v[36:39], v[192:195], v[168:171], v[36:39]
	v_mfma_f32_16x16x32_bf16 v[32:35], v[200:203], v[168:171], v[32:35]
	v_mfma_f32_16x16x32_bf16 v[20:23], v[192:195], v[176:179], v[20:23]
	v_mfma_f32_16x16x32_bf16 v[16:19], v[200:203], v[176:179], v[16:19]
	v_mfma_f32_16x16x32_bf16 v[4:7], v[192:195], v[184:187], v[4:7]
	v_mfma_f32_16x16x32_bf16 v[0:3], v[200:203], v[184:187], v[0:3]
	v_mfma_f32_16x16x32_bf16 v[52:55], v[196:199], v[164:167], v[52:55]
	v_mfma_f32_16x16x32_bf16 v[48:51], v[204:207], v[164:167], v[48:51]
	v_mfma_f32_16x16x32_bf16 v[36:39], v[196:199], v[172:175], v[36:39]
	v_mfma_f32_16x16x32_bf16 v[32:35], v[204:207], v[172:175], v[32:35]
	v_mfma_f32_16x16x32_bf16 v[20:23], v[196:199], v[180:183], v[20:23]
	v_mfma_f32_16x16x32_bf16 v[16:19], v[204:207], v[180:183], v[16:19]
	v_mfma_f32_16x16x32_bf16 v[4:7], v[196:199], v[188:191], v[4:7]
	v_mfma_f32_16x16x32_bf16 v[0:3], v[204:207], v[188:191], v[0:3]
	s_setprio 0
	s_add_i32 s82, s82, 2
	s_add_u32 s78, s78, 0x100
	s_addc_u32 s79, s79, 0
	s_cmpk_gt_u32 s82, 0x55
	s_mov_b64 s[26:27], s[28:29]
	s_barrier
	s_cbranch_scc0 .LBB0_873
	s_ashr_i32 s26, s74, 31
	s_lshr_b32 s26, s26, 29
	s_add_i32 s26, s74, s26
	s_ashr_i32 s26, s26, 3
	s_mul_i32 s26, s26, 6
	s_ashr_i32 s27, s26, 31
	s_lshl_b64 s[26:27], s[26:27], 13
	s_add_u32 s28, s48, s26
	s_addc_u32 s29, s49, s27
	s_lshl_b32 s26, s76, 8
	s_ashr_i32 s27, s26, 31
	v_lshl_add_u32 v157, s74, 8, v151
	v_or_b32_e32 v158, s26, v150
	s_lshl_b64 s[26:27], s[26:27], 2
	s_add_u32 s26, s28, s26
	s_addc_u32 s27, s29, s27
	s_add_u32 s26, s26, s69
	s_addc_u32 s27, s27, 0
	global_load_dwordx4 v[140:143], v162, s[26:27]
	global_load_dwordx4 v[136:139], v162, s[26:27] offset:16
	global_load_dwordx4 v[132:135], v162, s[26:27] offset:512
	global_load_dwordx4 v[128:131], v162, s[26:27] offset:528
	v_lshlrev_b32_e32 v156, 1, v158
	v_lshl_add_u32 v156, v157, 12, v156
	v_add_u32_e32 v157, 0x0, v156
	global_load_dwordx4 v[164:167], v157, s[96:97] offset:0
	v_add_u32_e32 v157, 0x0, v156
	global_load_dwordx4 v[168:171], v157, s[96:97] offset:256
	v_add_u32_e32 v157, 0x10000, v156
	global_load_dwordx4 v[172:175], v157, s[96:97] offset:0
	v_add_u32_e32 v157, 0x10000, v156
	global_load_dwordx4 v[184:187], v157, s[96:97] offset:256
	v_add_u32_e32 v157, 0x20000, v156
	global_load_dwordx4 v[188:191], v157, s[96:97] offset:0
	v_add_u32_e32 v157, 0x20000, v156
	global_load_dwordx4 v[192:195], v157, s[96:97] offset:256
	v_add_u32_e32 v157, 0x30000, v156
	global_load_dwordx4 v[196:199], v157, s[96:97] offset:0
	v_add_u32_e32 v157, 0x30000, v156
	global_load_dwordx4 v[200:203], v157, s[96:97] offset:256
	v_add_u32_e32 v157, 0x80000, v156
	global_load_dwordx4 v[204:207], v157, s[96:97] offset:0
	v_add_u32_e32 v157, 0x80000, v156
	global_load_dwordx4 v[228:231], v157, s[96:97] offset:256
	s_waitcnt vmcnt(9)
	v_lshlrev_b32_e32 v176, 16, v164
	v_and_b32_e32 v177, 0xffff0000, v164
	v_lshlrev_b32_e32 v178, 16, v165
	v_and_b32_e32 v179, 0xffff0000, v165
	v_lshlrev_b32_e32 v180, 16, v166
	v_and_b32_e32 v181, 0xffff0000, v166
	v_lshlrev_b32_e32 v182, 16, v167
	v_and_b32_e32 v183, 0xffff0000, v167
	v_pk_fma_f32 v[124:125], v[124:125], v[140:141], v[176:177]
	v_pk_fma_f32 v[126:127], v[126:127], v[142:143], v[178:179]
	v_pk_fma_f32 v[120:121], v[120:121], v[136:137], v[180:181]
	v_pk_fma_f32 v[122:123], v[122:123], v[138:139], v[182:183]
	v_cvt_pk_bf16_f32 v124, v124, v125
	v_cvt_pk_bf16_f32 v125, v126, v127
	v_cvt_pk_bf16_f32 v126, v120, v121
	v_cvt_pk_bf16_f32 v127, v122, v123
	v_add_u32_e32 v158, 0x0, v156
	global_store_dwordx4 v158, v[124:127], s[96:97] offset:0
	v_add_u32_e32 v157, 0x90000, v156
	global_load_dwordx4 v[164:167], v157, s[96:97] offset:0
	v_add_u32_e32 v157, 0x90000, v156
	global_load_dwordx4 v[120:123], v157, s[96:97] offset:256
	s_waitcnt vmcnt(11)
; __device__ __forceinline__ float bflo(unsigned w) { return __uint_as_float(w << 16); }
; __device__ __forceinline__ float bfhi(unsigned w) { return __uint_as_float(w & 0xffff0000u); }
; __device__ __forceinline__ u32x4 pack8u(f32x4 a, f32x4 b) { u32x4 w = {cvt_pk_bf16(a[0], a[1]), cvt_pk_bf16(a[2], a[3]), cvt_pk_bf16(b[0], b[1]), cvt_pk_bf16(b[2], b[3])}; return w; }
;     __device__ __forceinline__ void operator()(const AccT& acc, const Unit& u, int wr, int wc, int fr, int fq) const {
;     ...
;                 for (int bj = 0; bj < 2; ++bj) {
;                     const size_t off = (size_t)row * D + u.pn * 256 + bj * 128 + wc * 32 + fq * 8;
;                     f32x4 x0, x1;
;                     if (XINF) { x0 = *(const f32x4*)(XINF + off); x1 = *(const f32x4*)(XINF + off + 4); }
;                     else { const u32x4 w = *(const u32x4*)(XIN16 + off); x0 = (f32x4){bflo(w[0]), bfhi(w[0]), bflo(w[1]), bfhi(w[1])}; x1 = (f32x4){bflo(w[2]), bfhi(w[2]), bflo(w[3]), bfhi(w[3])}; }
;                     *(u32x4*)(XOUT + off) = pack8u(x0 + gt[bj][0] * acc[ai][bj][m][0], x1 + gt[bj][1] * acc[ai][bj][m][1]);
	v_lshlrev_b32_e32 v176, 16, v168
	v_and_b32_e32 v177, 0xffff0000, v168
	v_lshlrev_b32_e32 v178, 16, v169
	v_and_b32_e32 v179, 0xffff0000, v169
	v_lshlrev_b32_e32 v180, 16, v170
	v_and_b32_e32 v181, 0xffff0000, v170
	v_lshlrev_b32_e32 v182, 16, v171
	v_and_b32_e32 v183, 0xffff0000, v171
	v_pk_fma_f32 v[116:117], v[116:117], v[132:133], v[176:177]
	v_pk_fma_f32 v[118:119], v[118:119], v[134:135], v[178:179]
	v_pk_fma_f32 v[112:113], v[112:113], v[128:129], v[180:181]
	v_pk_fma_f32 v[114:115], v[114:115], v[130:131], v[182:183]
	v_cvt_pk_bf16_f32 v116, v116, v117
	v_cvt_pk_bf16_f32 v117, v118, v119
	v_cvt_pk_bf16_f32 v118, v112, v113
	v_cvt_pk_bf16_f32 v119, v114, v115
	v_add_u32_e32 v158, 0x0, v156
	global_store_dwordx4 v158, v[116:119], s[96:97] offset:256
	v_add_u32_e32 v157, 0xa0000, v156
	global_load_dwordx4 v[168:171], v157, s[96:97] offset:0
	v_add_u32_e32 v157, 0xa0000, v156
	global_load_dwordx4 v[112:115], v157, s[96:97] offset:256
	s_waitcnt vmcnt(13)
	v_lshlrev_b32_e32 v176, 16, v172
	v_and_b32_e32 v177, 0xffff0000, v172
	v_lshlrev_b32_e32 v178, 16, v173
	v_and_b32_e32 v179, 0xffff0000, v173
	v_lshlrev_b32_e32 v180, 16, v174
	v_and_b32_e32 v181, 0xffff0000, v174
	v_lshlrev_b32_e32 v182, 16, v175
	v_and_b32_e32 v183, 0xffff0000, v175
	v_pk_fma_f32 v[108:109], v[108:109], v[140:141], v[176:177]
	v_pk_fma_f32 v[110:111], v[110:111], v[142:143], v[178:179]
	v_pk_fma_f32 v[104:105], v[104:105], v[136:137], v[180:181]
	v_pk_fma_f32 v[106:107], v[106:107], v[138:139], v[182:183]
	v_cvt_pk_bf16_f32 v108, v108, v109
	v_cvt_pk_bf16_f32 v109, v110, v111
	v_cvt_pk_bf16_f32 v110, v104, v105
	v_cvt_pk_bf16_f32 v111, v106, v107
	v_add_u32_e32 v158, 0x10000, v156
	global_store_dwordx4 v158, v[108:111], s[96:97] offset:0
	v_add_u32_e32 v157, 0xb0000, v156
	global_load_dwordx4 v[172:175], v157, s[96:97] offset:0
	v_add_u32_e32 v157, 0xb0000, v156
	global_load_dwordx4 v[104:107], v157, s[96:97] offset:256
	s_waitcnt vmcnt(15)
	v_lshlrev_b32_e32 v176, 16, v184
	v_and_b32_e32 v177, 0xffff0000, v184
	v_lshlrev_b32_e32 v178, 16, v185
	v_and_b32_e32 v179, 0xffff0000, v185
	v_lshlrev_b32_e32 v180, 16, v186
	v_and_b32_e32 v181, 0xffff0000, v186
	v_lshlrev_b32_e32 v182, 16, v187
	v_and_b32_e32 v183, 0xffff0000, v187
	v_pk_fma_f32 v[100:101], v[100:101], v[132:133], v[176:177]
	v_pk_fma_f32 v[102:103], v[102:103], v[134:135], v[178:179]
	v_pk_fma_f32 v[96:97], v[96:97], v[128:129], v[180:181]
	v_pk_fma_f32 v[98:99], v[98:99], v[130:131], v[182:183]
	v_cvt_pk_bf16_f32 v100, v100, v101
	v_cvt_pk_bf16_f32 v101, v102, v103
	v_cvt_pk_bf16_f32 v102, v96, v97
	v_cvt_pk_bf16_f32 v103, v98, v99
	v_add_u32_e32 v158, 0x10000, v156
	global_store_dwordx4 v158, v[100:103], s[96:97] offset:256
	s_waitcnt vmcnt(15)
	v_lshlrev_b32_e32 v176, 16, v188
	v_and_b32_e32 v177, 0xffff0000, v188
	v_lshlrev_b32_e32 v178, 16, v189
	v_and_b32_e32 v179, 0xffff0000, v189
	v_lshlrev_b32_e32 v180, 16, v190
	v_and_b32_e32 v181, 0xffff0000, v190
	v_lshlrev_b32_e32 v182, 16, v191
	v_and_b32_e32 v183, 0xffff0000, v191
	v_pk_fma_f32 v[92:93], v[92:93], v[140:141], v[176:177]
	v_pk_fma_f32 v[94:95], v[94:95], v[142:143], v[178:179]
	v_pk_fma_f32 v[88:89], v[88:89], v[136:137], v[180:181]
	v_pk_fma_f32 v[90:91], v[90:91], v[138:139], v[182:183]
	v_cvt_pk_bf16_f32 v92, v92, v93
	v_cvt_pk_bf16_f32 v93, v94, v95
	v_cvt_pk_bf16_f32 v94, v88, v89
	v_cvt_pk_bf16_f32 v95, v90, v91
	v_add_u32_e32 v158, 0x20000, v156
	global_store_dwordx4 v158, v[92:95], s[96:97] offset:0
	s_waitcnt vmcnt(15)
	v_lshlrev_b32_e32 v176, 16, v192
	v_and_b32_e32 v177, 0xffff0000, v192
	v_lshlrev_b32_e32 v178, 16, v193
	v_and_b32_e32 v179, 0xffff0000, v193
	v_lshlrev_b32_e32 v180, 16, v194
	v_and_b32_e32 v181, 0xffff0000, v194
	v_lshlrev_b32_e32 v182, 16, v195
	v_and_b32_e32 v183, 0xffff0000, v195
	v_pk_fma_f32 v[84:85], v[84:85], v[132:133], v[176:177]
	v_pk_fma_f32 v[86:87], v[86:87], v[134:135], v[178:179]
	v_pk_fma_f32 v[80:81], v[80:81], v[128:129], v[180:181]
	v_pk_fma_f32 v[82:83], v[82:83], v[130:131], v[182:183]
	v_cvt_pk_bf16_f32 v84, v84, v85
	v_cvt_pk_bf16_f32 v85, v86, v87
	v_cvt_pk_bf16_f32 v86, v80, v81
	v_cvt_pk_bf16_f32 v87, v82, v83
	v_add_u32_e32 v158, 0x20000, v156
	global_store_dwordx4 v158, v[84:87], s[96:97] offset:256
	s_waitcnt vmcnt(15)
	v_lshlrev_b32_e32 v176, 16, v196
	v_and_b32_e32 v177, 0xffff0000, v196
	v_lshlrev_b32_e32 v178, 16, v197
	v_and_b32_e32 v179, 0xffff0000, v197
	v_lshlrev_b32_e32 v180, 16, v198
	v_and_b32_e32 v181, 0xffff0000, v198
	v_lshlrev_b32_e32 v182, 16, v199
	v_and_b32_e32 v183, 0xffff0000, v199
	v_pk_fma_f32 v[76:77], v[76:77], v[140:141], v[176:177]
	v_pk_fma_f32 v[78:79], v[78:79], v[142:143], v[178:179]
	v_pk_fma_f32 v[72:73], v[72:73], v[136:137], v[180:181]
	v_pk_fma_f32 v[74:75], v[74:75], v[138:139], v[182:183]
	v_cvt_pk_bf16_f32 v76, v76, v77
	v_cvt_pk_bf16_f32 v77, v78, v79
	v_cvt_pk_bf16_f32 v78, v72, v73
	v_cvt_pk_bf16_f32 v79, v74, v75
	v_add_u32_e32 v158, 0x30000, v156
	global_store_dwordx4 v158, v[76:79], s[96:97] offset:0
	s_waitcnt vmcnt(15)
	v_lshlrev_b32_e32 v176, 16, v200
	v_and_b32_e32 v177, 0xffff0000, v200
	v_lshlrev_b32_e32 v178, 16, v201
	v_and_b32_e32 v179, 0xffff0000, v201
	v_lshlrev_b32_e32 v180, 16, v202
	v_and_b32_e32 v181, 0xffff0000, v202
	v_lshlrev_b32_e32 v182, 16, v203
	v_and_b32_e32 v183, 0xffff0000, v203
	v_pk_fma_f32 v[68:69], v[68:69], v[132:133], v[176:177]
	v_pk_fma_f32 v[70:71], v[70:71], v[134:135], v[178:179]
	v_pk_fma_f32 v[64:65], v[64:65], v[128:129], v[180:181]
	v_pk_fma_f32 v[66:67], v[66:67], v[130:131], v[182:183]
	v_cvt_pk_bf16_f32 v68, v68, v69
	v_cvt_pk_bf16_f32 v69, v70, v71
	v_cvt_pk_bf16_f32 v70, v64, v65
	v_cvt_pk_bf16_f32 v71, v66, v67
	v_add_u32_e32 v158, 0x30000, v156
	global_store_dwordx4 v158, v[68:71], s[96:97] offset:256
	s_waitcnt vmcnt(15)
; __device__ __forceinline__ float bflo(unsigned w) { return __uint_as_float(w << 16); }
; __device__ __forceinline__ float bfhi(unsigned w) { return __uint_as_float(w & 0xffff0000u); }
; __device__ __forceinline__ u32x4 pack8u(f32x4 a, f32x4 b) { u32x4 w = {cvt_pk_bf16(a[0], a[1]), cvt_pk_bf16(a[2], a[3]), cvt_pk_bf16(b[0], b[1]), cvt_pk_bf16(b[2], b[3])}; return w; }
; #define PG8_WAIT_V(n) asm volatile("s_waitcnt vmcnt(" #n ")" ::: "memory")
; #define PG8_BAR __builtin_amdgcn_s_barrier()
; template <class Epi>
; __device__ __forceinline__ void gemm_phase(LAS unsigned char* lds, const Gemm g, const Epi& E) {
;     ...
;         E(acc, cur, wr, wc, fr, fq);
;         if (!has_next) break;
; #pragma unroll
;         for (int a = 0; a < 2; ++a)
; #pragma unroll
;             for (int b = 0; b < 2; ++b)
; #pragma unroll
;                 for (int m = 0; m < 4; ++m)
; #pragma unroll
;                     for (int n = 0; n < 2; ++n) acc[a][b][m][n] = (f32x4){0.f, 0.f, 0.f, 0.f};
;         cur = nxt; cA = nA; cB = nB; ++ui;
;     }
;     PG8_WAIT_V(0);
;     if (wr == 0) PG8_BAR;
;     __device__ __forceinline__ void operator()(const AccT& acc, const Unit& u, int wr, int wc, int fr, int fq) const {
;     ...
;                 for (int bj = 0; bj < 2; ++bj) {
;                     const size_t off = (size_t)row * D + u.pn * 256 + bj * 128 + wc * 32 + fq * 8;
;                     f32x4 x0, x1;
;                     if (XINF) { x0 = *(const f32x4*)(XINF + off); x1 = *(const f32x4*)(XINF + off + 4); }
;                     else { const u32x4 w = *(const u32x4*)(XIN16 + off); x0 = (f32x4){bflo(w[0]), bfhi(w[0]), bflo(w[1]), bfhi(w[1])}; x1 = (f32x4){bflo(w[2]), bfhi(w[2]), bflo(w[3]), bfhi(w[3])}; }
;                     *(u32x4*)(XOUT + off) = pack8u(x0 + gt[bj][0] * acc[ai][bj][m][0], x1 + gt[bj][1] * acc[ai][bj][m][1]);
	v_lshlrev_b32_e32 v176, 16, v204
	v_and_b32_e32 v177, 0xffff0000, v204
	v_lshlrev_b32_e32 v178, 16, v205
	v_and_b32_e32 v179, 0xffff0000, v205
	v_lshlrev_b32_e32 v180, 16, v206
	v_and_b32_e32 v181, 0xffff0000, v206
	v_lshlrev_b32_e32 v182, 16, v207
	v_and_b32_e32 v183, 0xffff0000, v207
	v_pk_fma_f32 v[60:61], v[60:61], v[140:141], v[176:177]
	v_pk_fma_f32 v[62:63], v[62:63], v[142:143], v[178:179]
	v_pk_fma_f32 v[56:57], v[56:57], v[136:137], v[180:181]
	v_pk_fma_f32 v[58:59], v[58:59], v[138:139], v[182:183]
	v_cvt_pk_bf16_f32 v60, v60, v61
	v_cvt_pk_bf16_f32 v61, v62, v63
	v_cvt_pk_bf16_f32 v62, v56, v57
	v_cvt_pk_bf16_f32 v63, v58, v59
	v_add_u32_e32 v158, 0x80000, v156
	global_store_dwordx4 v158, v[60:63], s[96:97] offset:0
	s_waitcnt vmcnt(15)
	v_lshlrev_b32_e32 v176, 16, v228
	v_and_b32_e32 v177, 0xffff0000, v228
	v_lshlrev_b32_e32 v178, 16, v229
	v_and_b32_e32 v179, 0xffff0000, v229
	v_lshlrev_b32_e32 v180, 16, v230
	v_and_b32_e32 v181, 0xffff0000, v230
	v_lshlrev_b32_e32 v182, 16, v231
	v_and_b32_e32 v183, 0xffff0000, v231
	v_pk_fma_f32 v[52:53], v[52:53], v[132:133], v[176:177]
	v_pk_fma_f32 v[54:55], v[54:55], v[134:135], v[178:179]
	v_pk_fma_f32 v[48:49], v[48:49], v[128:129], v[180:181]
	v_pk_fma_f32 v[50:51], v[50:51], v[130:131], v[182:183]
	v_cvt_pk_bf16_f32 v52, v52, v53
	v_cvt_pk_bf16_f32 v53, v54, v55
	v_cvt_pk_bf16_f32 v54, v48, v49
	v_cvt_pk_bf16_f32 v55, v50, v51
	v_add_u32_e32 v158, 0x80000, v156
	global_store_dwordx4 v158, v[52:55], s[96:97] offset:256
	s_waitcnt vmcnt(14)
	v_lshlrev_b32_e32 v176, 16, v164
	v_and_b32_e32 v177, 0xffff0000, v164
	v_lshlrev_b32_e32 v178, 16, v165
	v_and_b32_e32 v179, 0xffff0000, v165
	v_lshlrev_b32_e32 v180, 16, v166
	v_and_b32_e32 v181, 0xffff0000, v166
	v_lshlrev_b32_e32 v182, 16, v167
	v_and_b32_e32 v183, 0xffff0000, v167
	v_pk_fma_f32 v[44:45], v[44:45], v[140:141], v[176:177]
	v_pk_fma_f32 v[46:47], v[46:47], v[142:143], v[178:179]
	v_pk_fma_f32 v[40:41], v[40:41], v[136:137], v[180:181]
	v_pk_fma_f32 v[42:43], v[42:43], v[138:139], v[182:183]
	v_cvt_pk_bf16_f32 v44, v44, v45
	v_cvt_pk_bf16_f32 v45, v46, v47
	v_cvt_pk_bf16_f32 v46, v40, v41
	v_cvt_pk_bf16_f32 v47, v42, v43
	v_add_u32_e32 v158, 0x90000, v156
	global_store_dwordx4 v158, v[44:47], s[96:97] offset:0
	s_waitcnt vmcnt(14)
	v_lshlrev_b32_e32 v176, 16, v120
	v_and_b32_e32 v177, 0xffff0000, v120
	v_lshlrev_b32_e32 v178, 16, v121
	v_and_b32_e32 v179, 0xffff0000, v121
	v_lshlrev_b32_e32 v180, 16, v122
	v_and_b32_e32 v181, 0xffff0000, v122
	v_lshlrev_b32_e32 v182, 16, v123
	v_and_b32_e32 v183, 0xffff0000, v123
	v_pk_fma_f32 v[36:37], v[36:37], v[132:133], v[176:177]
	v_pk_fma_f32 v[38:39], v[38:39], v[134:135], v[178:179]
	v_pk_fma_f32 v[32:33], v[32:33], v[128:129], v[180:181]
	v_pk_fma_f32 v[34:35], v[34:35], v[130:131], v[182:183]
	v_cvt_pk_bf16_f32 v36, v36, v37
	v_cvt_pk_bf16_f32 v37, v38, v39
	v_cvt_pk_bf16_f32 v38, v32, v33
	v_cvt_pk_bf16_f32 v39, v34, v35
	v_add_u32_e32 v158, 0x90000, v156
	global_store_dwordx4 v158, v[36:39], s[96:97] offset:256
	s_waitcnt vmcnt(13)
	v_lshlrev_b32_e32 v176, 16, v168
	v_and_b32_e32 v177, 0xffff0000, v168
	v_lshlrev_b32_e32 v178, 16, v169
	v_and_b32_e32 v179, 0xffff0000, v169
	v_lshlrev_b32_e32 v180, 16, v170
	v_and_b32_e32 v181, 0xffff0000, v170
	v_lshlrev_b32_e32 v182, 16, v171
	v_and_b32_e32 v183, 0xffff0000, v171
	v_pk_fma_f32 v[28:29], v[28:29], v[140:141], v[176:177]
	v_pk_fma_f32 v[30:31], v[30:31], v[142:143], v[178:179]
	v_pk_fma_f32 v[24:25], v[24:25], v[136:137], v[180:181]
	v_pk_fma_f32 v[26:27], v[26:27], v[138:139], v[182:183]
	v_cvt_pk_bf16_f32 v28, v28, v29
	v_cvt_pk_bf16_f32 v29, v30, v31
	v_cvt_pk_bf16_f32 v30, v24, v25
	v_cvt_pk_bf16_f32 v31, v26, v27
	v_add_u32_e32 v158, 0xa0000, v156
	global_store_dwordx4 v158, v[28:31], s[96:97] offset:0
	s_waitcnt vmcnt(13)
	v_lshlrev_b32_e32 v176, 16, v112
	v_and_b32_e32 v177, 0xffff0000, v112
	v_lshlrev_b32_e32 v178, 16, v113
	v_and_b32_e32 v179, 0xffff0000, v113
	v_lshlrev_b32_e32 v180, 16, v114
	v_and_b32_e32 v181, 0xffff0000, v114
	v_lshlrev_b32_e32 v182, 16, v115
	v_and_b32_e32 v183, 0xffff0000, v115
	v_pk_fma_f32 v[20:21], v[20:21], v[132:133], v[176:177]
	v_pk_fma_f32 v[22:23], v[22:23], v[134:135], v[178:179]
	v_pk_fma_f32 v[16:17], v[16:17], v[128:129], v[180:181]
	v_pk_fma_f32 v[18:19], v[18:19], v[130:131], v[182:183]
	v_cvt_pk_bf16_f32 v20, v20, v21
	v_cvt_pk_bf16_f32 v21, v22, v23
	v_cvt_pk_bf16_f32 v22, v16, v17
	v_cvt_pk_bf16_f32 v23, v18, v19
	v_add_u32_e32 v158, 0xa0000, v156
	global_store_dwordx4 v158, v[20:23], s[96:97] offset:256
	s_waitcnt vmcnt(12)
	v_lshlrev_b32_e32 v176, 16, v172
	v_and_b32_e32 v177, 0xffff0000, v172
	v_lshlrev_b32_e32 v178, 16, v173
	v_and_b32_e32 v179, 0xffff0000, v173
	v_lshlrev_b32_e32 v180, 16, v174
	v_and_b32_e32 v181, 0xffff0000, v174
	v_lshlrev_b32_e32 v182, 16, v175
	v_and_b32_e32 v183, 0xffff0000, v175
	v_pk_fma_f32 v[12:13], v[12:13], v[140:141], v[176:177]
	v_pk_fma_f32 v[14:15], v[14:15], v[142:143], v[178:179]
	v_pk_fma_f32 v[8:9], v[8:9], v[136:137], v[180:181]
	v_pk_fma_f32 v[10:11], v[10:11], v[138:139], v[182:183]
	v_cvt_pk_bf16_f32 v12, v12, v13
	v_cvt_pk_bf16_f32 v13, v14, v15
	v_cvt_pk_bf16_f32 v14, v8, v9
	v_cvt_pk_bf16_f32 v15, v10, v11
	v_add_u32_e32 v158, 0xb0000, v156
	global_store_dwordx4 v158, v[12:15], s[96:97] offset:0
	s_waitcnt vmcnt(12)
	v_lshlrev_b32_e32 v176, 16, v104
	v_and_b32_e32 v177, 0xffff0000, v104
	v_lshlrev_b32_e32 v178, 16, v105
	v_and_b32_e32 v179, 0xffff0000, v105
	v_lshlrev_b32_e32 v180, 16, v106
	v_and_b32_e32 v181, 0xffff0000, v106
	v_lshlrev_b32_e32 v182, 16, v107
	v_and_b32_e32 v183, 0xffff0000, v107
	v_pk_fma_f32 v[4:5], v[4:5], v[132:133], v[176:177]
	v_pk_fma_f32 v[6:7], v[6:7], v[134:135], v[178:179]
	v_pk_fma_f32 v[0:1], v[0:1], v[128:129], v[180:181]
	v_pk_fma_f32 v[2:3], v[2:3], v[130:131], v[182:183]
	v_cvt_pk_bf16_f32 v4, v4, v5
	v_cvt_pk_bf16_f32 v5, v6, v7
	v_cvt_pk_bf16_f32 v6, v0, v1
	v_cvt_pk_bf16_f32 v7, v2, v3
	v_add_u32_e32 v158, 0xb0000, v156
	global_store_dwordx4 v158, v[4:7], s[96:97] offset:256
	s_mov_b64 s[28:29], s[42:43]
	s_mov_b64 s[26:27], s[0:1]
	s_mov_b32 s74, s71
	s_mov_b32 s76, s70
	s_and_b64 vcc, exec, s[40:41]
	v_readlane_b32 s82, v255, 24
	v_readlane_b32 s83, v255, 25
	s_cbranch_vccz .LBB0_862
	s_waitcnt vmcnt(0)
	s_cmpk_gt_u32 s3, 0xff
	s_cbranch_scc1 .LBB0_877
	s_barrier
